# GEMM K-loops: flip pairs every 8 MFMAs widened with s_nop 1 between s_setprio 0 and 1
# baseline (speedup 1.0000x reference)
; #define PG8_STAGE(bufoff, gbase, voff) do { _Pragma("unroll") for (int _i = 0; _i < 2; ++_i) \
;         __builtin_amdgcn_global_load_lds((const unsigned*)((const char*)(gbase) + (voff)[_i]), (PG8_LAS unsigned*)(lds + (bufoff) + ldsw + _i * 8192), 16, 0, 0); } while (0)
; #define PG8_LDA(dst, b, h) do { _Pragma("unroll") for (int m = 0; m < 4; ++m) _Pragma("unroll") for (int k = 0; k < 2; ++k) dst[m][k] = *(const PG8_LAS bf16x8*)(lds + PG8_SA(b, h) + aoff + m * 2048 + k * 1024); } while (0)
; #define PG8_LDB(dst, b, h) do { _Pragma("unroll") for (int n = 0; n < 2; ++n) _Pragma("unroll") for (int k = 0; k < 2; ++k) dst[n][k] = *(const PG8_LAS bf16x8*)(lds + PG8_SB(b, h) + boff + n * 2048 + k * 1024); } while (0)
; #define PG8_MMA(ai, bj, At, Bt) do { __builtin_amdgcn_s_setprio(1); _Pragma("unroll") for (int m = 0; m < 4; ++m) _Pragma("unroll") for (int n = 0; n < 2; ++n) _Pragma("unroll") for (int k = 0; k < 2; ++k) \
;         acc[ai][bj][m][n] = __builtin_amdgcn_mfma_f32_16x16x32_bf16(Bt[n][k], At[m][k], acc[ai][bj][m][n], 0, 0, 0); __builtin_amdgcn_s_setprio(0); } while (0)
; #define PG8_WAIT_V(n) asm volatile("s_waitcnt vmcnt(" #n ")" ::: "memory")
; #define PG8_BAR __builtin_amdgcn_s_barrier()
; template <class Epi, class Sched, bool ALIGN_EPI = false, bool SP2 = false>
; __device__ __forceinline__ void gemm_phase(PG8_LAS unsigned char* lds, const Gemm g, const Sched& S, const Epi& E, const int wave0) {
;     ...
;         for (int t = 0; t < nt; t += 2) {
;             const bool last = (t == nt - 2);
;             const char* a1 = cA + (size_t)(t + 1) * kstep;
;             const char* a2 = last ? nA : cA + (size_t)(t + 2) * kstep; const char* b2 = last ? nB : cB + (size_t)(t + 2) * kstep;
;             const char* a3 = a2 + kstep; const char* b3 = b2 + kstep;
;             if (last && has_next) S.a_ready(nxt);
;             if constexpr (SP2) {
;             PG8_LDB(B0, 0, 0); PG8_LDB(B1, 0, 1); PG8_SCHED; PG8_LDA(At, 0, 0); PG8_STAGE(PG8_SA(1, 1), a1 + hstepA, voffA);
;             PG8_WAIT_V(8); PG8_WAIT_L(0); PG8_BAR; PG8_MMA(0, 0, At, B0); PG8_MMA(0, 1, At, B1); PG8_BAR; PG8_SCHED;
;             PG8_LDA(At, 0, 1); PG8_STAGE(PG8_SB(0, 0), b2, voffB); PG8_STAGE(PG8_SB(0, 1), b2 + hstepB, voffB); PG8_STAGE(PG8_SA(0, 0), a2, voffA);
;             PG8_WAIT_V(8); PG8_WAIT_L(0); PG8_BAR; PG8_MMA(1, 0, At, B0); PG8_MMA(1, 1, At, B1); PG8_BAR; PG8_SCHED;
.LBB0_316:
	s_add_u32 s16, s0, 0xfff80080
	s_addc_u32 s17, s1, -1
	s_add_i32 s38, 0, 0x10000
	s_cmp_eq_u32 s37, 28
	s_cselect_b32 s19, s11, s17
	s_cselect_b32 s18, s33, s16
	s_cselect_b32 s17, s9, s36
	s_cselect_b32 s16, s34, s35
	s_add_i32 s40, 0, 0x14000
	ds_read_b128 v[144:147], v252
	ds_read_b128 v[148:151], v252 offset:1024
	ds_read_b128 v[152:155], v252 offset:2048
	ds_read_b128 v[156:159], v252 offset:3072
	ds_read_b128 v[178:181], v253
	ds_read_b128 v[182:185], v253 offset:1024
	ds_read_b128 v[186:189], v253 offset:2048
	ds_read_b128 v[190:193], v253 offset:3072
	s_add_i32 m0, s23, 0xc000
	ds_read_b128 v[194:197], v143
	ds_read_b128 v[208:211], v143 offset:1024
	ds_read_b128 v[212:215], v143 offset:2048
	ds_read_b128 v[216:219], v143 offset:3072
	ds_read_b128 v[220:223], v143 offset:4096
	ds_read_b128 v[224:227], v143 offset:5120
	ds_read_b128 v[228:231], v143 offset:6144
	ds_read_b128 v[232:235], v143 offset:7168
	global_load_lds_dwordx4 v136, s[0:1]
	s_add_i32 m0, s23, 0xe000
	s_nop 0
	global_load_lds_dwordx4 v138, s[0:1]
	s_waitcnt vmcnt(8)
	s_waitcnt lgkmcnt(0)
	s_barrier
	s_setprio 1
	s_waitcnt lgkmcnt(0)
	v_mfma_f32_16x16x32_bf16 v[126:129], v[144:147], v[194:197], v[126:129]
	v_mfma_f32_16x16x32_bf16 v[122:125], v[152:155], v[194:197], v[122:125]
	v_mfma_f32_16x16x32_bf16 v[118:121], v[144:147], v[212:215], v[118:121]
	v_mfma_f32_16x16x32_bf16 v[114:117], v[152:155], v[212:215], v[114:117]
	v_mfma_f32_16x16x32_bf16 v[102:105], v[144:147], v[220:223], v[102:105]
	v_mfma_f32_16x16x32_bf16 v[98:101], v[152:155], v[220:223], v[98:101]
	v_mfma_f32_16x16x32_bf16 v[86:89], v[144:147], v[228:231], v[86:89]
	v_mfma_f32_16x16x32_bf16 v[82:85], v[152:155], v[228:231], v[82:85]
	s_setprio 0
	s_nop 1
	s_setprio 1
	v_mfma_f32_16x16x32_bf16 v[126:129], v[148:151], v[208:211], v[126:129]
	v_mfma_f32_16x16x32_bf16 v[122:125], v[156:159], v[208:211], v[122:125]
	v_mfma_f32_16x16x32_bf16 v[118:121], v[148:151], v[216:219], v[118:121]
	v_mfma_f32_16x16x32_bf16 v[114:117], v[156:159], v[216:219], v[114:117]
	v_mfma_f32_16x16x32_bf16 v[102:105], v[148:151], v[224:227], v[102:105]
	v_mfma_f32_16x16x32_bf16 v[98:101], v[156:159], v[224:227], v[98:101]
	v_mfma_f32_16x16x32_bf16 v[86:89], v[148:151], v[232:235], v[86:89]
	v_mfma_f32_16x16x32_bf16 v[82:85], v[156:159], v[232:235], v[82:85]
	s_setprio 0
	s_nop 1
	s_setprio 1
	v_mfma_f32_16x16x32_bf16 v[110:113], v[178:181], v[194:197], v[110:113]
	v_mfma_f32_16x16x32_bf16 v[106:109], v[186:189], v[194:197], v[106:109]
	v_mfma_f32_16x16x32_bf16 v[94:97], v[178:181], v[212:215], v[94:97]
	v_mfma_f32_16x16x32_bf16 v[90:93], v[186:189], v[212:215], v[90:93]
	v_mfma_f32_16x16x32_bf16 v[78:81], v[178:181], v[220:223], v[78:81]
	v_mfma_f32_16x16x32_bf16 v[74:77], v[186:189], v[220:223], v[74:77]
	v_mfma_f32_16x16x32_bf16 v[70:73], v[178:181], v[228:231], v[70:73]
	v_mfma_f32_16x16x32_bf16 v[66:69], v[186:189], v[228:231], v[66:69]
	s_setprio 0
	s_nop 1
	s_setprio 1
	v_mfma_f32_16x16x32_bf16 v[110:113], v[182:185], v[208:211], v[110:113]
	v_mfma_f32_16x16x32_bf16 v[106:109], v[190:193], v[208:211], v[106:109]
	v_mfma_f32_16x16x32_bf16 v[94:97], v[182:185], v[216:219], v[94:97]
	v_mfma_f32_16x16x32_bf16 v[90:93], v[190:193], v[216:219], v[90:93]
	v_mfma_f32_16x16x32_bf16 v[78:81], v[182:185], v[224:227], v[78:81]
	v_mfma_f32_16x16x32_bf16 v[74:77], v[190:193], v[224:227], v[74:77]
	v_mfma_f32_16x16x32_bf16 v[70:73], v[182:185], v[232:235], v[70:73]
	v_mfma_f32_16x16x32_bf16 v[66:69], v[190:193], v[232:235], v[66:69]
	s_setprio 0
	s_barrier
	s_add_i32 s38, s38, s22
	s_mov_b32 m0, s38
	ds_read_b128 v[194:197], v143 offset:16384
	ds_read_b128 v[208:211], v143 offset:17408
	ds_read_b128 v[212:215], v143 offset:18432
	ds_read_b128 v[216:219], v143 offset:19456
	ds_read_b128 v[220:223], v143 offset:20480
	ds_read_b128 v[224:227], v143 offset:21504
	ds_read_b128 v[228:231], v143 offset:22528
	ds_read_b128 v[232:235], v143 offset:23552
	global_load_lds_dwordx4 v64, s[16:17]
	s_add_i32 m0, s38, 0x2000
	s_add_u32 s38, s16, 0x80000
	s_addc_u32 s39, s17, 0
	s_add_i32 s40, s40, s22
	global_load_lds_dwordx4 v130, s[16:17]
	s_mov_b32 m0, s40
	s_mov_b64 s[100:101], s[18:19]
	global_load_lds_dwordx4 v64, s[38:39]
	s_add_i32 m0, s40, 0x2000
	s_nop 0
	global_load_lds_dwordx4 v130, s[38:39]
	s_mov_b32 m0, s23
	s_nop 0
	global_load_lds_dwordx4 v134, s[18:19]
	s_mov_b32 m0, s24
	s_nop 0
	global_load_lds_dwordx4 v132, s[18:19]
	s_waitcnt vmcnt(8)
	s_waitcnt lgkmcnt(0)
	s_barrier
; #define PG8_STAGE(bufoff, gbase, voff) do { _Pragma("unroll") for (int _i = 0; _i < 2; ++_i) \
;         __builtin_amdgcn_global_load_lds((const unsigned*)((const char*)(gbase) + (voff)[_i]), (PG8_LAS unsigned*)(lds + (bufoff) + ldsw + _i * 8192), 16, 0, 0); } while (0)
; #define PG8_LDA(dst, b, h) do { _Pragma("unroll") for (int m = 0; m < 4; ++m) _Pragma("unroll") for (int k = 0; k < 2; ++k) dst[m][k] = *(const PG8_LAS bf16x8*)(lds + PG8_SA(b, h) + aoff + m * 2048 + k * 1024); } while (0)
; #define PG8_LDB(dst, b, h) do { _Pragma("unroll") for (int n = 0; n < 2; ++n) _Pragma("unroll") for (int k = 0; k < 2; ++k) dst[n][k] = *(const PG8_LAS bf16x8*)(lds + PG8_SB(b, h) + boff + n * 2048 + k * 1024); } while (0)
; #define PG8_MMA(ai, bj, At, Bt) do { __builtin_amdgcn_s_setprio(1); _Pragma("unroll") for (int m = 0; m < 4; ++m) _Pragma("unroll") for (int n = 0; n < 2; ++n) _Pragma("unroll") for (int k = 0; k < 2; ++k) \
;         acc[ai][bj][m][n] = __builtin_amdgcn_mfma_f32_16x16x32_bf16(Bt[n][k], At[m][k], acc[ai][bj][m][n], 0, 0, 0); __builtin_amdgcn_s_setprio(0); } while (0)
; #define PG8_WAIT_V(n) asm volatile("s_waitcnt vmcnt(" #n ")" ::: "memory")
; #define PG8_WAIT_L(n) asm volatile("s_waitcnt lgkmcnt(" #n ")" ::: "memory")
; #define PG8_BAR __builtin_amdgcn_s_barrier()
; #define PG8_SCHED __builtin_amdgcn_sched_barrier(0)
; template <class Epi, class Sched, bool ALIGN_EPI = false, bool SP2 = false>
; __device__ __forceinline__ void gemm_phase(PG8_LAS unsigned char* lds, const Gemm g, const Sched& S, const Epi& E, const int wave0) {
;     ...
;             PG8_WAIT_V(8); PG8_WAIT_L(0); PG8_BAR; PG8_MMA(0, 0, At, B0); PG8_MMA(0, 1, At, B1); PG8_BAR; PG8_SCHED;
;             PG8_LDA(At, 0, 1); PG8_STAGE(PG8_SB(0, 0), b2, voffB); PG8_STAGE(PG8_SB(0, 1), b2 + hstepB, voffB); PG8_STAGE(PG8_SA(0, 0), a2, voffA);
;             PG8_WAIT_V(8); PG8_WAIT_L(0); PG8_BAR; PG8_MMA(1, 0, At, B0); PG8_MMA(1, 1, At, B1); PG8_BAR; PG8_SCHED;
;             PG8_LDB(B0, 1, 0); PG8_LDB(B1, 1, 1); PG8_SCHED; PG8_LDA(At, 1, 0); PG8_STAGE(PG8_SA(0, 1), a2 + hstepA, voffA);
;             PG8_WAIT_V(8); PG8_WAIT_L(0); PG8_BAR; PG8_MMA(0, 0, At, B0); PG8_MMA(0, 1, At, B1); PG8_BAR; PG8_SCHED;
	s_setprio 1
	s_waitcnt lgkmcnt(0)
	v_mfma_f32_16x16x32_bf16 v[60:63], v[144:147], v[194:197], v[60:63]
	v_mfma_f32_16x16x32_bf16 v[56:59], v[152:155], v[194:197], v[56:59]
	v_mfma_f32_16x16x32_bf16 v[52:55], v[144:147], v[212:215], v[52:55]
	v_mfma_f32_16x16x32_bf16 v[48:51], v[152:155], v[212:215], v[48:51]
	v_mfma_f32_16x16x32_bf16 v[36:39], v[144:147], v[220:223], v[36:39]
	v_mfma_f32_16x16x32_bf16 v[32:35], v[152:155], v[220:223], v[32:35]
	v_mfma_f32_16x16x32_bf16 v[20:23], v[144:147], v[228:231], v[20:23]
	v_mfma_f32_16x16x32_bf16 v[16:19], v[152:155], v[228:231], v[16:19]
	s_setprio 0
	s_nop 1
	s_setprio 1
	v_mfma_f32_16x16x32_bf16 v[60:63], v[148:151], v[208:211], v[60:63]
	v_mfma_f32_16x16x32_bf16 v[56:59], v[156:159], v[208:211], v[56:59]
	v_mfma_f32_16x16x32_bf16 v[52:55], v[148:151], v[216:219], v[52:55]
	v_mfma_f32_16x16x32_bf16 v[48:51], v[156:159], v[216:219], v[48:51]
	v_mfma_f32_16x16x32_bf16 v[36:39], v[148:151], v[224:227], v[36:39]
	v_mfma_f32_16x16x32_bf16 v[32:35], v[156:159], v[224:227], v[32:35]
	v_mfma_f32_16x16x32_bf16 v[20:23], v[148:151], v[232:235], v[20:23]
	v_mfma_f32_16x16x32_bf16 v[16:19], v[156:159], v[232:235], v[16:19]
	s_setprio 0
	s_nop 1
	s_setprio 1
	v_mfma_f32_16x16x32_bf16 v[44:47], v[178:181], v[194:197], v[44:47]
	v_mfma_f32_16x16x32_bf16 v[40:43], v[186:189], v[194:197], v[40:43]
	v_mfma_f32_16x16x32_bf16 v[28:31], v[178:181], v[212:215], v[28:31]
	v_mfma_f32_16x16x32_bf16 v[24:27], v[186:189], v[212:215], v[24:27]
	v_mfma_f32_16x16x32_bf16 v[12:15], v[178:181], v[220:223], v[12:15]
	v_mfma_f32_16x16x32_bf16 v[8:11], v[186:189], v[220:223], v[8:11]
	v_mfma_f32_16x16x32_bf16 v[4:7], v[178:181], v[228:231], v[4:7]
	v_mfma_f32_16x16x32_bf16 v[0:3], v[186:189], v[228:231], v[0:3]
	s_setprio 0
	s_nop 1
	s_setprio 1
	v_mfma_f32_16x16x32_bf16 v[44:47], v[182:185], v[208:211], v[44:47]
	v_mfma_f32_16x16x32_bf16 v[40:43], v[190:193], v[208:211], v[40:43]
	v_mfma_f32_16x16x32_bf16 v[28:31], v[182:185], v[216:219], v[28:31]
	v_mfma_f32_16x16x32_bf16 v[24:27], v[190:193], v[216:219], v[24:27]
	v_mfma_f32_16x16x32_bf16 v[12:15], v[182:185], v[224:227], v[12:15]
	v_mfma_f32_16x16x32_bf16 v[8:11], v[190:193], v[224:227], v[8:11]
	v_mfma_f32_16x16x32_bf16 v[4:7], v[182:185], v[232:235], v[4:7]
	v_mfma_f32_16x16x32_bf16 v[0:3], v[190:193], v[232:235], v[0:3]
	s_setprio 0
	s_barrier
	s_add_i32 s38, 0, 0x18000
	s_add_i32 s39, 0, 0x1c000
	ds_read_b128 v[144:147], v254
	ds_read_b128 v[148:151], v254 offset:1024
	ds_read_b128 v[152:155], v254 offset:2048
	ds_read_b128 v[156:159], v254 offset:3072
	ds_read_b128 v[178:181], v255
	ds_read_b128 v[182:185], v255 offset:1024
	ds_read_b128 v[186:189], v255 offset:2048
	ds_read_b128 v[190:193], v255 offset:3072
	s_add_u32 s18, s18, 0x80000
	s_addc_u32 s19, s19, 0
	s_mov_b32 m0, s25
	ds_read_b128 v[194:197], v143 offset:32768
	ds_read_b128 v[208:211], v143 offset:33792
	ds_read_b128 v[212:215], v143 offset:34816
	ds_read_b128 v[216:219], v143 offset:35840
	ds_read_b128 v[220:223], v143 offset:36864
	ds_read_b128 v[224:227], v143 offset:37888
	ds_read_b128 v[228:231], v143 offset:38912
	ds_read_b128 v[232:235], v143 offset:39936
	global_load_lds_dwordx4 v134, s[18:19]
	s_mov_b32 m0, s26
	s_nop 0
	global_load_lds_dwordx4 v132, s[18:19]
	s_waitcnt vmcnt(8)
	s_waitcnt lgkmcnt(0)
	s_barrier
	s_setprio 1
	s_waitcnt lgkmcnt(0)
	v_mfma_f32_16x16x32_bf16 v[126:129], v[144:147], v[194:197], v[126:129]
	v_mfma_f32_16x16x32_bf16 v[122:125], v[152:155], v[194:197], v[122:125]
	v_mfma_f32_16x16x32_bf16 v[118:121], v[144:147], v[212:215], v[118:121]
	v_mfma_f32_16x16x32_bf16 v[114:117], v[152:155], v[212:215], v[114:117]
	v_mfma_f32_16x16x32_bf16 v[102:105], v[144:147], v[220:223], v[102:105]
	v_mfma_f32_16x16x32_bf16 v[98:101], v[152:155], v[220:223], v[98:101]
	v_mfma_f32_16x16x32_bf16 v[86:89], v[144:147], v[228:231], v[86:89]
	v_mfma_f32_16x16x32_bf16 v[82:85], v[152:155], v[228:231], v[82:85]
	s_setprio 0
	s_nop 1
	s_setprio 1
	v_mfma_f32_16x16x32_bf16 v[126:129], v[148:151], v[208:211], v[126:129]
	v_mfma_f32_16x16x32_bf16 v[122:125], v[156:159], v[208:211], v[122:125]
	v_mfma_f32_16x16x32_bf16 v[118:121], v[148:151], v[216:219], v[118:121]
	v_mfma_f32_16x16x32_bf16 v[114:117], v[156:159], v[216:219], v[114:117]
	v_mfma_f32_16x16x32_bf16 v[102:105], v[148:151], v[224:227], v[102:105]
	v_mfma_f32_16x16x32_bf16 v[98:101], v[156:159], v[224:227], v[98:101]
	v_mfma_f32_16x16x32_bf16 v[86:89], v[148:151], v[232:235], v[86:89]
	v_mfma_f32_16x16x32_bf16 v[82:85], v[156:159], v[232:235], v[82:85]
	s_setprio 0
	s_nop 1
	s_setprio 1
	v_mfma_f32_16x16x32_bf16 v[110:113], v[178:181], v[194:197], v[110:113]
	v_mfma_f32_16x16x32_bf16 v[106:109], v[186:189], v[194:197], v[106:109]
	v_mfma_f32_16x16x32_bf16 v[94:97], v[178:181], v[212:215], v[94:97]
	v_mfma_f32_16x16x32_bf16 v[90:93], v[186:189], v[212:215], v[90:93]
	v_mfma_f32_16x16x32_bf16 v[78:81], v[178:181], v[220:223], v[78:81]
	v_mfma_f32_16x16x32_bf16 v[74:77], v[186:189], v[220:223], v[74:77]
	v_mfma_f32_16x16x32_bf16 v[70:73], v[178:181], v[228:231], v[70:73]
	v_mfma_f32_16x16x32_bf16 v[66:69], v[186:189], v[228:231], v[66:69]
	s_setprio 0
	s_nop 1
	s_setprio 1
	v_mfma_f32_16x16x32_bf16 v[110:113], v[182:185], v[208:211], v[110:113]
	v_mfma_f32_16x16x32_bf16 v[106:109], v[190:193], v[208:211], v[106:109]
	v_mfma_f32_16x16x32_bf16 v[94:97], v[182:185], v[216:219], v[94:97]
	v_mfma_f32_16x16x32_bf16 v[90:93], v[190:193], v[216:219], v[90:93]
	v_mfma_f32_16x16x32_bf16 v[78:81], v[182:185], v[224:227], v[78:81]
	v_mfma_f32_16x16x32_bf16 v[74:77], v[190:193], v[224:227], v[74:77]
	v_mfma_f32_16x16x32_bf16 v[70:73], v[182:185], v[232:235], v[70:73]
	v_mfma_f32_16x16x32_bf16 v[66:69], v[190:193], v[232:235], v[66:69]
	s_setprio 0
	s_barrier
; #define PG8_STAGE(bufoff, gbase, voff) do { _Pragma("unroll") for (int _i = 0; _i < 2; ++_i) \
;         __builtin_amdgcn_global_load_lds((const unsigned*)((const char*)(gbase) + (voff)[_i]), (PG8_LAS unsigned*)(lds + (bufoff) + ldsw + _i * 8192), 16, 0, 0); } while (0)
; #define PG8_LDA(dst, b, h) do { _Pragma("unroll") for (int m = 0; m < 4; ++m) _Pragma("unroll") for (int k = 0; k < 2; ++k) dst[m][k] = *(const PG8_LAS bf16x8*)(lds + PG8_SA(b, h) + aoff + m * 2048 + k * 1024); } while (0)
; #define PG8_MMA(ai, bj, At, Bt) do { __builtin_amdgcn_s_setprio(1); _Pragma("unroll") for (int m = 0; m < 4; ++m) _Pragma("unroll") for (int n = 0; n < 2; ++n) _Pragma("unroll") for (int k = 0; k < 2; ++k) \
;         acc[ai][bj][m][n] = __builtin_amdgcn_mfma_f32_16x16x32_bf16(Bt[n][k], At[m][k], acc[ai][bj][m][n], 0, 0, 0); __builtin_amdgcn_s_setprio(0); } while (0)
; #define PG8_WAIT_V(n) asm volatile("s_waitcnt vmcnt(" #n ")" ::: "memory")
; #define PG8_WAIT_L(n) asm volatile("s_waitcnt lgkmcnt(" #n ")" ::: "memory")
; #define PG8_BAR __builtin_amdgcn_s_barrier()
; #define PG8_SCHED __builtin_amdgcn_sched_barrier(0)
; template <class Epi, class Sched, bool ALIGN_EPI = false, bool SP2 = false>
; __device__ __forceinline__ void gemm_phase(PG8_LAS unsigned char* lds, const Gemm g, const Sched& S, const Epi& E, const int wave0) {
;     ...
;         for (int t = 0; t < nt; t += 2) {
;             const bool last = (t == nt - 2);
;     ...
;             PG8_LDA(At, 1, 1); PG8_STAGE(PG8_SB(1, 0), b3, voffB); PG8_STAGE(PG8_SB(1, 1), b3 + hstepB, voffB); PG8_STAGE(PG8_SA(1, 0), a3, voffA);
;             PG8_WAIT_V(8); PG8_WAIT_L(0); PG8_BAR; PG8_MMA(1, 0, At, B0); PG8_MMA(1, 1, At, B1); PG8_BAR; PG8_SCHED;
	s_add_i32 s18, s38, s22
	s_add_u32 s42, s16, 0x80
	s_addc_u32 s43, s17, 0
	s_mov_b32 m0, s18
	ds_read_b128 v[194:197], v143 offset:49152
	ds_read_b128 v[208:211], v143 offset:50176
	ds_read_b128 v[212:215], v143 offset:51200
	ds_read_b128 v[216:219], v143 offset:52224
	ds_read_b128 v[220:223], v143 offset:53248
	ds_read_b128 v[224:227], v143 offset:54272
	ds_read_b128 v[228:231], v143 offset:55296
	ds_read_b128 v[232:235], v143 offset:56320
	global_load_lds_dwordx4 v64, s[42:43]
	s_add_i32 m0, s18, 0x2000
	s_add_u32 s16, s16, 0x80080
	s_addc_u32 s17, s17, 0
	s_add_i32 s18, s39, s22
	global_load_lds_dwordx4 v130, s[42:43]
	s_mov_b32 m0, s18
	s_nop 0
	global_load_lds_dwordx4 v64, s[16:17]
	s_add_i32 m0, s18, 0x2000
	s_nop 0
	global_load_lds_dwordx4 v130, s[16:17]
	s_add_u32 s100, s100, 0x80
	s_addc_u32 s101, s101, 0
	s_mov_b32 m0, s27
	s_nop 0
	global_load_lds_dwordx4 v134, s[100:101]
	s_mov_b32 m0, s28
	s_nop 0
	global_load_lds_dwordx4 v132, s[100:101]
	s_waitcnt vmcnt(8)
	s_waitcnt lgkmcnt(0)
	s_barrier
	s_setprio 1
	s_waitcnt lgkmcnt(0)
	v_mfma_f32_16x16x32_bf16 v[60:63], v[144:147], v[194:197], v[60:63]
	v_mfma_f32_16x16x32_bf16 v[56:59], v[152:155], v[194:197], v[56:59]
	v_mfma_f32_16x16x32_bf16 v[52:55], v[144:147], v[212:215], v[52:55]
	v_mfma_f32_16x16x32_bf16 v[48:51], v[152:155], v[212:215], v[48:51]
	v_mfma_f32_16x16x32_bf16 v[36:39], v[144:147], v[220:223], v[36:39]
	v_mfma_f32_16x16x32_bf16 v[32:35], v[152:155], v[220:223], v[32:35]
	v_mfma_f32_16x16x32_bf16 v[20:23], v[144:147], v[228:231], v[20:23]
	v_mfma_f32_16x16x32_bf16 v[16:19], v[152:155], v[228:231], v[16:19]
	s_setprio 0
	s_nop 1
	s_setprio 1
	v_mfma_f32_16x16x32_bf16 v[60:63], v[148:151], v[208:211], v[60:63]
	v_mfma_f32_16x16x32_bf16 v[56:59], v[156:159], v[208:211], v[56:59]
	v_mfma_f32_16x16x32_bf16 v[52:55], v[148:151], v[216:219], v[52:55]
	v_mfma_f32_16x16x32_bf16 v[48:51], v[156:159], v[216:219], v[48:51]
	v_mfma_f32_16x16x32_bf16 v[36:39], v[148:151], v[224:227], v[36:39]
	v_mfma_f32_16x16x32_bf16 v[32:35], v[156:159], v[224:227], v[32:35]
	v_mfma_f32_16x16x32_bf16 v[20:23], v[148:151], v[232:235], v[20:23]
	v_mfma_f32_16x16x32_bf16 v[16:19], v[156:159], v[232:235], v[16:19]
	s_setprio 0
	s_nop 1
	s_setprio 1
	v_mfma_f32_16x16x32_bf16 v[44:47], v[178:181], v[194:197], v[44:47]
	v_mfma_f32_16x16x32_bf16 v[40:43], v[186:189], v[194:197], v[40:43]
	v_mfma_f32_16x16x32_bf16 v[28:31], v[178:181], v[212:215], v[28:31]
	v_mfma_f32_16x16x32_bf16 v[24:27], v[186:189], v[212:215], v[24:27]
	v_mfma_f32_16x16x32_bf16 v[12:15], v[178:181], v[220:223], v[12:15]
	v_mfma_f32_16x16x32_bf16 v[8:11], v[186:189], v[220:223], v[8:11]
	v_mfma_f32_16x16x32_bf16 v[4:7], v[178:181], v[228:231], v[4:7]
	v_mfma_f32_16x16x32_bf16 v[0:3], v[186:189], v[228:231], v[0:3]
	s_setprio 0
	s_nop 1
	s_setprio 1
	v_mfma_f32_16x16x32_bf16 v[44:47], v[182:185], v[208:211], v[44:47]
	v_mfma_f32_16x16x32_bf16 v[40:43], v[190:193], v[208:211], v[40:43]
	v_mfma_f32_16x16x32_bf16 v[28:31], v[182:185], v[216:219], v[28:31]
	v_mfma_f32_16x16x32_bf16 v[24:27], v[190:193], v[216:219], v[24:27]
	v_mfma_f32_16x16x32_bf16 v[12:15], v[182:185], v[224:227], v[12:15]
	v_mfma_f32_16x16x32_bf16 v[8:11], v[190:193], v[224:227], v[8:11]
	v_mfma_f32_16x16x32_bf16 v[4:7], v[182:185], v[232:235], v[4:7]
	v_mfma_f32_16x16x32_bf16 v[0:3], v[190:193], v[232:235], v[0:3]
	s_setprio 0
	s_barrier
	s_add_i32 s37, s37, 2
	s_add_u32 s0, s0, 0x100
	s_addc_u32 s1, s1, 0
	s_add_u32 s35, s35, 0x100
	s_addc_u32 s36, s36, 0
	s_cmp_gt_u32 s37, 29
	s_cbranch_scc0 .LBB0_316
	s_mov_b64 s[42:43], 0x80
	s_and_b64 vcc, exec, s[6:7]
	s_mov_b64 s[34:35], 0x45000
	s_cbranch_vccz .LBB0_319
	s_barrier

; #define PG8_STAGE(bufoff, gbase, voff) do { _Pragma("unroll") for (int _i = 0; _i < 2; ++_i) \
;         __builtin_amdgcn_global_load_lds((const unsigned*)((const char*)(gbase) + (voff)[_i]), (PG8_LAS unsigned*)(lds + (bufoff) + ldsw + _i * 8192), 16, 0, 0); } while (0)
; #define PG8_LDA(dst, b, h) do { _Pragma("unroll") for (int m = 0; m < 4; ++m) _Pragma("unroll") for (int k = 0; k < 2; ++k) dst[m][k] = *(const PG8_LAS bf16x8*)(lds + PG8_SA(b, h) + aoff + m * 2048 + k * 1024); } while (0)
; #define PG8_LDB(dst, b, h) do { _Pragma("unroll") for (int n = 0; n < 2; ++n) _Pragma("unroll") for (int k = 0; k < 2; ++k) dst[n][k] = *(const PG8_LAS bf16x8*)(lds + PG8_SB(b, h) + boff + n * 2048 + k * 1024); } while (0)
; #define PG8_WAIT_V(n) asm volatile("s_waitcnt vmcnt(" #n ")" ::: "memory")
; #define PG8_WAIT_L(n) asm volatile("s_waitcnt lgkmcnt(" #n ")" ::: "memory")
; #define PG8_BAR __builtin_amdgcn_s_barrier()
; #define PG8_SCHED __builtin_amdgcn_sched_barrier(0)
; template <class Epi, class Sched, bool ALIGN_EPI = false, bool SP2 = false>
; __device__ __forceinline__ void gemm_phase(PG8_LAS unsigned char* lds, const Gemm g, const Sched& S, const Epi& E, const int wave0) {
;     ...
;         for (int t = 0; t < nt; t += 2) {
;             const bool last = (t == nt - 2);
;             const char* a1 = cA + (size_t)(t + 1) * kstep;
;             const char* a2 = last ? nA : cA + (size_t)(t + 2) * kstep; const char* b2 = last ? nB : cB + (size_t)(t + 2) * kstep;
;             const char* a3 = a2 + kstep; const char* b3 = b2 + kstep;
;             if (last && has_next) S.a_ready(nxt);
;             if constexpr (SP2) {
;             PG8_LDB(B0, 0, 0); PG8_LDB(B1, 0, 1); PG8_SCHED; PG8_LDA(At, 0, 0); PG8_STAGE(PG8_SA(1, 1), a1 + hstepA, voffA);
;             PG8_WAIT_V(8); PG8_WAIT_L(0); PG8_BAR; PG8_MMA(0, 0, At, B0); PG8_MMA(0, 1, At, B1); PG8_BAR; PG8_SCHED;
;             PG8_LDA(At, 0, 1); PG8_STAGE(PG8_SB(0, 0), b2, voffB); PG8_STAGE(PG8_SB(0, 1), b2 + hstepB, voffB); PG8_STAGE(PG8_SA(0, 0), a2, voffA);
;             PG8_WAIT_V(8); PG8_WAIT_L(0); PG8_BAR; PG8_MMA(1, 0, At, B0); PG8_MMA(1, 1, At, B1); PG8_BAR; PG8_SCHED;
;             PG8_LDB(B0, 1, 0); PG8_LDB(B1, 1, 1); PG8_SCHED; PG8_LDA(At, 1, 0); PG8_STAGE(PG8_SA(0, 1), a2 + hstepA, voffA);
;             PG8_WAIT_V(8); PG8_WAIT_L(0); PG8_BAR; PG8_MMA(0, 0, At, B0); PG8_MMA(0, 1, At, B1); PG8_BAR; PG8_SCHED;
.LBB0_1178:
	s_add_u32 s2, s0, 0xfffc0080
	s_addc_u32 s3, s1, -1
	s_add_i32 s31, 0, 0x10000
	s_cmp_eq_u32 s19, 12
	s_cselect_b32 s17, s45, s3
	s_cselect_b32 s16, s44, s2
	s_cselect_b32 s3, s9, s18
	s_cselect_b32 s2, s11, s13
	s_add_i32 s33, 0, 0x14000
	ds_read_b128 v[130:133], v252
	ds_read_b128 v[134:137], v252 offset:1024
	ds_read_b128 v[148:151], v252 offset:2048
	ds_read_b128 v[152:155], v252 offset:3072
	ds_read_b128 v[178:181], v253
	ds_read_b128 v[182:185], v253 offset:1024
	ds_read_b128 v[186:189], v253 offset:2048
	ds_read_b128 v[190:193], v253 offset:3072
	s_add_i32 m0, s23, 0xc000
	ds_read_b128 v[194:197], v159
	ds_read_b128 v[208:211], v159 offset:1024
	ds_read_b128 v[212:215], v159 offset:2048
	ds_read_b128 v[216:219], v159 offset:3072
	ds_read_b128 v[220:223], v159 offset:4096
	ds_read_b128 v[224:227], v159 offset:5120
	ds_read_b128 v[228:231], v159 offset:6144
	ds_read_b128 v[232:235], v159 offset:7168
	global_load_lds_dwordx4 v144, s[0:1]
	s_add_i32 m0, s23, 0xe000
	s_nop 0
	global_load_lds_dwordx4 v146, s[0:1]
	s_waitcnt vmcnt(8)
	s_waitcnt lgkmcnt(0)
	s_barrier
	s_setprio 1
	s_waitcnt lgkmcnt(0)
	v_mfma_f32_16x16x32_bf16 v[126:129], v[130:133], v[194:197], v[126:129]
	v_mfma_f32_16x16x32_bf16 v[122:125], v[148:151], v[194:197], v[122:125]
	v_mfma_f32_16x16x32_bf16 v[110:113], v[130:133], v[212:215], v[110:113]
	v_mfma_f32_16x16x32_bf16 v[106:109], v[148:151], v[212:215], v[106:109]
	v_mfma_f32_16x16x32_bf16 v[94:97], v[130:133], v[220:223], v[94:97]
	v_mfma_f32_16x16x32_bf16 v[90:93], v[148:151], v[220:223], v[90:93]
	v_mfma_f32_16x16x32_bf16 v[78:81], v[130:133], v[228:231], v[78:81]
	v_mfma_f32_16x16x32_bf16 v[74:77], v[148:151], v[228:231], v[74:77]
	s_setprio 0
	s_nop 1
	s_setprio 1
	v_mfma_f32_16x16x32_bf16 v[126:129], v[134:137], v[208:211], v[126:129]
	v_mfma_f32_16x16x32_bf16 v[122:125], v[152:155], v[208:211], v[122:125]
	v_mfma_f32_16x16x32_bf16 v[110:113], v[134:137], v[216:219], v[110:113]
	v_mfma_f32_16x16x32_bf16 v[106:109], v[152:155], v[216:219], v[106:109]
	v_mfma_f32_16x16x32_bf16 v[94:97], v[134:137], v[224:227], v[94:97]
	v_mfma_f32_16x16x32_bf16 v[90:93], v[152:155], v[224:227], v[90:93]
	v_mfma_f32_16x16x32_bf16 v[78:81], v[134:137], v[232:235], v[78:81]
	v_mfma_f32_16x16x32_bf16 v[74:77], v[152:155], v[232:235], v[74:77]
	s_setprio 0
	s_nop 1
	s_setprio 1
	v_mfma_f32_16x16x32_bf16 v[118:121], v[178:181], v[194:197], v[118:121]
	v_mfma_f32_16x16x32_bf16 v[114:117], v[186:189], v[194:197], v[114:117]
	v_mfma_f32_16x16x32_bf16 v[102:105], v[178:181], v[212:215], v[102:105]
	v_mfma_f32_16x16x32_bf16 v[98:101], v[186:189], v[212:215], v[98:101]
	v_mfma_f32_16x16x32_bf16 v[86:89], v[178:181], v[220:223], v[86:89]
	v_mfma_f32_16x16x32_bf16 v[82:85], v[186:189], v[220:223], v[82:85]
	v_mfma_f32_16x16x32_bf16 v[70:73], v[178:181], v[228:231], v[70:73]
	v_mfma_f32_16x16x32_bf16 v[66:69], v[186:189], v[228:231], v[66:69]
	s_setprio 0
	s_nop 1
	s_setprio 1
	v_mfma_f32_16x16x32_bf16 v[118:121], v[182:185], v[208:211], v[118:121]
	v_mfma_f32_16x16x32_bf16 v[114:117], v[190:193], v[208:211], v[114:117]
	v_mfma_f32_16x16x32_bf16 v[102:105], v[182:185], v[216:219], v[102:105]
	v_mfma_f32_16x16x32_bf16 v[98:101], v[190:193], v[216:219], v[98:101]
	v_mfma_f32_16x16x32_bf16 v[86:89], v[182:185], v[224:227], v[86:89]
	v_mfma_f32_16x16x32_bf16 v[82:85], v[190:193], v[224:227], v[82:85]
	v_mfma_f32_16x16x32_bf16 v[70:73], v[182:185], v[232:235], v[70:73]
	v_mfma_f32_16x16x32_bf16 v[66:69], v[190:193], v[232:235], v[66:69]
	s_setprio 0
	s_barrier
	s_add_i32 s31, s31, s22
	s_mov_b32 m0, s31
	ds_read_b128 v[194:197], v159 offset:16384
	ds_read_b128 v[208:211], v159 offset:17408
	ds_read_b128 v[212:215], v159 offset:18432
	ds_read_b128 v[216:219], v159 offset:19456
	ds_read_b128 v[220:223], v159 offset:20480
	ds_read_b128 v[224:227], v159 offset:21504
	ds_read_b128 v[228:231], v159 offset:22528
	ds_read_b128 v[232:235], v159 offset:23552
	global_load_lds_dwordx4 v64, s[2:3]
	s_add_i32 m0, s31, 0x2000
	s_add_u32 s34, s2, 0x40000
	s_addc_u32 s35, s3, 0
	s_add_i32 s31, s33, s22
	global_load_lds_dwordx4 v138, s[2:3]
	s_mov_b32 m0, s31
	s_mov_b64 s[100:101], s[16:17]
	global_load_lds_dwordx4 v64, s[34:35]
	s_add_i32 m0, s31, 0x2000
	s_nop 0
	global_load_lds_dwordx4 v138, s[34:35]
	s_mov_b32 m0, s23
	s_nop 0
	global_load_lds_dwordx4 v142, s[16:17]
	s_mov_b32 m0, s24
	s_nop 0
	global_load_lds_dwordx4 v140, s[16:17]
	s_waitcnt vmcnt(8)
	s_waitcnt lgkmcnt(0)
	s_barrier
	s_setprio 1
	s_waitcnt lgkmcnt(0)
	v_mfma_f32_16x16x32_bf16 v[60:63], v[130:133], v[194:197], v[60:63]
	v_mfma_f32_16x16x32_bf16 v[56:59], v[148:151], v[194:197], v[56:59]
	v_mfma_f32_16x16x32_bf16 v[44:47], v[130:133], v[212:215], v[44:47]
	v_mfma_f32_16x16x32_bf16 v[40:43], v[148:151], v[212:215], v[40:43]
	v_mfma_f32_16x16x32_bf16 v[28:31], v[130:133], v[220:223], v[28:31]
	v_mfma_f32_16x16x32_bf16 v[24:27], v[148:151], v[220:223], v[24:27]
	v_mfma_f32_16x16x32_bf16 v[12:15], v[130:133], v[228:231], v[12:15]
	v_mfma_f32_16x16x32_bf16 v[8:11], v[148:151], v[228:231], v[8:11]
	s_setprio 0
	s_nop 1
	s_setprio 1
	v_mfma_f32_16x16x32_bf16 v[60:63], v[134:137], v[208:211], v[60:63]
	v_mfma_f32_16x16x32_bf16 v[56:59], v[152:155], v[208:211], v[56:59]
	v_mfma_f32_16x16x32_bf16 v[44:47], v[134:137], v[216:219], v[44:47]
	v_mfma_f32_16x16x32_bf16 v[40:43], v[152:155], v[216:219], v[40:43]
	v_mfma_f32_16x16x32_bf16 v[28:31], v[134:137], v[224:227], v[28:31]
	v_mfma_f32_16x16x32_bf16 v[24:27], v[152:155], v[224:227], v[24:27]
	v_mfma_f32_16x16x32_bf16 v[12:15], v[134:137], v[232:235], v[12:15]
	v_mfma_f32_16x16x32_bf16 v[8:11], v[152:155], v[232:235], v[8:11]
	s_setprio 0
	s_nop 1
	s_setprio 1
	v_mfma_f32_16x16x32_bf16 v[52:55], v[178:181], v[194:197], v[52:55]
	v_mfma_f32_16x16x32_bf16 v[48:51], v[186:189], v[194:197], v[48:51]
	v_mfma_f32_16x16x32_bf16 v[36:39], v[178:181], v[212:215], v[36:39]
	v_mfma_f32_16x16x32_bf16 v[32:35], v[186:189], v[212:215], v[32:35]
	v_mfma_f32_16x16x32_bf16 v[20:23], v[178:181], v[220:223], v[20:23]
	v_mfma_f32_16x16x32_bf16 v[16:19], v[186:189], v[220:223], v[16:19]
	v_mfma_f32_16x16x32_bf16 v[4:7], v[178:181], v[228:231], v[4:7]
	v_mfma_f32_16x16x32_bf16 v[0:3], v[186:189], v[228:231], v[0:3]
	s_setprio 0
	s_nop 1
	s_setprio 1
	v_mfma_f32_16x16x32_bf16 v[52:55], v[182:185], v[208:211], v[52:55]
	v_mfma_f32_16x16x32_bf16 v[48:51], v[190:193], v[208:211], v[48:51]
	v_mfma_f32_16x16x32_bf16 v[36:39], v[182:185], v[216:219], v[36:39]
	v_mfma_f32_16x16x32_bf16 v[32:35], v[190:193], v[216:219], v[32:35]
	v_mfma_f32_16x16x32_bf16 v[20:23], v[182:185], v[224:227], v[20:23]
	v_mfma_f32_16x16x32_bf16 v[16:19], v[190:193], v[224:227], v[16:19]
	v_mfma_f32_16x16x32_bf16 v[4:7], v[182:185], v[232:235], v[4:7]
	v_mfma_f32_16x16x32_bf16 v[0:3], v[190:193], v[232:235], v[0:3]
	s_setprio 0
	s_barrier
; #define PG8_STAGE(bufoff, gbase, voff) do { _Pragma("unroll") for (int _i = 0; _i < 2; ++_i) \
;         __builtin_amdgcn_global_load_lds((const unsigned*)((const char*)(gbase) + (voff)[_i]), (PG8_LAS unsigned*)(lds + (bufoff) + ldsw + _i * 8192), 16, 0, 0); } while (0)
; #define PG8_LDA(dst, b, h) do { _Pragma("unroll") for (int m = 0; m < 4; ++m) _Pragma("unroll") for (int k = 0; k < 2; ++k) dst[m][k] = *(const PG8_LAS bf16x8*)(lds + PG8_SA(b, h) + aoff + m * 2048 + k * 1024); } while (0)
; #define PG8_LDB(dst, b, h) do { _Pragma("unroll") for (int n = 0; n < 2; ++n) _Pragma("unroll") for (int k = 0; k < 2; ++k) dst[n][k] = *(const PG8_LAS bf16x8*)(lds + PG8_SB(b, h) + boff + n * 2048 + k * 1024); } while (0)
; #define PG8_MMA(ai, bj, At, Bt) do { __builtin_amdgcn_s_setprio(1); _Pragma("unroll") for (int m = 0; m < 4; ++m) _Pragma("unroll") for (int n = 0; n < 2; ++n) _Pragma("unroll") for (int k = 0; k < 2; ++k) \
;         acc[ai][bj][m][n] = __builtin_amdgcn_mfma_f32_16x16x32_bf16(Bt[n][k], At[m][k], acc[ai][bj][m][n], 0, 0, 0); __builtin_amdgcn_s_setprio(0); } while (0)
; #define PG8_WAIT_V(n) asm volatile("s_waitcnt vmcnt(" #n ")" ::: "memory")
; #define PG8_WAIT_L(n) asm volatile("s_waitcnt lgkmcnt(" #n ")" ::: "memory")
; #define PG8_BAR __builtin_amdgcn_s_barrier()
; #define PG8_SCHED __builtin_amdgcn_sched_barrier(0)
; template <class Epi, class Sched, bool ALIGN_EPI = false, bool SP2 = false>
; __device__ __forceinline__ void gemm_phase(PG8_LAS unsigned char* lds, const Gemm g, const Sched& S, const Epi& E, const int wave0) {
;     ...
;         for (int t = 0; t < nt; t += 2) {
;             const bool last = (t == nt - 2);
;     ...
;             PG8_LDB(B0, 1, 0); PG8_LDB(B1, 1, 1); PG8_SCHED; PG8_LDA(At, 1, 0); PG8_STAGE(PG8_SA(0, 1), a2 + hstepA, voffA);
;             PG8_WAIT_V(8); PG8_WAIT_L(0); PG8_BAR; PG8_MMA(0, 0, At, B0); PG8_MMA(0, 1, At, B1); PG8_BAR; PG8_SCHED;
;             PG8_LDA(At, 1, 1); PG8_STAGE(PG8_SB(1, 0), b3, voffB); PG8_STAGE(PG8_SB(1, 1), b3 + hstepB, voffB); PG8_STAGE(PG8_SA(1, 0), a3, voffA);
;             PG8_WAIT_V(8); PG8_WAIT_L(0); PG8_BAR; PG8_MMA(1, 0, At, B0); PG8_MMA(1, 1, At, B1); PG8_BAR; PG8_SCHED;
	s_add_i32 s31, 0, 0x18000
	s_add_i32 s33, 0, 0x1c000
	ds_read_b128 v[130:133], v254
	ds_read_b128 v[134:137], v254 offset:1024
	ds_read_b128 v[148:151], v254 offset:2048
	ds_read_b128 v[152:155], v254 offset:3072
	ds_read_b128 v[178:181], v255
	ds_read_b128 v[182:185], v255 offset:1024
	ds_read_b128 v[186:189], v255 offset:2048
	ds_read_b128 v[190:193], v255 offset:3072
	s_add_u32 s16, s16, 0x40000
	s_addc_u32 s17, s17, 0
	s_mov_b32 m0, s25
	ds_read_b128 v[194:197], v159 offset:32768
	ds_read_b128 v[208:211], v159 offset:33792
	ds_read_b128 v[212:215], v159 offset:34816
	ds_read_b128 v[216:219], v159 offset:35840
	ds_read_b128 v[220:223], v159 offset:36864
	ds_read_b128 v[224:227], v159 offset:37888
	ds_read_b128 v[228:231], v159 offset:38912
	ds_read_b128 v[232:235], v159 offset:39936
	global_load_lds_dwordx4 v142, s[16:17]
	s_mov_b32 m0, s26
	s_nop 0
	global_load_lds_dwordx4 v140, s[16:17]
	s_waitcnt vmcnt(8)
	s_waitcnt lgkmcnt(0)
	s_barrier
	s_setprio 1
	s_waitcnt lgkmcnt(0)
	v_mfma_f32_16x16x32_bf16 v[126:129], v[130:133], v[194:197], v[126:129]
	v_mfma_f32_16x16x32_bf16 v[122:125], v[148:151], v[194:197], v[122:125]
	v_mfma_f32_16x16x32_bf16 v[110:113], v[130:133], v[212:215], v[110:113]
	v_mfma_f32_16x16x32_bf16 v[106:109], v[148:151], v[212:215], v[106:109]
	v_mfma_f32_16x16x32_bf16 v[94:97], v[130:133], v[220:223], v[94:97]
	v_mfma_f32_16x16x32_bf16 v[90:93], v[148:151], v[220:223], v[90:93]
	v_mfma_f32_16x16x32_bf16 v[78:81], v[130:133], v[228:231], v[78:81]
	v_mfma_f32_16x16x32_bf16 v[74:77], v[148:151], v[228:231], v[74:77]
	s_setprio 0
	s_nop 1
	s_setprio 1
	v_mfma_f32_16x16x32_bf16 v[126:129], v[134:137], v[208:211], v[126:129]
	v_mfma_f32_16x16x32_bf16 v[122:125], v[152:155], v[208:211], v[122:125]
	v_mfma_f32_16x16x32_bf16 v[110:113], v[134:137], v[216:219], v[110:113]
	v_mfma_f32_16x16x32_bf16 v[106:109], v[152:155], v[216:219], v[106:109]
	v_mfma_f32_16x16x32_bf16 v[94:97], v[134:137], v[224:227], v[94:97]
	v_mfma_f32_16x16x32_bf16 v[90:93], v[152:155], v[224:227], v[90:93]
	v_mfma_f32_16x16x32_bf16 v[78:81], v[134:137], v[232:235], v[78:81]
	v_mfma_f32_16x16x32_bf16 v[74:77], v[152:155], v[232:235], v[74:77]
	s_setprio 0
	s_nop 1
	s_setprio 1
	v_mfma_f32_16x16x32_bf16 v[118:121], v[178:181], v[194:197], v[118:121]
	v_mfma_f32_16x16x32_bf16 v[114:117], v[186:189], v[194:197], v[114:117]
	v_mfma_f32_16x16x32_bf16 v[102:105], v[178:181], v[212:215], v[102:105]
	v_mfma_f32_16x16x32_bf16 v[98:101], v[186:189], v[212:215], v[98:101]
	v_mfma_f32_16x16x32_bf16 v[86:89], v[178:181], v[220:223], v[86:89]
	v_mfma_f32_16x16x32_bf16 v[82:85], v[186:189], v[220:223], v[82:85]
	v_mfma_f32_16x16x32_bf16 v[70:73], v[178:181], v[228:231], v[70:73]
	v_mfma_f32_16x16x32_bf16 v[66:69], v[186:189], v[228:231], v[66:69]
	s_setprio 0
	s_nop 1
	s_setprio 1
	v_mfma_f32_16x16x32_bf16 v[118:121], v[182:185], v[208:211], v[118:121]
	v_mfma_f32_16x16x32_bf16 v[114:117], v[190:193], v[208:211], v[114:117]
	v_mfma_f32_16x16x32_bf16 v[102:105], v[182:185], v[216:219], v[102:105]
	v_mfma_f32_16x16x32_bf16 v[98:101], v[190:193], v[216:219], v[98:101]
	v_mfma_f32_16x16x32_bf16 v[86:89], v[182:185], v[224:227], v[86:89]
	v_mfma_f32_16x16x32_bf16 v[82:85], v[190:193], v[224:227], v[82:85]
	v_mfma_f32_16x16x32_bf16 v[70:73], v[182:185], v[232:235], v[70:73]
	v_mfma_f32_16x16x32_bf16 v[66:69], v[190:193], v[232:235], v[66:69]
	s_setprio 0
	s_barrier
	s_add_i32 s16, s31, s22
	s_add_u32 s36, s2, 0x80
	s_addc_u32 s37, s3, 0
	s_mov_b32 m0, s16
	ds_read_b128 v[194:197], v159 offset:49152
	ds_read_b128 v[208:211], v159 offset:50176
	ds_read_b128 v[212:215], v159 offset:51200
	ds_read_b128 v[216:219], v159 offset:52224
	ds_read_b128 v[220:223], v159 offset:53248
	ds_read_b128 v[224:227], v159 offset:54272
	ds_read_b128 v[228:231], v159 offset:55296
	ds_read_b128 v[232:235], v159 offset:56320
	global_load_lds_dwordx4 v64, s[36:37]
	s_add_i32 m0, s16, 0x2000
	s_add_u32 s2, s2, 0x40080
	s_addc_u32 s3, s3, 0
	s_add_i32 s16, s33, s22
	global_load_lds_dwordx4 v138, s[36:37]
	s_mov_b32 m0, s16
	s_nop 0
	global_load_lds_dwordx4 v64, s[2:3]
	s_add_i32 m0, s16, 0x2000
	s_nop 0
	global_load_lds_dwordx4 v138, s[2:3]
	s_add_u32 s100, s100, 0x80
	s_addc_u32 s101, s101, 0
	s_mov_b32 m0, s27
	s_nop 0
	global_load_lds_dwordx4 v142, s[100:101]
	s_mov_b32 m0, s28
	s_nop 0
	global_load_lds_dwordx4 v140, s[100:101]
	s_waitcnt vmcnt(8)
	s_waitcnt lgkmcnt(0)
	s_barrier
	s_setprio 1
	s_waitcnt lgkmcnt(0)
	v_mfma_f32_16x16x32_bf16 v[60:63], v[130:133], v[194:197], v[60:63]
	v_mfma_f32_16x16x32_bf16 v[56:59], v[148:151], v[194:197], v[56:59]
	v_mfma_f32_16x16x32_bf16 v[44:47], v[130:133], v[212:215], v[44:47]
	v_mfma_f32_16x16x32_bf16 v[40:43], v[148:151], v[212:215], v[40:43]
	v_mfma_f32_16x16x32_bf16 v[28:31], v[130:133], v[220:223], v[28:31]
	v_mfma_f32_16x16x32_bf16 v[24:27], v[148:151], v[220:223], v[24:27]
	v_mfma_f32_16x16x32_bf16 v[12:15], v[130:133], v[228:231], v[12:15]
	v_mfma_f32_16x16x32_bf16 v[8:11], v[148:151], v[228:231], v[8:11]
	s_setprio 0
	s_nop 1
	s_setprio 1
	v_mfma_f32_16x16x32_bf16 v[60:63], v[134:137], v[208:211], v[60:63]
	v_mfma_f32_16x16x32_bf16 v[56:59], v[152:155], v[208:211], v[56:59]
	v_mfma_f32_16x16x32_bf16 v[44:47], v[134:137], v[216:219], v[44:47]
	v_mfma_f32_16x16x32_bf16 v[40:43], v[152:155], v[216:219], v[40:43]
	v_mfma_f32_16x16x32_bf16 v[28:31], v[134:137], v[224:227], v[28:31]
	v_mfma_f32_16x16x32_bf16 v[24:27], v[152:155], v[224:227], v[24:27]
	v_mfma_f32_16x16x32_bf16 v[12:15], v[134:137], v[232:235], v[12:15]
	v_mfma_f32_16x16x32_bf16 v[8:11], v[152:155], v[232:235], v[8:11]
	s_setprio 0
	s_nop 1
	s_setprio 1
	v_mfma_f32_16x16x32_bf16 v[52:55], v[178:181], v[194:197], v[52:55]
	v_mfma_f32_16x16x32_bf16 v[48:51], v[186:189], v[194:197], v[48:51]
	v_mfma_f32_16x16x32_bf16 v[36:39], v[178:181], v[212:215], v[36:39]
	v_mfma_f32_16x16x32_bf16 v[32:35], v[186:189], v[212:215], v[32:35]
	v_mfma_f32_16x16x32_bf16 v[20:23], v[178:181], v[220:223], v[20:23]
	v_mfma_f32_16x16x32_bf16 v[16:19], v[186:189], v[220:223], v[16:19]
	v_mfma_f32_16x16x32_bf16 v[4:7], v[178:181], v[228:231], v[4:7]
	v_mfma_f32_16x16x32_bf16 v[0:3], v[186:189], v[228:231], v[0:3]
	s_setprio 0
	s_nop 1
	s_setprio 1
	v_mfma_f32_16x16x32_bf16 v[52:55], v[182:185], v[208:211], v[52:55]
	v_mfma_f32_16x16x32_bf16 v[48:51], v[190:193], v[208:211], v[48:51]
	v_mfma_f32_16x16x32_bf16 v[36:39], v[182:185], v[216:219], v[36:39]
	v_mfma_f32_16x16x32_bf16 v[32:35], v[190:193], v[216:219], v[32:35]
	v_mfma_f32_16x16x32_bf16 v[20:23], v[182:185], v[224:227], v[20:23]
	v_mfma_f32_16x16x32_bf16 v[16:19], v[190:193], v[224:227], v[16:19]
	v_mfma_f32_16x16x32_bf16 v[4:7], v[182:185], v[232:235], v[4:7]
	v_mfma_f32_16x16x32_bf16 v[0:3], v[190:193], v[232:235], v[0:3]
	s_setprio 0
	s_barrier
	s_add_i32 s19, s19, 2
	s_add_u32 s0, s0, 0x100
	s_addc_u32 s1, s1, 0
	s_add_u32 s13, s13, 0x100
	s_addc_u32 s18, s18, 0
	s_cmp_gt_u32 s19, 13
	s_cbranch_scc0 .LBB0_1178
	s_mov_b64 s[36:37], 0x80
	s_and_b64 vcc, exec, s[6:7]
	s_cbranch_vccz .LBB0_1181
	s_barrier

; #define PG8_STAGE(bufoff, gbase, voff) do { _Pragma("unroll") for (int _i = 0; _i < 2; ++_i) \
;         __builtin_amdgcn_global_load_lds((const unsigned*)((const char*)(gbase) + (voff)[_i]), (PG8_LAS unsigned*)(lds + (bufoff) + ldsw + _i * 8192), 16, 0, 0); } while (0)
; #define PG8_LDA(dst, b, h) do { _Pragma("unroll") for (int m = 0; m < 4; ++m) _Pragma("unroll") for (int k = 0; k < 2; ++k) dst[m][k] = *(const PG8_LAS bf16x8*)(lds + PG8_SA(b, h) + aoff + m * 2048 + k * 1024); } while (0)
; #define PG8_LDB(dst, b, h) do { _Pragma("unroll") for (int n = 0; n < 2; ++n) _Pragma("unroll") for (int k = 0; k < 2; ++k) dst[n][k] = *(const PG8_LAS bf16x8*)(lds + PG8_SB(b, h) + boff + n * 2048 + k * 1024); } while (0)
; #define PG8_WAIT_V(n) asm volatile("s_waitcnt vmcnt(" #n ")" ::: "memory")
; #define PG8_WAIT_L(n) asm volatile("s_waitcnt lgkmcnt(" #n ")" ::: "memory")
; #define PG8_BAR __builtin_amdgcn_s_barrier()
; #define PG8_SCHED __builtin_amdgcn_sched_barrier(0)
; template <class Epi, class Sched, bool ALIGN_EPI = false, bool SP2 = false>
; __device__ __forceinline__ void gemm_phase(PG8_LAS unsigned char* lds, const Gemm g, const Sched& S, const Epi& E, const int wave0) {
;     ...
;         for (int t = 0; t < nt; t += 2) {
;             const bool last = (t == nt - 2);
;             const char* a1 = cA + (size_t)(t + 1) * kstep;
;             const char* a2 = last ? nA : cA + (size_t)(t + 2) * kstep; const char* b2 = last ? nB : cB + (size_t)(t + 2) * kstep;
;             const char* a3 = a2 + kstep; const char* b3 = b2 + kstep;
;             if (last && has_next) S.a_ready(nxt);
;             if constexpr (SP2) {
;             PG8_LDB(B0, 0, 0); PG8_LDB(B1, 0, 1); PG8_SCHED; PG8_LDA(At, 0, 0); PG8_STAGE(PG8_SA(1, 1), a1 + hstepA, voffA);
;             PG8_WAIT_V(8); PG8_WAIT_L(0); PG8_BAR; PG8_MMA(0, 0, At, B0); PG8_MMA(0, 1, At, B1); PG8_BAR; PG8_SCHED;
;             PG8_LDA(At, 0, 1); PG8_STAGE(PG8_SB(0, 0), b2, voffB); PG8_STAGE(PG8_SB(0, 1), b2 + hstepB, voffB); PG8_STAGE(PG8_SA(0, 0), a2, voffA);
;             PG8_WAIT_V(8); PG8_WAIT_L(0); PG8_BAR; PG8_MMA(1, 0, At, B0); PG8_MMA(1, 1, At, B1); PG8_BAR; PG8_SCHED;
;             PG8_LDB(B0, 1, 0); PG8_LDB(B1, 1, 1); PG8_SCHED; PG8_LDA(At, 1, 0); PG8_STAGE(PG8_SA(0, 1), a2 + hstepA, voffA);
;             PG8_WAIT_V(8); PG8_WAIT_L(0); PG8_BAR; PG8_MMA(0, 0, At, B0); PG8_MMA(0, 1, At, B1); PG8_BAR; PG8_SCHED;
.LBB0_1231:
	s_add_u32 s2, s0, 0xfffc0080
	s_addc_u32 s3, s1, -1
	s_add_i32 s31, 0, 0x10000
	s_cmp_eq_u32 s19, 12
	s_cselect_b32 s17, s43, s3
	s_cselect_b32 s16, s42, s2
	s_cselect_b32 s3, s9, s18
	s_cselect_b32 s2, s11, s13
	s_add_i32 s33, 0, 0x14000
	ds_read_b128 v[140:143], v252
	ds_read_b128 v[144:147], v252 offset:1024
	ds_read_b128 v[154:157], v252 offset:2048
	ds_read_b128 v[158:161], v252 offset:3072
	ds_read_b128 v[178:181], v253
	ds_read_b128 v[182:185], v253 offset:1024
	ds_read_b128 v[186:189], v253 offset:2048
	ds_read_b128 v[190:193], v253 offset:3072
	s_add_i32 m0, s23, 0xc000
	ds_read_b128 v[194:197], v153
	ds_read_b128 v[208:211], v153 offset:1024
	ds_read_b128 v[212:215], v153 offset:2048
	ds_read_b128 v[216:219], v153 offset:3072
	ds_read_b128 v[220:223], v153 offset:4096
	ds_read_b128 v[224:227], v153 offset:5120
	ds_read_b128 v[228:231], v153 offset:6144
	ds_read_b128 v[232:235], v153 offset:7168
	global_load_lds_dwordx4 v136, s[0:1]
	s_add_i32 m0, s23, 0xe000
	s_nop 0
	global_load_lds_dwordx4 v138, s[0:1]
	s_waitcnt vmcnt(8)
	s_waitcnt lgkmcnt(0)
	s_barrier
	s_setprio 1
	s_waitcnt lgkmcnt(0)
	v_mfma_f32_16x16x32_bf16 v[126:129], v[140:143], v[194:197], v[126:129]
	v_mfma_f32_16x16x32_bf16 v[122:125], v[154:157], v[194:197], v[122:125]
	v_mfma_f32_16x16x32_bf16 v[110:113], v[140:143], v[212:215], v[110:113]
	v_mfma_f32_16x16x32_bf16 v[106:109], v[154:157], v[212:215], v[106:109]
	v_mfma_f32_16x16x32_bf16 v[94:97], v[140:143], v[220:223], v[94:97]
	v_mfma_f32_16x16x32_bf16 v[90:93], v[154:157], v[220:223], v[90:93]
	v_mfma_f32_16x16x32_bf16 v[78:81], v[140:143], v[228:231], v[78:81]
	v_mfma_f32_16x16x32_bf16 v[74:77], v[154:157], v[228:231], v[74:77]
	s_setprio 0
	s_nop 1
	s_setprio 1
	v_mfma_f32_16x16x32_bf16 v[126:129], v[144:147], v[208:211], v[126:129]
	v_mfma_f32_16x16x32_bf16 v[122:125], v[158:161], v[208:211], v[122:125]
	v_mfma_f32_16x16x32_bf16 v[110:113], v[144:147], v[216:219], v[110:113]
	v_mfma_f32_16x16x32_bf16 v[106:109], v[158:161], v[216:219], v[106:109]
	v_mfma_f32_16x16x32_bf16 v[94:97], v[144:147], v[224:227], v[94:97]
	v_mfma_f32_16x16x32_bf16 v[90:93], v[158:161], v[224:227], v[90:93]
	v_mfma_f32_16x16x32_bf16 v[78:81], v[144:147], v[232:235], v[78:81]
	v_mfma_f32_16x16x32_bf16 v[74:77], v[158:161], v[232:235], v[74:77]
	s_setprio 0
	s_nop 1
	s_setprio 1
	v_mfma_f32_16x16x32_bf16 v[118:121], v[178:181], v[194:197], v[118:121]
	v_mfma_f32_16x16x32_bf16 v[114:117], v[186:189], v[194:197], v[114:117]
	v_mfma_f32_16x16x32_bf16 v[102:105], v[178:181], v[212:215], v[102:105]
	v_mfma_f32_16x16x32_bf16 v[98:101], v[186:189], v[212:215], v[98:101]
	v_mfma_f32_16x16x32_bf16 v[86:89], v[178:181], v[220:223], v[86:89]
	v_mfma_f32_16x16x32_bf16 v[82:85], v[186:189], v[220:223], v[82:85]
	v_mfma_f32_16x16x32_bf16 v[70:73], v[178:181], v[228:231], v[70:73]
	v_mfma_f32_16x16x32_bf16 v[66:69], v[186:189], v[228:231], v[66:69]
	s_setprio 0
	s_nop 1
	s_setprio 1
	v_mfma_f32_16x16x32_bf16 v[118:121], v[182:185], v[208:211], v[118:121]
	v_mfma_f32_16x16x32_bf16 v[114:117], v[190:193], v[208:211], v[114:117]
	v_mfma_f32_16x16x32_bf16 v[102:105], v[182:185], v[216:219], v[102:105]
	v_mfma_f32_16x16x32_bf16 v[98:101], v[190:193], v[216:219], v[98:101]
	v_mfma_f32_16x16x32_bf16 v[86:89], v[182:185], v[224:227], v[86:89]
	v_mfma_f32_16x16x32_bf16 v[82:85], v[190:193], v[224:227], v[82:85]
	v_mfma_f32_16x16x32_bf16 v[70:73], v[182:185], v[232:235], v[70:73]
	v_mfma_f32_16x16x32_bf16 v[66:69], v[190:193], v[232:235], v[66:69]
	s_setprio 0
	s_barrier
	s_add_i32 s31, s31, s22
	s_mov_b32 m0, s31
	ds_read_b128 v[194:197], v153 offset:16384
	ds_read_b128 v[208:211], v153 offset:17408
	ds_read_b128 v[212:215], v153 offset:18432
	ds_read_b128 v[216:219], v153 offset:19456
	ds_read_b128 v[220:223], v153 offset:20480
	ds_read_b128 v[224:227], v153 offset:21504
	ds_read_b128 v[228:231], v153 offset:22528
	ds_read_b128 v[232:235], v153 offset:23552
	global_load_lds_dwordx4 v64, s[2:3]
	s_add_i32 m0, s31, 0x2000
	s_add_u32 s34, s2, 0x40000
	s_addc_u32 s35, s3, 0
	s_add_i32 s31, s33, s22
	global_load_lds_dwordx4 v130, s[2:3]
	s_mov_b32 m0, s31
	s_mov_b64 s[100:101], s[16:17]
	global_load_lds_dwordx4 v64, s[34:35]
	s_add_i32 m0, s31, 0x2000
	s_nop 0
	global_load_lds_dwordx4 v130, s[34:35]
	s_mov_b32 m0, s23
	s_nop 0
	global_load_lds_dwordx4 v134, s[16:17]
	s_mov_b32 m0, s24
	s_nop 0
	global_load_lds_dwordx4 v132, s[16:17]
	s_waitcnt vmcnt(8)
	s_waitcnt lgkmcnt(0)
	s_barrier
	s_setprio 1
	s_waitcnt lgkmcnt(0)
	v_mfma_f32_16x16x32_bf16 v[60:63], v[140:143], v[194:197], v[60:63]
	v_mfma_f32_16x16x32_bf16 v[56:59], v[154:157], v[194:197], v[56:59]
	v_mfma_f32_16x16x32_bf16 v[44:47], v[140:143], v[212:215], v[44:47]
	v_mfma_f32_16x16x32_bf16 v[40:43], v[154:157], v[212:215], v[40:43]
	v_mfma_f32_16x16x32_bf16 v[28:31], v[140:143], v[220:223], v[28:31]
	v_mfma_f32_16x16x32_bf16 v[24:27], v[154:157], v[220:223], v[24:27]
	v_mfma_f32_16x16x32_bf16 v[12:15], v[140:143], v[228:231], v[12:15]
	v_mfma_f32_16x16x32_bf16 v[8:11], v[154:157], v[228:231], v[8:11]
	s_setprio 0
	s_nop 1
	s_setprio 1
	v_mfma_f32_16x16x32_bf16 v[60:63], v[144:147], v[208:211], v[60:63]
	v_mfma_f32_16x16x32_bf16 v[56:59], v[158:161], v[208:211], v[56:59]
	v_mfma_f32_16x16x32_bf16 v[44:47], v[144:147], v[216:219], v[44:47]
	v_mfma_f32_16x16x32_bf16 v[40:43], v[158:161], v[216:219], v[40:43]
	v_mfma_f32_16x16x32_bf16 v[28:31], v[144:147], v[224:227], v[28:31]
	v_mfma_f32_16x16x32_bf16 v[24:27], v[158:161], v[224:227], v[24:27]
	v_mfma_f32_16x16x32_bf16 v[12:15], v[144:147], v[232:235], v[12:15]
	v_mfma_f32_16x16x32_bf16 v[8:11], v[158:161], v[232:235], v[8:11]
	s_setprio 0
	s_nop 1
	s_setprio 1
	v_mfma_f32_16x16x32_bf16 v[52:55], v[178:181], v[194:197], v[52:55]
	v_mfma_f32_16x16x32_bf16 v[48:51], v[186:189], v[194:197], v[48:51]
	v_mfma_f32_16x16x32_bf16 v[36:39], v[178:181], v[212:215], v[36:39]
	v_mfma_f32_16x16x32_bf16 v[32:35], v[186:189], v[212:215], v[32:35]
	v_mfma_f32_16x16x32_bf16 v[20:23], v[178:181], v[220:223], v[20:23]
	v_mfma_f32_16x16x32_bf16 v[16:19], v[186:189], v[220:223], v[16:19]
	v_mfma_f32_16x16x32_bf16 v[4:7], v[178:181], v[228:231], v[4:7]
	v_mfma_f32_16x16x32_bf16 v[0:3], v[186:189], v[228:231], v[0:3]
	s_setprio 0
	s_nop 1
	s_setprio 1
	v_mfma_f32_16x16x32_bf16 v[52:55], v[182:185], v[208:211], v[52:55]
	v_mfma_f32_16x16x32_bf16 v[48:51], v[190:193], v[208:211], v[48:51]
	v_mfma_f32_16x16x32_bf16 v[36:39], v[182:185], v[216:219], v[36:39]
	v_mfma_f32_16x16x32_bf16 v[32:35], v[190:193], v[216:219], v[32:35]
	v_mfma_f32_16x16x32_bf16 v[20:23], v[182:185], v[224:227], v[20:23]
	v_mfma_f32_16x16x32_bf16 v[16:19], v[190:193], v[224:227], v[16:19]
	v_mfma_f32_16x16x32_bf16 v[4:7], v[182:185], v[232:235], v[4:7]
	v_mfma_f32_16x16x32_bf16 v[0:3], v[190:193], v[232:235], v[0:3]
	s_setprio 0
	s_barrier
; #define PG8_STAGE(bufoff, gbase, voff) do { _Pragma("unroll") for (int _i = 0; _i < 2; ++_i) \
;         __builtin_amdgcn_global_load_lds((const unsigned*)((const char*)(gbase) + (voff)[_i]), (PG8_LAS unsigned*)(lds + (bufoff) + ldsw + _i * 8192), 16, 0, 0); } while (0)
; #define PG8_LDA(dst, b, h) do { _Pragma("unroll") for (int m = 0; m < 4; ++m) _Pragma("unroll") for (int k = 0; k < 2; ++k) dst[m][k] = *(const PG8_LAS bf16x8*)(lds + PG8_SA(b, h) + aoff + m * 2048 + k * 1024); } while (0)
; #define PG8_LDB(dst, b, h) do { _Pragma("unroll") for (int n = 0; n < 2; ++n) _Pragma("unroll") for (int k = 0; k < 2; ++k) dst[n][k] = *(const PG8_LAS bf16x8*)(lds + PG8_SB(b, h) + boff + n * 2048 + k * 1024); } while (0)
; #define PG8_MMA(ai, bj, At, Bt) do { __builtin_amdgcn_s_setprio(1); _Pragma("unroll") for (int m = 0; m < 4; ++m) _Pragma("unroll") for (int n = 0; n < 2; ++n) _Pragma("unroll") for (int k = 0; k < 2; ++k) \
;         acc[ai][bj][m][n] = __builtin_amdgcn_mfma_f32_16x16x32_bf16(Bt[n][k], At[m][k], acc[ai][bj][m][n], 0, 0, 0); __builtin_amdgcn_s_setprio(0); } while (0)
; #define PG8_WAIT_V(n) asm volatile("s_waitcnt vmcnt(" #n ")" ::: "memory")
; #define PG8_WAIT_L(n) asm volatile("s_waitcnt lgkmcnt(" #n ")" ::: "memory")
; #define PG8_BAR __builtin_amdgcn_s_barrier()
; #define PG8_SCHED __builtin_amdgcn_sched_barrier(0)
; template <class Epi, class Sched, bool ALIGN_EPI = false, bool SP2 = false>
; __device__ __forceinline__ void gemm_phase(PG8_LAS unsigned char* lds, const Gemm g, const Sched& S, const Epi& E, const int wave0) {
;     ...
;         for (int t = 0; t < nt; t += 2) {
;             const bool last = (t == nt - 2);
;     ...
;             PG8_LDB(B0, 1, 0); PG8_LDB(B1, 1, 1); PG8_SCHED; PG8_LDA(At, 1, 0); PG8_STAGE(PG8_SA(0, 1), a2 + hstepA, voffA);
;             PG8_WAIT_V(8); PG8_WAIT_L(0); PG8_BAR; PG8_MMA(0, 0, At, B0); PG8_MMA(0, 1, At, B1); PG8_BAR; PG8_SCHED;
;             PG8_LDA(At, 1, 1); PG8_STAGE(PG8_SB(1, 0), b3, voffB); PG8_STAGE(PG8_SB(1, 1), b3 + hstepB, voffB); PG8_STAGE(PG8_SA(1, 0), a3, voffA);
;             PG8_WAIT_V(8); PG8_WAIT_L(0); PG8_BAR; PG8_MMA(1, 0, At, B0); PG8_MMA(1, 1, At, B1); PG8_BAR; PG8_SCHED;
	s_add_i32 s31, 0, 0x18000
	s_add_i32 s33, 0, 0x1c000
	ds_read_b128 v[140:143], v254
	ds_read_b128 v[144:147], v254 offset:1024
	ds_read_b128 v[154:157], v254 offset:2048
	ds_read_b128 v[158:161], v254 offset:3072
	ds_read_b128 v[178:181], v255
	ds_read_b128 v[182:185], v255 offset:1024
	ds_read_b128 v[186:189], v255 offset:2048
	ds_read_b128 v[190:193], v255 offset:3072
	s_add_u32 s16, s16, 0x40000
	s_addc_u32 s17, s17, 0
	s_mov_b32 m0, s25
	ds_read_b128 v[194:197], v153 offset:32768
	ds_read_b128 v[208:211], v153 offset:33792
	ds_read_b128 v[212:215], v153 offset:34816
	ds_read_b128 v[216:219], v153 offset:35840
	ds_read_b128 v[220:223], v153 offset:36864
	ds_read_b128 v[224:227], v153 offset:37888
	ds_read_b128 v[228:231], v153 offset:38912
	ds_read_b128 v[232:235], v153 offset:39936
	global_load_lds_dwordx4 v134, s[16:17]
	s_mov_b32 m0, s26
	s_nop 0
	global_load_lds_dwordx4 v132, s[16:17]
	s_waitcnt vmcnt(8)
	s_waitcnt lgkmcnt(0)
	s_barrier
	s_setprio 1
	s_waitcnt lgkmcnt(0)
	v_mfma_f32_16x16x32_bf16 v[126:129], v[140:143], v[194:197], v[126:129]
	v_mfma_f32_16x16x32_bf16 v[122:125], v[154:157], v[194:197], v[122:125]
	v_mfma_f32_16x16x32_bf16 v[110:113], v[140:143], v[212:215], v[110:113]
	v_mfma_f32_16x16x32_bf16 v[106:109], v[154:157], v[212:215], v[106:109]
	v_mfma_f32_16x16x32_bf16 v[94:97], v[140:143], v[220:223], v[94:97]
	v_mfma_f32_16x16x32_bf16 v[90:93], v[154:157], v[220:223], v[90:93]
	v_mfma_f32_16x16x32_bf16 v[78:81], v[140:143], v[228:231], v[78:81]
	v_mfma_f32_16x16x32_bf16 v[74:77], v[154:157], v[228:231], v[74:77]
	s_setprio 0
	s_nop 1
	s_setprio 1
	v_mfma_f32_16x16x32_bf16 v[126:129], v[144:147], v[208:211], v[126:129]
	v_mfma_f32_16x16x32_bf16 v[122:125], v[158:161], v[208:211], v[122:125]
	v_mfma_f32_16x16x32_bf16 v[110:113], v[144:147], v[216:219], v[110:113]
	v_mfma_f32_16x16x32_bf16 v[106:109], v[158:161], v[216:219], v[106:109]
	v_mfma_f32_16x16x32_bf16 v[94:97], v[144:147], v[224:227], v[94:97]
	v_mfma_f32_16x16x32_bf16 v[90:93], v[158:161], v[224:227], v[90:93]
	v_mfma_f32_16x16x32_bf16 v[78:81], v[144:147], v[232:235], v[78:81]
	v_mfma_f32_16x16x32_bf16 v[74:77], v[158:161], v[232:235], v[74:77]
	s_setprio 0
	s_nop 1
	s_setprio 1
	v_mfma_f32_16x16x32_bf16 v[118:121], v[178:181], v[194:197], v[118:121]
	v_mfma_f32_16x16x32_bf16 v[114:117], v[186:189], v[194:197], v[114:117]
	v_mfma_f32_16x16x32_bf16 v[102:105], v[178:181], v[212:215], v[102:105]
	v_mfma_f32_16x16x32_bf16 v[98:101], v[186:189], v[212:215], v[98:101]
	v_mfma_f32_16x16x32_bf16 v[86:89], v[178:181], v[220:223], v[86:89]
	v_mfma_f32_16x16x32_bf16 v[82:85], v[186:189], v[220:223], v[82:85]
	v_mfma_f32_16x16x32_bf16 v[70:73], v[178:181], v[228:231], v[70:73]
	v_mfma_f32_16x16x32_bf16 v[66:69], v[186:189], v[228:231], v[66:69]
	s_setprio 0
	s_nop 1
	s_setprio 1
	v_mfma_f32_16x16x32_bf16 v[118:121], v[182:185], v[208:211], v[118:121]
	v_mfma_f32_16x16x32_bf16 v[114:117], v[190:193], v[208:211], v[114:117]
	v_mfma_f32_16x16x32_bf16 v[102:105], v[182:185], v[216:219], v[102:105]
	v_mfma_f32_16x16x32_bf16 v[98:101], v[190:193], v[216:219], v[98:101]
	v_mfma_f32_16x16x32_bf16 v[86:89], v[182:185], v[224:227], v[86:89]
	v_mfma_f32_16x16x32_bf16 v[82:85], v[190:193], v[224:227], v[82:85]
	v_mfma_f32_16x16x32_bf16 v[70:73], v[182:185], v[232:235], v[70:73]
	v_mfma_f32_16x16x32_bf16 v[66:69], v[190:193], v[232:235], v[66:69]
	s_setprio 0
	s_barrier
	s_add_i32 s16, s31, s22
	s_add_u32 s36, s2, 0x80
	s_addc_u32 s37, s3, 0
	s_mov_b32 m0, s16
	ds_read_b128 v[194:197], v153 offset:49152
	ds_read_b128 v[208:211], v153 offset:50176
	ds_read_b128 v[212:215], v153 offset:51200
	ds_read_b128 v[216:219], v153 offset:52224
	ds_read_b128 v[220:223], v153 offset:53248
	ds_read_b128 v[224:227], v153 offset:54272
	ds_read_b128 v[228:231], v153 offset:55296
	ds_read_b128 v[232:235], v153 offset:56320
	global_load_lds_dwordx4 v64, s[36:37]
	s_add_i32 m0, s16, 0x2000
	s_add_u32 s2, s2, 0x40080
	s_addc_u32 s3, s3, 0
	s_add_i32 s16, s33, s22
	global_load_lds_dwordx4 v130, s[36:37]
	s_mov_b32 m0, s16
	s_nop 0
	global_load_lds_dwordx4 v64, s[2:3]
	s_add_i32 m0, s16, 0x2000
	s_nop 0
	global_load_lds_dwordx4 v130, s[2:3]
	s_add_u32 s100, s100, 0x80
	s_addc_u32 s101, s101, 0
	s_mov_b32 m0, s27
	s_nop 0
	global_load_lds_dwordx4 v134, s[100:101]
	s_mov_b32 m0, s28
	s_nop 0
	global_load_lds_dwordx4 v132, s[100:101]
	s_waitcnt vmcnt(8)
	s_waitcnt lgkmcnt(0)
	s_barrier
	s_setprio 1
	s_waitcnt lgkmcnt(0)
	v_mfma_f32_16x16x32_bf16 v[60:63], v[140:143], v[194:197], v[60:63]
	v_mfma_f32_16x16x32_bf16 v[56:59], v[154:157], v[194:197], v[56:59]
	v_mfma_f32_16x16x32_bf16 v[44:47], v[140:143], v[212:215], v[44:47]
	v_mfma_f32_16x16x32_bf16 v[40:43], v[154:157], v[212:215], v[40:43]
	v_mfma_f32_16x16x32_bf16 v[28:31], v[140:143], v[220:223], v[28:31]
	v_mfma_f32_16x16x32_bf16 v[24:27], v[154:157], v[220:223], v[24:27]
	v_mfma_f32_16x16x32_bf16 v[12:15], v[140:143], v[228:231], v[12:15]
	v_mfma_f32_16x16x32_bf16 v[8:11], v[154:157], v[228:231], v[8:11]
	s_setprio 0
	s_nop 1
	s_setprio 1
	v_mfma_f32_16x16x32_bf16 v[60:63], v[144:147], v[208:211], v[60:63]
	v_mfma_f32_16x16x32_bf16 v[56:59], v[158:161], v[208:211], v[56:59]
	v_mfma_f32_16x16x32_bf16 v[44:47], v[144:147], v[216:219], v[44:47]
	v_mfma_f32_16x16x32_bf16 v[40:43], v[158:161], v[216:219], v[40:43]
	v_mfma_f32_16x16x32_bf16 v[28:31], v[144:147], v[224:227], v[28:31]
	v_mfma_f32_16x16x32_bf16 v[24:27], v[158:161], v[224:227], v[24:27]
	v_mfma_f32_16x16x32_bf16 v[12:15], v[144:147], v[232:235], v[12:15]
	v_mfma_f32_16x16x32_bf16 v[8:11], v[158:161], v[232:235], v[8:11]
	s_setprio 0
	s_nop 1
	s_setprio 1
	v_mfma_f32_16x16x32_bf16 v[52:55], v[178:181], v[194:197], v[52:55]
	v_mfma_f32_16x16x32_bf16 v[48:51], v[186:189], v[194:197], v[48:51]
	v_mfma_f32_16x16x32_bf16 v[36:39], v[178:181], v[212:215], v[36:39]
	v_mfma_f32_16x16x32_bf16 v[32:35], v[186:189], v[212:215], v[32:35]
	v_mfma_f32_16x16x32_bf16 v[20:23], v[178:181], v[220:223], v[20:23]
	v_mfma_f32_16x16x32_bf16 v[16:19], v[186:189], v[220:223], v[16:19]
	v_mfma_f32_16x16x32_bf16 v[4:7], v[178:181], v[228:231], v[4:7]
	v_mfma_f32_16x16x32_bf16 v[0:3], v[186:189], v[228:231], v[0:3]
	s_setprio 0
	s_nop 1
	s_setprio 1
	v_mfma_f32_16x16x32_bf16 v[52:55], v[182:185], v[208:211], v[52:55]
	v_mfma_f32_16x16x32_bf16 v[48:51], v[190:193], v[208:211], v[48:51]
	v_mfma_f32_16x16x32_bf16 v[36:39], v[182:185], v[216:219], v[36:39]
	v_mfma_f32_16x16x32_bf16 v[32:35], v[190:193], v[216:219], v[32:35]
	v_mfma_f32_16x16x32_bf16 v[20:23], v[182:185], v[224:227], v[20:23]
	v_mfma_f32_16x16x32_bf16 v[16:19], v[190:193], v[224:227], v[16:19]
	v_mfma_f32_16x16x32_bf16 v[4:7], v[182:185], v[232:235], v[4:7]
	v_mfma_f32_16x16x32_bf16 v[0:3], v[190:193], v[232:235], v[0:3]
	s_setprio 0
	s_barrier
	s_add_i32 s19, s19, 2
	s_add_u32 s0, s0, 0x100
	s_addc_u32 s1, s1, 0
	s_add_u32 s13, s13, 0x100
	s_addc_u32 s18, s18, 0
	s_cmp_gt_u32 s19, 13
	s_cbranch_scc0 .LBB0_1231
	s_mov_b64 s[36:37], 0x80
	s_and_b64 vcc, exec, s[6:7]
	s_cbranch_vccz .LBB0_1234
	s_barrier

; #define PG8_STAGE(bufoff, gbase, voff) do { _Pragma("unroll") for (int _i = 0; _i < 2; ++_i) \
;         __builtin_amdgcn_global_load_lds((const unsigned*)((const char*)(gbase) + (voff)[_i]), (PG8_LAS unsigned*)(lds + (bufoff) + ldsw + _i * 8192), 16, 0, 0); } while (0)
; #define PG8_LDA(dst, b, h) do { _Pragma("unroll") for (int m = 0; m < 4; ++m) _Pragma("unroll") for (int k = 0; k < 2; ++k) dst[m][k] = *(const PG8_LAS bf16x8*)(lds + PG8_SA(b, h) + aoff + m * 2048 + k * 1024); } while (0)
; #define PG8_LDB(dst, b, h) do { _Pragma("unroll") for (int n = 0; n < 2; ++n) _Pragma("unroll") for (int k = 0; k < 2; ++k) dst[n][k] = *(const PG8_LAS bf16x8*)(lds + PG8_SB(b, h) + boff + n * 2048 + k * 1024); } while (0)
; #define PG8_MMA(ai, bj, At, Bt) do { __builtin_amdgcn_s_setprio(1); _Pragma("unroll") for (int m = 0; m < 4; ++m) _Pragma("unroll") for (int n = 0; n < 2; ++n) _Pragma("unroll") for (int k = 0; k < 2; ++k) \
;         acc[ai][bj][m][n] = __builtin_amdgcn_mfma_f32_16x16x32_bf16(Bt[n][k], At[m][k], acc[ai][bj][m][n], 0, 0, 0); __builtin_amdgcn_s_setprio(0); } while (0)
; #define PG8_WAIT_V(n) asm volatile("s_waitcnt vmcnt(" #n ")" ::: "memory")
; #define PG8_BAR __builtin_amdgcn_s_barrier()
; template <class Epi, class Sched, bool ALIGN_EPI = false, bool SP2 = false>
; __device__ __forceinline__ void gemm_phase(PG8_LAS unsigned char* lds, const Gemm g, const Sched& S, const Epi& E, const int wave0) {
;     ...
;         for (int t = 0; t < nt; t += 2) {
;             const bool last = (t == nt - 2);
;             const char* a1 = cA + (size_t)(t + 1) * kstep;
;             const char* a2 = last ? nA : cA + (size_t)(t + 2) * kstep; const char* b2 = last ? nB : cB + (size_t)(t + 2) * kstep;
;             const char* a3 = a2 + kstep; const char* b3 = b2 + kstep;
;             if (last && has_next) S.a_ready(nxt);
;             if constexpr (SP2) {
;             PG8_LDB(B0, 0, 0); PG8_LDB(B1, 0, 1); PG8_SCHED; PG8_LDA(At, 0, 0); PG8_STAGE(PG8_SA(1, 1), a1 + hstepA, voffA);
;             PG8_WAIT_V(8); PG8_WAIT_L(0); PG8_BAR; PG8_MMA(0, 0, At, B0); PG8_MMA(0, 1, At, B1); PG8_BAR; PG8_SCHED;
;             PG8_LDA(At, 0, 1); PG8_STAGE(PG8_SB(0, 0), b2, voffB); PG8_STAGE(PG8_SB(0, 1), b2 + hstepB, voffB); PG8_STAGE(PG8_SA(0, 0), a2, voffA);
;             PG8_WAIT_V(8); PG8_WAIT_L(0); PG8_BAR; PG8_MMA(1, 0, At, B0); PG8_MMA(1, 1, At, B1); PG8_BAR; PG8_SCHED;
.LBB0_1341:
	s_add_u32 s16, s0, 0xfff80080
	s_addc_u32 s17, s1, -1
	s_add_i32 s40, 0, 0x10000
	s_cmp_eq_u32 s37, 28
	s_cselect_b32 s19, s11, s17
	s_cselect_b32 s18, s33, s16
	s_cselect_b32 s17, s9, s36
	s_cselect_b32 s16, s34, s35
	s_add_i32 s42, 0, 0x14000
	ds_read_b128 v[144:147], v252
	ds_read_b128 v[148:151], v252 offset:1024
	ds_read_b128 v[152:155], v252 offset:2048
	ds_read_b128 v[156:159], v252 offset:3072
	ds_read_b128 v[178:181], v253
	ds_read_b128 v[182:185], v253 offset:1024
	ds_read_b128 v[186:189], v253 offset:2048
	ds_read_b128 v[190:193], v253 offset:3072
	s_add_i32 m0, s23, 0xc000
	ds_read_b128 v[194:197], v143
	ds_read_b128 v[208:211], v143 offset:1024
	ds_read_b128 v[212:215], v143 offset:2048
	ds_read_b128 v[216:219], v143 offset:3072
	ds_read_b128 v[220:223], v143 offset:4096
	ds_read_b128 v[224:227], v143 offset:5120
	ds_read_b128 v[228:231], v143 offset:6144
	ds_read_b128 v[232:235], v143 offset:7168
	global_load_lds_dwordx4 v136, s[0:1]
	s_add_i32 m0, s23, 0xe000
	s_nop 0
	global_load_lds_dwordx4 v138, s[0:1]
	s_waitcnt vmcnt(8)
	s_waitcnt lgkmcnt(0)
	s_barrier
	s_setprio 1
	s_waitcnt lgkmcnt(0)
	v_mfma_f32_16x16x32_bf16 v[126:129], v[144:147], v[194:197], v[126:129]
	v_mfma_f32_16x16x32_bf16 v[122:125], v[152:155], v[194:197], v[122:125]
	v_mfma_f32_16x16x32_bf16 v[118:121], v[144:147], v[212:215], v[118:121]
	v_mfma_f32_16x16x32_bf16 v[114:117], v[152:155], v[212:215], v[114:117]
	v_mfma_f32_16x16x32_bf16 v[102:105], v[144:147], v[220:223], v[102:105]
	v_mfma_f32_16x16x32_bf16 v[98:101], v[152:155], v[220:223], v[98:101]
	v_mfma_f32_16x16x32_bf16 v[86:89], v[144:147], v[228:231], v[86:89]
	v_mfma_f32_16x16x32_bf16 v[82:85], v[152:155], v[228:231], v[82:85]
	s_setprio 0
	s_nop 1
	s_setprio 1
	v_mfma_f32_16x16x32_bf16 v[126:129], v[148:151], v[208:211], v[126:129]
	v_mfma_f32_16x16x32_bf16 v[122:125], v[156:159], v[208:211], v[122:125]
	v_mfma_f32_16x16x32_bf16 v[118:121], v[148:151], v[216:219], v[118:121]
	v_mfma_f32_16x16x32_bf16 v[114:117], v[156:159], v[216:219], v[114:117]
	v_mfma_f32_16x16x32_bf16 v[102:105], v[148:151], v[224:227], v[102:105]
	v_mfma_f32_16x16x32_bf16 v[98:101], v[156:159], v[224:227], v[98:101]
	v_mfma_f32_16x16x32_bf16 v[86:89], v[148:151], v[232:235], v[86:89]
	v_mfma_f32_16x16x32_bf16 v[82:85], v[156:159], v[232:235], v[82:85]
	s_setprio 0
	s_nop 1
	s_setprio 1
	v_mfma_f32_16x16x32_bf16 v[110:113], v[178:181], v[194:197], v[110:113]
	v_mfma_f32_16x16x32_bf16 v[106:109], v[186:189], v[194:197], v[106:109]
	v_mfma_f32_16x16x32_bf16 v[94:97], v[178:181], v[212:215], v[94:97]
	v_mfma_f32_16x16x32_bf16 v[90:93], v[186:189], v[212:215], v[90:93]
	v_mfma_f32_16x16x32_bf16 v[78:81], v[178:181], v[220:223], v[78:81]
	v_mfma_f32_16x16x32_bf16 v[74:77], v[186:189], v[220:223], v[74:77]
	v_mfma_f32_16x16x32_bf16 v[70:73], v[178:181], v[228:231], v[70:73]
	v_mfma_f32_16x16x32_bf16 v[66:69], v[186:189], v[228:231], v[66:69]
	s_setprio 0
	s_nop 1
	s_setprio 1
	v_mfma_f32_16x16x32_bf16 v[110:113], v[182:185], v[208:211], v[110:113]
	v_mfma_f32_16x16x32_bf16 v[106:109], v[190:193], v[208:211], v[106:109]
	v_mfma_f32_16x16x32_bf16 v[94:97], v[182:185], v[216:219], v[94:97]
	v_mfma_f32_16x16x32_bf16 v[90:93], v[190:193], v[216:219], v[90:93]
	v_mfma_f32_16x16x32_bf16 v[78:81], v[182:185], v[224:227], v[78:81]
	v_mfma_f32_16x16x32_bf16 v[74:77], v[190:193], v[224:227], v[74:77]
	v_mfma_f32_16x16x32_bf16 v[70:73], v[182:185], v[232:235], v[70:73]
	v_mfma_f32_16x16x32_bf16 v[66:69], v[190:193], v[232:235], v[66:69]
	s_setprio 0
	s_barrier
	s_add_i32 s40, s40, s22
	s_mov_b32 m0, s40
	ds_read_b128 v[194:197], v143 offset:16384
	ds_read_b128 v[208:211], v143 offset:17408
	ds_read_b128 v[212:215], v143 offset:18432
	ds_read_b128 v[216:219], v143 offset:19456
	ds_read_b128 v[220:223], v143 offset:20480
	ds_read_b128 v[224:227], v143 offset:21504
	ds_read_b128 v[228:231], v143 offset:22528
	ds_read_b128 v[232:235], v143 offset:23552
	global_load_lds_dwordx4 v64, s[16:17]
	s_add_i32 m0, s40, 0x2000
	s_add_u32 s40, s16, 0x80000
	s_addc_u32 s41, s17, 0
	s_add_i32 s42, s42, s22
	global_load_lds_dwordx4 v130, s[16:17]
	s_mov_b32 m0, s42
	s_mov_b64 s[100:101], s[18:19]
	global_load_lds_dwordx4 v64, s[40:41]
	s_add_i32 m0, s42, 0x2000
	s_nop 0
	global_load_lds_dwordx4 v130, s[40:41]
	s_mov_b32 m0, s23
	s_nop 0
	global_load_lds_dwordx4 v134, s[18:19]
	s_mov_b32 m0, s24
	s_nop 0
	global_load_lds_dwordx4 v132, s[18:19]
	s_waitcnt vmcnt(8)
	s_waitcnt lgkmcnt(0)
	s_barrier
; #define PG8_STAGE(bufoff, gbase, voff) do { _Pragma("unroll") for (int _i = 0; _i < 2; ++_i) \
;         __builtin_amdgcn_global_load_lds((const unsigned*)((const char*)(gbase) + (voff)[_i]), (PG8_LAS unsigned*)(lds + (bufoff) + ldsw + _i * 8192), 16, 0, 0); } while (0)
; #define PG8_LDA(dst, b, h) do { _Pragma("unroll") for (int m = 0; m < 4; ++m) _Pragma("unroll") for (int k = 0; k < 2; ++k) dst[m][k] = *(const PG8_LAS bf16x8*)(lds + PG8_SA(b, h) + aoff + m * 2048 + k * 1024); } while (0)
; #define PG8_LDB(dst, b, h) do { _Pragma("unroll") for (int n = 0; n < 2; ++n) _Pragma("unroll") for (int k = 0; k < 2; ++k) dst[n][k] = *(const PG8_LAS bf16x8*)(lds + PG8_SB(b, h) + boff + n * 2048 + k * 1024); } while (0)
; #define PG8_MMA(ai, bj, At, Bt) do { __builtin_amdgcn_s_setprio(1); _Pragma("unroll") for (int m = 0; m < 4; ++m) _Pragma("unroll") for (int n = 0; n < 2; ++n) _Pragma("unroll") for (int k = 0; k < 2; ++k) \
;         acc[ai][bj][m][n] = __builtin_amdgcn_mfma_f32_16x16x32_bf16(Bt[n][k], At[m][k], acc[ai][bj][m][n], 0, 0, 0); __builtin_amdgcn_s_setprio(0); } while (0)
; #define PG8_WAIT_V(n) asm volatile("s_waitcnt vmcnt(" #n ")" ::: "memory")
; #define PG8_WAIT_L(n) asm volatile("s_waitcnt lgkmcnt(" #n ")" ::: "memory")
; #define PG8_BAR __builtin_amdgcn_s_barrier()
; #define PG8_SCHED __builtin_amdgcn_sched_barrier(0)
; template <class Epi, class Sched, bool ALIGN_EPI = false, bool SP2 = false>
; __device__ __forceinline__ void gemm_phase(PG8_LAS unsigned char* lds, const Gemm g, const Sched& S, const Epi& E, const int wave0) {
;     ...
;             PG8_WAIT_V(8); PG8_WAIT_L(0); PG8_BAR; PG8_MMA(1, 0, At, B0); PG8_MMA(1, 1, At, B1); PG8_BAR; PG8_SCHED;
;             PG8_LDB(B0, 1, 0); PG8_LDB(B1, 1, 1); PG8_SCHED; PG8_LDA(At, 1, 0); PG8_STAGE(PG8_SA(0, 1), a2 + hstepA, voffA);
;             PG8_WAIT_V(8); PG8_WAIT_L(0); PG8_BAR; PG8_MMA(0, 0, At, B0); PG8_MMA(0, 1, At, B1); PG8_BAR; PG8_SCHED;
	s_setprio 1
	s_waitcnt lgkmcnt(0)
	v_mfma_f32_16x16x32_bf16 v[60:63], v[144:147], v[194:197], v[60:63]
	v_mfma_f32_16x16x32_bf16 v[56:59], v[152:155], v[194:197], v[56:59]
	v_mfma_f32_16x16x32_bf16 v[52:55], v[144:147], v[212:215], v[52:55]
	v_mfma_f32_16x16x32_bf16 v[48:51], v[152:155], v[212:215], v[48:51]
	v_mfma_f32_16x16x32_bf16 v[36:39], v[144:147], v[220:223], v[36:39]
	v_mfma_f32_16x16x32_bf16 v[32:35], v[152:155], v[220:223], v[32:35]
	v_mfma_f32_16x16x32_bf16 v[20:23], v[144:147], v[228:231], v[20:23]
	v_mfma_f32_16x16x32_bf16 v[16:19], v[152:155], v[228:231], v[16:19]
	s_setprio 0
	s_nop 1
	s_setprio 1
	v_mfma_f32_16x16x32_bf16 v[60:63], v[148:151], v[208:211], v[60:63]
	v_mfma_f32_16x16x32_bf16 v[56:59], v[156:159], v[208:211], v[56:59]
	v_mfma_f32_16x16x32_bf16 v[52:55], v[148:151], v[216:219], v[52:55]
	v_mfma_f32_16x16x32_bf16 v[48:51], v[156:159], v[216:219], v[48:51]
	v_mfma_f32_16x16x32_bf16 v[36:39], v[148:151], v[224:227], v[36:39]
	v_mfma_f32_16x16x32_bf16 v[32:35], v[156:159], v[224:227], v[32:35]
	v_mfma_f32_16x16x32_bf16 v[20:23], v[148:151], v[232:235], v[20:23]
	v_mfma_f32_16x16x32_bf16 v[16:19], v[156:159], v[232:235], v[16:19]
	s_setprio 0
	s_nop 1
	s_setprio 1
	v_mfma_f32_16x16x32_bf16 v[44:47], v[178:181], v[194:197], v[44:47]
	v_mfma_f32_16x16x32_bf16 v[40:43], v[186:189], v[194:197], v[40:43]
	v_mfma_f32_16x16x32_bf16 v[28:31], v[178:181], v[212:215], v[28:31]
	v_mfma_f32_16x16x32_bf16 v[24:27], v[186:189], v[212:215], v[24:27]
	v_mfma_f32_16x16x32_bf16 v[12:15], v[178:181], v[220:223], v[12:15]
	v_mfma_f32_16x16x32_bf16 v[8:11], v[186:189], v[220:223], v[8:11]
	v_mfma_f32_16x16x32_bf16 v[4:7], v[178:181], v[228:231], v[4:7]
	v_mfma_f32_16x16x32_bf16 v[0:3], v[186:189], v[228:231], v[0:3]
	s_setprio 0
	s_nop 1
	s_setprio 1
	v_mfma_f32_16x16x32_bf16 v[44:47], v[182:185], v[208:211], v[44:47]
	v_mfma_f32_16x16x32_bf16 v[40:43], v[190:193], v[208:211], v[40:43]
	v_mfma_f32_16x16x32_bf16 v[28:31], v[182:185], v[216:219], v[28:31]
	v_mfma_f32_16x16x32_bf16 v[24:27], v[190:193], v[216:219], v[24:27]
	v_mfma_f32_16x16x32_bf16 v[12:15], v[182:185], v[224:227], v[12:15]
	v_mfma_f32_16x16x32_bf16 v[8:11], v[190:193], v[224:227], v[8:11]
	v_mfma_f32_16x16x32_bf16 v[4:7], v[182:185], v[232:235], v[4:7]
	v_mfma_f32_16x16x32_bf16 v[0:3], v[190:193], v[232:235], v[0:3]
	s_setprio 0
	s_barrier
	s_add_i32 s40, 0, 0x18000
	s_add_i32 s41, 0, 0x1c000
	ds_read_b128 v[144:147], v254
	ds_read_b128 v[148:151], v254 offset:1024
	ds_read_b128 v[152:155], v254 offset:2048
	ds_read_b128 v[156:159], v254 offset:3072
	ds_read_b128 v[178:181], v255
	ds_read_b128 v[182:185], v255 offset:1024
	ds_read_b128 v[186:189], v255 offset:2048
	ds_read_b128 v[190:193], v255 offset:3072
	s_add_u32 s18, s18, 0x80000
	s_addc_u32 s19, s19, 0
	s_mov_b32 m0, s25
	ds_read_b128 v[194:197], v143 offset:32768
	ds_read_b128 v[208:211], v143 offset:33792
	ds_read_b128 v[212:215], v143 offset:34816
	ds_read_b128 v[216:219], v143 offset:35840
	ds_read_b128 v[220:223], v143 offset:36864
	ds_read_b128 v[224:227], v143 offset:37888
	ds_read_b128 v[228:231], v143 offset:38912
	ds_read_b128 v[232:235], v143 offset:39936
	global_load_lds_dwordx4 v134, s[18:19]
	s_mov_b32 m0, s26
	s_nop 0
	global_load_lds_dwordx4 v132, s[18:19]
	s_waitcnt vmcnt(8)
	s_waitcnt lgkmcnt(0)
	s_barrier
	s_setprio 1
	s_waitcnt lgkmcnt(0)
	v_mfma_f32_16x16x32_bf16 v[126:129], v[144:147], v[194:197], v[126:129]
	v_mfma_f32_16x16x32_bf16 v[122:125], v[152:155], v[194:197], v[122:125]
	v_mfma_f32_16x16x32_bf16 v[118:121], v[144:147], v[212:215], v[118:121]
	v_mfma_f32_16x16x32_bf16 v[114:117], v[152:155], v[212:215], v[114:117]
	v_mfma_f32_16x16x32_bf16 v[102:105], v[144:147], v[220:223], v[102:105]
	v_mfma_f32_16x16x32_bf16 v[98:101], v[152:155], v[220:223], v[98:101]
	v_mfma_f32_16x16x32_bf16 v[86:89], v[144:147], v[228:231], v[86:89]
	v_mfma_f32_16x16x32_bf16 v[82:85], v[152:155], v[228:231], v[82:85]
	s_setprio 0
	s_nop 1
	s_setprio 1
	v_mfma_f32_16x16x32_bf16 v[126:129], v[148:151], v[208:211], v[126:129]
	v_mfma_f32_16x16x32_bf16 v[122:125], v[156:159], v[208:211], v[122:125]
	v_mfma_f32_16x16x32_bf16 v[118:121], v[148:151], v[216:219], v[118:121]
	v_mfma_f32_16x16x32_bf16 v[114:117], v[156:159], v[216:219], v[114:117]
	v_mfma_f32_16x16x32_bf16 v[102:105], v[148:151], v[224:227], v[102:105]
	v_mfma_f32_16x16x32_bf16 v[98:101], v[156:159], v[224:227], v[98:101]
	v_mfma_f32_16x16x32_bf16 v[86:89], v[148:151], v[232:235], v[86:89]
	v_mfma_f32_16x16x32_bf16 v[82:85], v[156:159], v[232:235], v[82:85]
	s_setprio 0
	s_nop 1
	s_setprio 1
	v_mfma_f32_16x16x32_bf16 v[110:113], v[178:181], v[194:197], v[110:113]
	v_mfma_f32_16x16x32_bf16 v[106:109], v[186:189], v[194:197], v[106:109]
	v_mfma_f32_16x16x32_bf16 v[94:97], v[178:181], v[212:215], v[94:97]
	v_mfma_f32_16x16x32_bf16 v[90:93], v[186:189], v[212:215], v[90:93]
	v_mfma_f32_16x16x32_bf16 v[78:81], v[178:181], v[220:223], v[78:81]
	v_mfma_f32_16x16x32_bf16 v[74:77], v[186:189], v[220:223], v[74:77]
	v_mfma_f32_16x16x32_bf16 v[70:73], v[178:181], v[228:231], v[70:73]
	v_mfma_f32_16x16x32_bf16 v[66:69], v[186:189], v[228:231], v[66:69]
	s_setprio 0
	s_nop 1
	s_setprio 1
	v_mfma_f32_16x16x32_bf16 v[110:113], v[182:185], v[208:211], v[110:113]
	v_mfma_f32_16x16x32_bf16 v[106:109], v[190:193], v[208:211], v[106:109]
	v_mfma_f32_16x16x32_bf16 v[94:97], v[182:185], v[216:219], v[94:97]
	v_mfma_f32_16x16x32_bf16 v[90:93], v[190:193], v[216:219], v[90:93]
	v_mfma_f32_16x16x32_bf16 v[78:81], v[182:185], v[224:227], v[78:81]
	v_mfma_f32_16x16x32_bf16 v[74:77], v[190:193], v[224:227], v[74:77]
	v_mfma_f32_16x16x32_bf16 v[70:73], v[182:185], v[232:235], v[70:73]
	v_mfma_f32_16x16x32_bf16 v[66:69], v[190:193], v[232:235], v[66:69]
	s_setprio 0
	s_barrier
; #define PG8_STAGE(bufoff, gbase, voff) do { _Pragma("unroll") for (int _i = 0; _i < 2; ++_i) \
;         __builtin_amdgcn_global_load_lds((const unsigned*)((const char*)(gbase) + (voff)[_i]), (PG8_LAS unsigned*)(lds + (bufoff) + ldsw + _i * 8192), 16, 0, 0); } while (0)
; #define PG8_LDA(dst, b, h) do { _Pragma("unroll") for (int m = 0; m < 4; ++m) _Pragma("unroll") for (int k = 0; k < 2; ++k) dst[m][k] = *(const PG8_LAS bf16x8*)(lds + PG8_SA(b, h) + aoff + m * 2048 + k * 1024); } while (0)
; #define PG8_MMA(ai, bj, At, Bt) do { __builtin_amdgcn_s_setprio(1); _Pragma("unroll") for (int m = 0; m < 4; ++m) _Pragma("unroll") for (int n = 0; n < 2; ++n) _Pragma("unroll") for (int k = 0; k < 2; ++k) \
;         acc[ai][bj][m][n] = __builtin_amdgcn_mfma_f32_16x16x32_bf16(Bt[n][k], At[m][k], acc[ai][bj][m][n], 0, 0, 0); __builtin_amdgcn_s_setprio(0); } while (0)
; #define PG8_WAIT_V(n) asm volatile("s_waitcnt vmcnt(" #n ")" ::: "memory")
; #define PG8_WAIT_L(n) asm volatile("s_waitcnt lgkmcnt(" #n ")" ::: "memory")
; #define PG8_BAR __builtin_amdgcn_s_barrier()
; #define PG8_SCHED __builtin_amdgcn_sched_barrier(0)
; template <class Epi, class Sched, bool ALIGN_EPI = false, bool SP2 = false>
; __device__ __forceinline__ void gemm_phase(PG8_LAS unsigned char* lds, const Gemm g, const Sched& S, const Epi& E, const int wave0) {
;     ...
;         for (int t = 0; t < nt; t += 2) {
;             const bool last = (t == nt - 2);
;             const char* a1 = cA + (size_t)(t + 1) * kstep;
;             const char* a2 = last ? nA : cA + (size_t)(t + 2) * kstep; const char* b2 = last ? nB : cB + (size_t)(t + 2) * kstep;
;     ...
;             PG8_LDA(At, 1, 1); PG8_STAGE(PG8_SB(1, 0), b3, voffB); PG8_STAGE(PG8_SB(1, 1), b3 + hstepB, voffB); PG8_STAGE(PG8_SA(1, 0), a3, voffA);
;             PG8_WAIT_V(8); PG8_WAIT_L(0); PG8_BAR; PG8_MMA(1, 0, At, B0); PG8_MMA(1, 1, At, B1); PG8_BAR; PG8_SCHED;
	s_add_i32 s18, s40, s22
	s_add_u32 s44, s16, 0x80
	s_addc_u32 s45, s17, 0
	s_mov_b32 m0, s18
	ds_read_b128 v[194:197], v143 offset:49152
	ds_read_b128 v[208:211], v143 offset:50176
	ds_read_b128 v[212:215], v143 offset:51200
	ds_read_b128 v[216:219], v143 offset:52224
	ds_read_b128 v[220:223], v143 offset:53248
	ds_read_b128 v[224:227], v143 offset:54272
	ds_read_b128 v[228:231], v143 offset:55296
	ds_read_b128 v[232:235], v143 offset:56320
	global_load_lds_dwordx4 v64, s[44:45]
	s_add_i32 m0, s18, 0x2000
	s_add_u32 s16, s16, 0x80080
	s_addc_u32 s17, s17, 0
	s_add_i32 s18, s41, s22
	global_load_lds_dwordx4 v130, s[44:45]
	s_mov_b32 m0, s18
	s_nop 0
	global_load_lds_dwordx4 v64, s[16:17]
	s_add_i32 m0, s18, 0x2000
	s_nop 0
	global_load_lds_dwordx4 v130, s[16:17]
	s_add_u32 s100, s100, 0x80
	s_addc_u32 s101, s101, 0
	s_mov_b32 m0, s27
	s_nop 0
	global_load_lds_dwordx4 v134, s[100:101]
	s_mov_b32 m0, s28
	s_nop 0
	global_load_lds_dwordx4 v132, s[100:101]
	s_waitcnt vmcnt(8)
	s_waitcnt lgkmcnt(0)
	s_barrier
	s_setprio 1
	s_waitcnt lgkmcnt(0)
	v_mfma_f32_16x16x32_bf16 v[60:63], v[144:147], v[194:197], v[60:63]
	v_mfma_f32_16x16x32_bf16 v[56:59], v[152:155], v[194:197], v[56:59]
	v_mfma_f32_16x16x32_bf16 v[52:55], v[144:147], v[212:215], v[52:55]
	v_mfma_f32_16x16x32_bf16 v[48:51], v[152:155], v[212:215], v[48:51]
	v_mfma_f32_16x16x32_bf16 v[36:39], v[144:147], v[220:223], v[36:39]
	v_mfma_f32_16x16x32_bf16 v[32:35], v[152:155], v[220:223], v[32:35]
	v_mfma_f32_16x16x32_bf16 v[20:23], v[144:147], v[228:231], v[20:23]
	v_mfma_f32_16x16x32_bf16 v[16:19], v[152:155], v[228:231], v[16:19]
	s_setprio 0
	s_nop 1
	s_setprio 1
	v_mfma_f32_16x16x32_bf16 v[60:63], v[148:151], v[208:211], v[60:63]
	v_mfma_f32_16x16x32_bf16 v[56:59], v[156:159], v[208:211], v[56:59]
	v_mfma_f32_16x16x32_bf16 v[52:55], v[148:151], v[216:219], v[52:55]
	v_mfma_f32_16x16x32_bf16 v[48:51], v[156:159], v[216:219], v[48:51]
	v_mfma_f32_16x16x32_bf16 v[36:39], v[148:151], v[224:227], v[36:39]
	v_mfma_f32_16x16x32_bf16 v[32:35], v[156:159], v[224:227], v[32:35]
	v_mfma_f32_16x16x32_bf16 v[20:23], v[148:151], v[232:235], v[20:23]
	v_mfma_f32_16x16x32_bf16 v[16:19], v[156:159], v[232:235], v[16:19]
	s_setprio 0
	s_nop 1
	s_setprio 1
	v_mfma_f32_16x16x32_bf16 v[44:47], v[178:181], v[194:197], v[44:47]
	v_mfma_f32_16x16x32_bf16 v[40:43], v[186:189], v[194:197], v[40:43]
	v_mfma_f32_16x16x32_bf16 v[28:31], v[178:181], v[212:215], v[28:31]
	v_mfma_f32_16x16x32_bf16 v[24:27], v[186:189], v[212:215], v[24:27]
	v_mfma_f32_16x16x32_bf16 v[12:15], v[178:181], v[220:223], v[12:15]
	v_mfma_f32_16x16x32_bf16 v[8:11], v[186:189], v[220:223], v[8:11]
	v_mfma_f32_16x16x32_bf16 v[4:7], v[178:181], v[228:231], v[4:7]
	v_mfma_f32_16x16x32_bf16 v[0:3], v[186:189], v[228:231], v[0:3]
	s_setprio 0
	s_nop 1
	s_setprio 1
	v_mfma_f32_16x16x32_bf16 v[44:47], v[182:185], v[208:211], v[44:47]
	v_mfma_f32_16x16x32_bf16 v[40:43], v[190:193], v[208:211], v[40:43]
	v_mfma_f32_16x16x32_bf16 v[28:31], v[182:185], v[216:219], v[28:31]
	v_mfma_f32_16x16x32_bf16 v[24:27], v[190:193], v[216:219], v[24:27]
	v_mfma_f32_16x16x32_bf16 v[12:15], v[182:185], v[224:227], v[12:15]
	v_mfma_f32_16x16x32_bf16 v[8:11], v[190:193], v[224:227], v[8:11]
	v_mfma_f32_16x16x32_bf16 v[4:7], v[182:185], v[232:235], v[4:7]
	v_mfma_f32_16x16x32_bf16 v[0:3], v[190:193], v[232:235], v[0:3]
	s_setprio 0
	s_barrier
	s_add_i32 s37, s37, 2
	s_add_u32 s0, s0, 0x100
	s_addc_u32 s1, s1, 0
	s_add_u32 s35, s35, 0x100
	s_addc_u32 s36, s36, 0
	s_cmp_gt_u32 s37, 29
	s_cbranch_scc0 .LBB0_1341
	s_mov_b64 s[44:45], 0x80
	s_and_b64 vcc, exec, s[6:7]
	s_mov_b64 s[34:35], 0x45000
	s_cbranch_vccz .LBB0_1344
	s_barrier

; #define PG8_STAGE(bufoff, gbase, voff) do { _Pragma("unroll") for (int _i = 0; _i < 2; ++_i) \
;         __builtin_amdgcn_global_load_lds((const unsigned*)((const char*)(gbase) + (voff)[_i]), (PG8_LAS unsigned*)(lds + (bufoff) + ldsw + _i * 8192), 16, 0, 0); } while (0)
; #define PG8_LDA(dst, b, h) do { _Pragma("unroll") for (int m = 0; m < 4; ++m) _Pragma("unroll") for (int k = 0; k < 2; ++k) dst[m][k] = *(const PG8_LAS bf16x8*)(lds + PG8_SA(b, h) + aoff + m * 2048 + k * 1024); } while (0)
; #define PG8_LDB(dst, b, h) do { _Pragma("unroll") for (int n = 0; n < 2; ++n) _Pragma("unroll") for (int k = 0; k < 2; ++k) dst[n][k] = *(const PG8_LAS bf16x8*)(lds + PG8_SB(b, h) + boff + n * 2048 + k * 1024); } while (0)
; #define PG8_MMA(ai, bj, At, Bt) do { __builtin_amdgcn_s_setprio(1); _Pragma("unroll") for (int m = 0; m < 4; ++m) _Pragma("unroll") for (int n = 0; n < 2; ++n) _Pragma("unroll") for (int k = 0; k < 2; ++k) \
;         acc[ai][bj][m][n] = __builtin_amdgcn_mfma_f32_16x16x32_bf16(Bt[n][k], At[m][k], acc[ai][bj][m][n], 0, 0, 0); __builtin_amdgcn_s_setprio(0); } while (0)
; #define PG8_WAIT_V(n) asm volatile("s_waitcnt vmcnt(" #n ")" ::: "memory")
; #define PG8_BAR __builtin_amdgcn_s_barrier()
; template <class Epi, class Sched, bool ALIGN_EPI = false, bool SP2 = false>
; __device__ __forceinline__ void gemm_phase(PG8_LAS unsigned char* lds, const Gemm g, const Sched& S, const Epi& E, const int wave0) {
;     ...
;         for (int t = 0; t < nt; t += 2) {
;             const bool last = (t == nt - 2);
;             const char* a1 = cA + (size_t)(t + 1) * kstep;
;             const char* a2 = last ? nA : cA + (size_t)(t + 2) * kstep; const char* b2 = last ? nB : cB + (size_t)(t + 2) * kstep;
;             const char* a3 = a2 + kstep; const char* b3 = b2 + kstep;
;             if (last && has_next) S.a_ready(nxt);
;             if constexpr (SP2) {
;             PG8_LDB(B0, 0, 0); PG8_LDB(B1, 0, 1); PG8_SCHED; PG8_LDA(At, 0, 0); PG8_STAGE(PG8_SA(1, 1), a1 + hstepA, voffA);
;             PG8_WAIT_V(8); PG8_WAIT_L(0); PG8_BAR; PG8_MMA(0, 0, At, B0); PG8_MMA(0, 1, At, B1); PG8_BAR; PG8_SCHED;
;             PG8_LDA(At, 0, 1); PG8_STAGE(PG8_SB(0, 0), b2, voffB); PG8_STAGE(PG8_SB(0, 1), b2 + hstepB, voffB); PG8_STAGE(PG8_SA(0, 0), a2, voffA);
;             PG8_WAIT_V(8); PG8_WAIT_L(0); PG8_BAR; PG8_MMA(1, 0, At, B0); PG8_MMA(1, 1, At, B1); PG8_BAR; PG8_SCHED;
.LBB0_1360:
	s_add_u32 s16, s0, 0xfff80080
	s_addc_u32 s17, s1, -1
	s_add_i32 s42, 0, 0x10000
	s_cmp_eq_u32 s41, 12
	s_cselect_b32 s19, s5, s17
	s_cselect_b32 s18, s4, s16
	s_cselect_b32 s17, s11, s27
	s_cselect_b32 s16, s13, s15
	s_add_i32 s44, 0, 0x14000
	ds_read_b128 v[144:147], v252
	ds_read_b128 v[148:151], v252 offset:1024
	ds_read_b128 v[152:155], v252 offset:2048
	ds_read_b128 v[156:159], v252 offset:3072
	ds_read_b128 v[178:181], v253
	ds_read_b128 v[182:185], v253 offset:1024
	ds_read_b128 v[186:189], v253 offset:2048
	ds_read_b128 v[190:193], v253 offset:3072
	s_add_i32 m0, s23, 0xc000
	ds_read_b128 v[194:197], v143
	ds_read_b128 v[208:211], v143 offset:1024
	ds_read_b128 v[212:215], v143 offset:2048
	ds_read_b128 v[216:219], v143 offset:3072
	ds_read_b128 v[220:223], v143 offset:4096
	ds_read_b128 v[224:227], v143 offset:5120
	ds_read_b128 v[228:231], v143 offset:6144
	ds_read_b128 v[232:235], v143 offset:7168
	global_load_lds_dwordx4 v136, s[0:1]
	s_add_i32 m0, s23, 0xe000
	s_nop 0
	global_load_lds_dwordx4 v138, s[0:1]
	s_waitcnt vmcnt(8)
	s_waitcnt lgkmcnt(0)
	s_barrier
	s_setprio 1
	s_waitcnt lgkmcnt(0)
	v_mfma_f32_16x16x32_bf16 v[126:129], v[144:147], v[194:197], v[126:129]
	v_mfma_f32_16x16x32_bf16 v[122:125], v[152:155], v[194:197], v[122:125]
	v_mfma_f32_16x16x32_bf16 v[118:121], v[144:147], v[212:215], v[118:121]
	v_mfma_f32_16x16x32_bf16 v[114:117], v[152:155], v[212:215], v[114:117]
	v_mfma_f32_16x16x32_bf16 v[102:105], v[144:147], v[220:223], v[102:105]
	v_mfma_f32_16x16x32_bf16 v[98:101], v[152:155], v[220:223], v[98:101]
	v_mfma_f32_16x16x32_bf16 v[86:89], v[144:147], v[228:231], v[86:89]
	v_mfma_f32_16x16x32_bf16 v[82:85], v[152:155], v[228:231], v[82:85]
	s_setprio 0
	s_nop 1
	s_setprio 1
	v_mfma_f32_16x16x32_bf16 v[126:129], v[148:151], v[208:211], v[126:129]
	v_mfma_f32_16x16x32_bf16 v[122:125], v[156:159], v[208:211], v[122:125]
	v_mfma_f32_16x16x32_bf16 v[118:121], v[148:151], v[216:219], v[118:121]
	v_mfma_f32_16x16x32_bf16 v[114:117], v[156:159], v[216:219], v[114:117]
	v_mfma_f32_16x16x32_bf16 v[102:105], v[148:151], v[224:227], v[102:105]
	v_mfma_f32_16x16x32_bf16 v[98:101], v[156:159], v[224:227], v[98:101]
	v_mfma_f32_16x16x32_bf16 v[86:89], v[148:151], v[232:235], v[86:89]
	v_mfma_f32_16x16x32_bf16 v[82:85], v[156:159], v[232:235], v[82:85]
	s_setprio 0
	s_nop 1
	s_setprio 1
	v_mfma_f32_16x16x32_bf16 v[110:113], v[178:181], v[194:197], v[110:113]
	v_mfma_f32_16x16x32_bf16 v[106:109], v[186:189], v[194:197], v[106:109]
	v_mfma_f32_16x16x32_bf16 v[94:97], v[178:181], v[212:215], v[94:97]
	v_mfma_f32_16x16x32_bf16 v[90:93], v[186:189], v[212:215], v[90:93]
	v_mfma_f32_16x16x32_bf16 v[78:81], v[178:181], v[220:223], v[78:81]
	v_mfma_f32_16x16x32_bf16 v[74:77], v[186:189], v[220:223], v[74:77]
	v_mfma_f32_16x16x32_bf16 v[70:73], v[178:181], v[228:231], v[70:73]
	v_mfma_f32_16x16x32_bf16 v[66:69], v[186:189], v[228:231], v[66:69]
	s_setprio 0
	s_nop 1
	s_setprio 1
	v_mfma_f32_16x16x32_bf16 v[110:113], v[182:185], v[208:211], v[110:113]
	v_mfma_f32_16x16x32_bf16 v[106:109], v[190:193], v[208:211], v[106:109]
	v_mfma_f32_16x16x32_bf16 v[94:97], v[182:185], v[216:219], v[94:97]
	v_mfma_f32_16x16x32_bf16 v[90:93], v[190:193], v[216:219], v[90:93]
	v_mfma_f32_16x16x32_bf16 v[78:81], v[182:185], v[224:227], v[78:81]
	v_mfma_f32_16x16x32_bf16 v[74:77], v[190:193], v[224:227], v[74:77]
	v_mfma_f32_16x16x32_bf16 v[70:73], v[182:185], v[232:235], v[70:73]
	v_mfma_f32_16x16x32_bf16 v[66:69], v[190:193], v[232:235], v[66:69]
	s_setprio 0
	s_barrier
	s_add_i32 s42, s42, s22
	s_mov_b32 m0, s42
	ds_read_b128 v[194:197], v143 offset:16384
	ds_read_b128 v[208:211], v143 offset:17408
	ds_read_b128 v[212:215], v143 offset:18432
	ds_read_b128 v[216:219], v143 offset:19456
	ds_read_b128 v[220:223], v143 offset:20480
	ds_read_b128 v[224:227], v143 offset:21504
	ds_read_b128 v[228:231], v143 offset:22528
	ds_read_b128 v[232:235], v143 offset:23552
	global_load_lds_dwordx4 v64, s[16:17]
	s_add_i32 m0, s42, 0x2000
	s_add_u32 s42, s16, 0x80000
	s_addc_u32 s43, s17, 0
	s_add_i32 s44, s44, s22
	global_load_lds_dwordx4 v130, s[16:17]
	s_mov_b32 m0, s44
	s_mov_b64 s[100:101], s[18:19]
	global_load_lds_dwordx4 v64, s[42:43]
	s_add_i32 m0, s44, 0x2000
	s_nop 0
	global_load_lds_dwordx4 v130, s[42:43]
	s_mov_b32 m0, s23
	s_nop 0
	global_load_lds_dwordx4 v134, s[18:19]
	s_mov_b32 m0, s24
	s_nop 0
	global_load_lds_dwordx4 v132, s[18:19]
	s_waitcnt vmcnt(8)
	s_waitcnt lgkmcnt(0)
	s_barrier
; #define PG8_STAGE(bufoff, gbase, voff) do { _Pragma("unroll") for (int _i = 0; _i < 2; ++_i) \
;         __builtin_amdgcn_global_load_lds((const unsigned*)((const char*)(gbase) + (voff)[_i]), (PG8_LAS unsigned*)(lds + (bufoff) + ldsw + _i * 8192), 16, 0, 0); } while (0)
; #define PG8_LDA(dst, b, h) do { _Pragma("unroll") for (int m = 0; m < 4; ++m) _Pragma("unroll") for (int k = 0; k < 2; ++k) dst[m][k] = *(const PG8_LAS bf16x8*)(lds + PG8_SA(b, h) + aoff + m * 2048 + k * 1024); } while (0)
; #define PG8_LDB(dst, b, h) do { _Pragma("unroll") for (int n = 0; n < 2; ++n) _Pragma("unroll") for (int k = 0; k < 2; ++k) dst[n][k] = *(const PG8_LAS bf16x8*)(lds + PG8_SB(b, h) + boff + n * 2048 + k * 1024); } while (0)
; #define PG8_MMA(ai, bj, At, Bt) do { __builtin_amdgcn_s_setprio(1); _Pragma("unroll") for (int m = 0; m < 4; ++m) _Pragma("unroll") for (int n = 0; n < 2; ++n) _Pragma("unroll") for (int k = 0; k < 2; ++k) \
;         acc[ai][bj][m][n] = __builtin_amdgcn_mfma_f32_16x16x32_bf16(Bt[n][k], At[m][k], acc[ai][bj][m][n], 0, 0, 0); __builtin_amdgcn_s_setprio(0); } while (0)
; #define PG8_WAIT_V(n) asm volatile("s_waitcnt vmcnt(" #n ")" ::: "memory")
; #define PG8_WAIT_L(n) asm volatile("s_waitcnt lgkmcnt(" #n ")" ::: "memory")
; #define PG8_BAR __builtin_amdgcn_s_barrier()
; #define PG8_SCHED __builtin_amdgcn_sched_barrier(0)
; template <class Epi, class Sched, bool ALIGN_EPI = false, bool SP2 = false>
; __device__ __forceinline__ void gemm_phase(PG8_LAS unsigned char* lds, const Gemm g, const Sched& S, const Epi& E, const int wave0) {
;     ...
;             PG8_WAIT_V(8); PG8_WAIT_L(0); PG8_BAR; PG8_MMA(1, 0, At, B0); PG8_MMA(1, 1, At, B1); PG8_BAR; PG8_SCHED;
;             PG8_LDB(B0, 1, 0); PG8_LDB(B1, 1, 1); PG8_SCHED; PG8_LDA(At, 1, 0); PG8_STAGE(PG8_SA(0, 1), a2 + hstepA, voffA);
;             PG8_WAIT_V(8); PG8_WAIT_L(0); PG8_BAR; PG8_MMA(0, 0, At, B0); PG8_MMA(0, 1, At, B1); PG8_BAR; PG8_SCHED;
	s_setprio 1
	s_waitcnt lgkmcnt(0)
	v_mfma_f32_16x16x32_bf16 v[60:63], v[144:147], v[194:197], v[60:63]
	v_mfma_f32_16x16x32_bf16 v[56:59], v[152:155], v[194:197], v[56:59]
	v_mfma_f32_16x16x32_bf16 v[52:55], v[144:147], v[212:215], v[52:55]
	v_mfma_f32_16x16x32_bf16 v[48:51], v[152:155], v[212:215], v[48:51]
	v_mfma_f32_16x16x32_bf16 v[36:39], v[144:147], v[220:223], v[36:39]
	v_mfma_f32_16x16x32_bf16 v[32:35], v[152:155], v[220:223], v[32:35]
	v_mfma_f32_16x16x32_bf16 v[20:23], v[144:147], v[228:231], v[20:23]
	v_mfma_f32_16x16x32_bf16 v[16:19], v[152:155], v[228:231], v[16:19]
	s_setprio 0
	s_nop 1
	s_setprio 1
	v_mfma_f32_16x16x32_bf16 v[60:63], v[148:151], v[208:211], v[60:63]
	v_mfma_f32_16x16x32_bf16 v[56:59], v[156:159], v[208:211], v[56:59]
	v_mfma_f32_16x16x32_bf16 v[52:55], v[148:151], v[216:219], v[52:55]
	v_mfma_f32_16x16x32_bf16 v[48:51], v[156:159], v[216:219], v[48:51]
	v_mfma_f32_16x16x32_bf16 v[36:39], v[148:151], v[224:227], v[36:39]
	v_mfma_f32_16x16x32_bf16 v[32:35], v[156:159], v[224:227], v[32:35]
	v_mfma_f32_16x16x32_bf16 v[20:23], v[148:151], v[232:235], v[20:23]
	v_mfma_f32_16x16x32_bf16 v[16:19], v[156:159], v[232:235], v[16:19]
	s_setprio 0
	s_nop 1
	s_setprio 1
	v_mfma_f32_16x16x32_bf16 v[44:47], v[178:181], v[194:197], v[44:47]
	v_mfma_f32_16x16x32_bf16 v[40:43], v[186:189], v[194:197], v[40:43]
	v_mfma_f32_16x16x32_bf16 v[28:31], v[178:181], v[212:215], v[28:31]
	v_mfma_f32_16x16x32_bf16 v[24:27], v[186:189], v[212:215], v[24:27]
	v_mfma_f32_16x16x32_bf16 v[12:15], v[178:181], v[220:223], v[12:15]
	v_mfma_f32_16x16x32_bf16 v[8:11], v[186:189], v[220:223], v[8:11]
	v_mfma_f32_16x16x32_bf16 v[4:7], v[178:181], v[228:231], v[4:7]
	v_mfma_f32_16x16x32_bf16 v[0:3], v[186:189], v[228:231], v[0:3]
	s_setprio 0
	s_nop 1
	s_setprio 1
	v_mfma_f32_16x16x32_bf16 v[44:47], v[182:185], v[208:211], v[44:47]
	v_mfma_f32_16x16x32_bf16 v[40:43], v[190:193], v[208:211], v[40:43]
	v_mfma_f32_16x16x32_bf16 v[28:31], v[182:185], v[216:219], v[28:31]
	v_mfma_f32_16x16x32_bf16 v[24:27], v[190:193], v[216:219], v[24:27]
	v_mfma_f32_16x16x32_bf16 v[12:15], v[182:185], v[224:227], v[12:15]
	v_mfma_f32_16x16x32_bf16 v[8:11], v[190:193], v[224:227], v[8:11]
	v_mfma_f32_16x16x32_bf16 v[4:7], v[182:185], v[232:235], v[4:7]
	v_mfma_f32_16x16x32_bf16 v[0:3], v[190:193], v[232:235], v[0:3]
	s_setprio 0
	s_barrier
	s_add_i32 s42, 0, 0x18000
	s_add_i32 s43, 0, 0x1c000
	ds_read_b128 v[144:147], v254
	ds_read_b128 v[148:151], v254 offset:1024
	ds_read_b128 v[152:155], v254 offset:2048
	ds_read_b128 v[156:159], v254 offset:3072
	ds_read_b128 v[178:181], v255
	ds_read_b128 v[182:185], v255 offset:1024
	ds_read_b128 v[186:189], v255 offset:2048
	ds_read_b128 v[190:193], v255 offset:3072
	s_add_u32 s18, s18, 0x80000
	s_addc_u32 s19, s19, 0
	s_mov_b32 m0, s25
	ds_read_b128 v[194:197], v143 offset:32768
	ds_read_b128 v[208:211], v143 offset:33792
	ds_read_b128 v[212:215], v143 offset:34816
	ds_read_b128 v[216:219], v143 offset:35840
	ds_read_b128 v[220:223], v143 offset:36864
	ds_read_b128 v[224:227], v143 offset:37888
	ds_read_b128 v[228:231], v143 offset:38912
	ds_read_b128 v[232:235], v143 offset:39936
	global_load_lds_dwordx4 v134, s[18:19]
	s_mov_b32 m0, s33
	s_nop 0
	global_load_lds_dwordx4 v132, s[18:19]
	s_waitcnt vmcnt(8)
	s_waitcnt lgkmcnt(0)
	s_barrier
	s_setprio 1
	s_waitcnt lgkmcnt(0)
	v_mfma_f32_16x16x32_bf16 v[126:129], v[144:147], v[194:197], v[126:129]
	v_mfma_f32_16x16x32_bf16 v[122:125], v[152:155], v[194:197], v[122:125]
	v_mfma_f32_16x16x32_bf16 v[118:121], v[144:147], v[212:215], v[118:121]
	v_mfma_f32_16x16x32_bf16 v[114:117], v[152:155], v[212:215], v[114:117]
	v_mfma_f32_16x16x32_bf16 v[102:105], v[144:147], v[220:223], v[102:105]
	v_mfma_f32_16x16x32_bf16 v[98:101], v[152:155], v[220:223], v[98:101]
	v_mfma_f32_16x16x32_bf16 v[86:89], v[144:147], v[228:231], v[86:89]
	v_mfma_f32_16x16x32_bf16 v[82:85], v[152:155], v[228:231], v[82:85]
	s_setprio 0
	s_nop 1
	s_setprio 1
	v_mfma_f32_16x16x32_bf16 v[126:129], v[148:151], v[208:211], v[126:129]
	v_mfma_f32_16x16x32_bf16 v[122:125], v[156:159], v[208:211], v[122:125]
	v_mfma_f32_16x16x32_bf16 v[118:121], v[148:151], v[216:219], v[118:121]
	v_mfma_f32_16x16x32_bf16 v[114:117], v[156:159], v[216:219], v[114:117]
	v_mfma_f32_16x16x32_bf16 v[102:105], v[148:151], v[224:227], v[102:105]
	v_mfma_f32_16x16x32_bf16 v[98:101], v[156:159], v[224:227], v[98:101]
	v_mfma_f32_16x16x32_bf16 v[86:89], v[148:151], v[232:235], v[86:89]
	v_mfma_f32_16x16x32_bf16 v[82:85], v[156:159], v[232:235], v[82:85]
	s_setprio 0
	s_nop 1
	s_setprio 1
	v_mfma_f32_16x16x32_bf16 v[110:113], v[178:181], v[194:197], v[110:113]
	v_mfma_f32_16x16x32_bf16 v[106:109], v[186:189], v[194:197], v[106:109]
	v_mfma_f32_16x16x32_bf16 v[94:97], v[178:181], v[212:215], v[94:97]
	v_mfma_f32_16x16x32_bf16 v[90:93], v[186:189], v[212:215], v[90:93]
	v_mfma_f32_16x16x32_bf16 v[78:81], v[178:181], v[220:223], v[78:81]
	v_mfma_f32_16x16x32_bf16 v[74:77], v[186:189], v[220:223], v[74:77]
	v_mfma_f32_16x16x32_bf16 v[70:73], v[178:181], v[228:231], v[70:73]
	v_mfma_f32_16x16x32_bf16 v[66:69], v[186:189], v[228:231], v[66:69]
	s_setprio 0
	s_nop 1
	s_setprio 1
	v_mfma_f32_16x16x32_bf16 v[110:113], v[182:185], v[208:211], v[110:113]
	v_mfma_f32_16x16x32_bf16 v[106:109], v[190:193], v[208:211], v[106:109]
	v_mfma_f32_16x16x32_bf16 v[94:97], v[182:185], v[216:219], v[94:97]
	v_mfma_f32_16x16x32_bf16 v[90:93], v[190:193], v[216:219], v[90:93]
	v_mfma_f32_16x16x32_bf16 v[78:81], v[182:185], v[224:227], v[78:81]
	v_mfma_f32_16x16x32_bf16 v[74:77], v[190:193], v[224:227], v[74:77]
	v_mfma_f32_16x16x32_bf16 v[70:73], v[182:185], v[232:235], v[70:73]
	v_mfma_f32_16x16x32_bf16 v[66:69], v[190:193], v[232:235], v[66:69]
	s_setprio 0
	s_barrier
; #define PG8_STAGE(bufoff, gbase, voff) do { _Pragma("unroll") for (int _i = 0; _i < 2; ++_i) \
;         __builtin_amdgcn_global_load_lds((const unsigned*)((const char*)(gbase) + (voff)[_i]), (PG8_LAS unsigned*)(lds + (bufoff) + ldsw + _i * 8192), 16, 0, 0); } while (0)
; #define PG8_LDA(dst, b, h) do { _Pragma("unroll") for (int m = 0; m < 4; ++m) _Pragma("unroll") for (int k = 0; k < 2; ++k) dst[m][k] = *(const PG8_LAS bf16x8*)(lds + PG8_SA(b, h) + aoff + m * 2048 + k * 1024); } while (0)
; #define PG8_MMA(ai, bj, At, Bt) do { __builtin_amdgcn_s_setprio(1); _Pragma("unroll") for (int m = 0; m < 4; ++m) _Pragma("unroll") for (int n = 0; n < 2; ++n) _Pragma("unroll") for (int k = 0; k < 2; ++k) \
;         acc[ai][bj][m][n] = __builtin_amdgcn_mfma_f32_16x16x32_bf16(Bt[n][k], At[m][k], acc[ai][bj][m][n], 0, 0, 0); __builtin_amdgcn_s_setprio(0); } while (0)
; #define PG8_WAIT_V(n) asm volatile("s_waitcnt vmcnt(" #n ")" ::: "memory")
; #define PG8_WAIT_L(n) asm volatile("s_waitcnt lgkmcnt(" #n ")" ::: "memory")
; #define PG8_BAR __builtin_amdgcn_s_barrier()
; #define PG8_SCHED __builtin_amdgcn_sched_barrier(0)
; template <class Epi, class Sched, bool ALIGN_EPI = false, bool SP2 = false>
; __device__ __forceinline__ void gemm_phase(PG8_LAS unsigned char* lds, const Gemm g, const Sched& S, const Epi& E, const int wave0) {
;     ...
;         for (int t = 0; t < nt; t += 2) {
;             const bool last = (t == nt - 2);
;             const char* a1 = cA + (size_t)(t + 1) * kstep;
;             const char* a2 = last ? nA : cA + (size_t)(t + 2) * kstep; const char* b2 = last ? nB : cB + (size_t)(t + 2) * kstep;
;     ...
;             PG8_LDA(At, 1, 1); PG8_STAGE(PG8_SB(1, 0), b3, voffB); PG8_STAGE(PG8_SB(1, 1), b3 + hstepB, voffB); PG8_STAGE(PG8_SA(1, 0), a3, voffA);
;             PG8_WAIT_V(8); PG8_WAIT_L(0); PG8_BAR; PG8_MMA(1, 0, At, B0); PG8_MMA(1, 1, At, B1); PG8_BAR; PG8_SCHED;
	s_add_i32 s18, s42, s22
	s_add_u32 s46, s16, 0x80
	s_addc_u32 s47, s17, 0
	s_mov_b32 m0, s18
	ds_read_b128 v[194:197], v143 offset:49152
	ds_read_b128 v[208:211], v143 offset:50176
	ds_read_b128 v[212:215], v143 offset:51200
	ds_read_b128 v[216:219], v143 offset:52224
	ds_read_b128 v[220:223], v143 offset:53248
	ds_read_b128 v[224:227], v143 offset:54272
	ds_read_b128 v[228:231], v143 offset:55296
	ds_read_b128 v[232:235], v143 offset:56320
	global_load_lds_dwordx4 v64, s[46:47]
	s_add_i32 m0, s18, 0x2000
	s_add_u32 s16, s16, 0x80080
	s_addc_u32 s17, s17, 0
	s_add_i32 s18, s43, s22
	global_load_lds_dwordx4 v130, s[46:47]
	s_mov_b32 m0, s18
	s_nop 0
	global_load_lds_dwordx4 v64, s[16:17]
	s_add_i32 m0, s18, 0x2000
	s_nop 0
	global_load_lds_dwordx4 v130, s[16:17]
	s_add_u32 s100, s100, 0x80
	s_addc_u32 s101, s101, 0
	s_mov_b32 m0, s34
	s_nop 0
	global_load_lds_dwordx4 v134, s[100:101]
	s_mov_b32 m0, s35
	s_nop 0
	global_load_lds_dwordx4 v132, s[100:101]
	s_waitcnt vmcnt(8)
	s_waitcnt lgkmcnt(0)
	s_barrier
	s_setprio 1
	s_waitcnt lgkmcnt(0)
	v_mfma_f32_16x16x32_bf16 v[60:63], v[144:147], v[194:197], v[60:63]
	v_mfma_f32_16x16x32_bf16 v[56:59], v[152:155], v[194:197], v[56:59]
	v_mfma_f32_16x16x32_bf16 v[52:55], v[144:147], v[212:215], v[52:55]
	v_mfma_f32_16x16x32_bf16 v[48:51], v[152:155], v[212:215], v[48:51]
	v_mfma_f32_16x16x32_bf16 v[36:39], v[144:147], v[220:223], v[36:39]
	v_mfma_f32_16x16x32_bf16 v[32:35], v[152:155], v[220:223], v[32:35]
	v_mfma_f32_16x16x32_bf16 v[20:23], v[144:147], v[228:231], v[20:23]
	v_mfma_f32_16x16x32_bf16 v[16:19], v[152:155], v[228:231], v[16:19]
	s_setprio 0
	s_nop 1
	s_setprio 1
	v_mfma_f32_16x16x32_bf16 v[60:63], v[148:151], v[208:211], v[60:63]
	v_mfma_f32_16x16x32_bf16 v[56:59], v[156:159], v[208:211], v[56:59]
	v_mfma_f32_16x16x32_bf16 v[52:55], v[148:151], v[216:219], v[52:55]
	v_mfma_f32_16x16x32_bf16 v[48:51], v[156:159], v[216:219], v[48:51]
	v_mfma_f32_16x16x32_bf16 v[36:39], v[148:151], v[224:227], v[36:39]
	v_mfma_f32_16x16x32_bf16 v[32:35], v[156:159], v[224:227], v[32:35]
	v_mfma_f32_16x16x32_bf16 v[20:23], v[148:151], v[232:235], v[20:23]
	v_mfma_f32_16x16x32_bf16 v[16:19], v[156:159], v[232:235], v[16:19]
	s_setprio 0
	s_nop 1
	s_setprio 1
	v_mfma_f32_16x16x32_bf16 v[44:47], v[178:181], v[194:197], v[44:47]
	v_mfma_f32_16x16x32_bf16 v[40:43], v[186:189], v[194:197], v[40:43]
	v_mfma_f32_16x16x32_bf16 v[28:31], v[178:181], v[212:215], v[28:31]
	v_mfma_f32_16x16x32_bf16 v[24:27], v[186:189], v[212:215], v[24:27]
	v_mfma_f32_16x16x32_bf16 v[12:15], v[178:181], v[220:223], v[12:15]
	v_mfma_f32_16x16x32_bf16 v[8:11], v[186:189], v[220:223], v[8:11]
	v_mfma_f32_16x16x32_bf16 v[4:7], v[178:181], v[228:231], v[4:7]
	v_mfma_f32_16x16x32_bf16 v[0:3], v[186:189], v[228:231], v[0:3]
	s_setprio 0
	s_nop 1
	s_setprio 1
	v_mfma_f32_16x16x32_bf16 v[44:47], v[182:185], v[208:211], v[44:47]
	v_mfma_f32_16x16x32_bf16 v[40:43], v[190:193], v[208:211], v[40:43]
	v_mfma_f32_16x16x32_bf16 v[28:31], v[182:185], v[216:219], v[28:31]
	v_mfma_f32_16x16x32_bf16 v[24:27], v[190:193], v[216:219], v[24:27]
	v_mfma_f32_16x16x32_bf16 v[12:15], v[182:185], v[224:227], v[12:15]
	v_mfma_f32_16x16x32_bf16 v[8:11], v[190:193], v[224:227], v[8:11]
	v_mfma_f32_16x16x32_bf16 v[4:7], v[182:185], v[232:235], v[4:7]
	v_mfma_f32_16x16x32_bf16 v[0:3], v[190:193], v[232:235], v[0:3]
	s_setprio 0
	s_barrier
	s_add_i32 s41, s41, 2
	s_add_u32 s0, s0, 0x100
	s_addc_u32 s1, s1, 0
	s_add_u32 s15, s15, 0x100
	s_addc_u32 s27, s27, 0
	s_cmp_gt_u32 s41, 13
	s_cbranch_scc0 .LBB0_1360
	s_mov_b64 s[46:47], 0x80
	s_and_b64 vcc, exec, s[8:9]
	s_cbranch_vccz .LBB0_1363
	s_barrier

; #define PG8_STAGE(bufoff, gbase, voff) do { _Pragma("unroll") for (int _i = 0; _i < 2; ++_i) \
;         __builtin_amdgcn_global_load_lds((const unsigned*)((const char*)(gbase) + (voff)[_i]), (PG8_LAS unsigned*)(lds + (bufoff) + ldsw + _i * 8192), 16, 0, 0); } while (0)
; #define PG8_LDA(dst, b, h) do { _Pragma("unroll") for (int m = 0; m < 4; ++m) _Pragma("unroll") for (int k = 0; k < 2; ++k) dst[m][k] = *(const PG8_LAS bf16x8*)(lds + PG8_SA(b, h) + aoff + m * 2048 + k * 1024); } while (0)
; #define PG8_LDB(dst, b, h) do { _Pragma("unroll") for (int n = 0; n < 2; ++n) _Pragma("unroll") for (int k = 0; k < 2; ++k) dst[n][k] = *(const PG8_LAS bf16x8*)(lds + PG8_SB(b, h) + boff + n * 2048 + k * 1024); } while (0)
; #define PG8_MMA(ai, bj, At, Bt) do { __builtin_amdgcn_s_setprio(1); _Pragma("unroll") for (int m = 0; m < 4; ++m) _Pragma("unroll") for (int n = 0; n < 2; ++n) _Pragma("unroll") for (int k = 0; k < 2; ++k) \
;         acc[ai][bj][m][n] = __builtin_amdgcn_mfma_f32_16x16x32_bf16(Bt[n][k], At[m][k], acc[ai][bj][m][n], 0, 0, 0); __builtin_amdgcn_s_setprio(0); } while (0)
; #define PG8_WAIT_V(n) asm volatile("s_waitcnt vmcnt(" #n ")" ::: "memory")
; #define PG8_BAR __builtin_amdgcn_s_barrier()
; template <class Epi, class Sched, bool ALIGN_EPI = false, bool SP2 = false>
; __device__ __forceinline__ void gemm_phase(PG8_LAS unsigned char* lds, const Gemm g, const Sched& S, const Epi& E, const int wave0) {
;     ...
;         for (int t = 0; t < nt; t += 2) {
;             const bool last = (t == nt - 2);
;             const char* a1 = cA + (size_t)(t + 1) * kstep;
;             const char* a2 = last ? nA : cA + (size_t)(t + 2) * kstep; const char* b2 = last ? nB : cB + (size_t)(t + 2) * kstep;
;             const char* a3 = a2 + kstep; const char* b3 = b2 + kstep;
;             if (last && has_next) S.a_ready(nxt);
;             if constexpr (SP2) {
;             PG8_LDB(B0, 0, 0); PG8_LDB(B1, 0, 1); PG8_SCHED; PG8_LDA(At, 0, 0); PG8_STAGE(PG8_SA(1, 1), a1 + hstepA, voffA);
;             PG8_WAIT_V(8); PG8_WAIT_L(0); PG8_BAR; PG8_MMA(0, 0, At, B0); PG8_MMA(0, 1, At, B1); PG8_BAR; PG8_SCHED;
;             PG8_LDA(At, 0, 1); PG8_STAGE(PG8_SB(0, 0), b2, voffB); PG8_STAGE(PG8_SB(0, 1), b2 + hstepB, voffB); PG8_STAGE(PG8_SA(0, 0), a2, voffA);
;             PG8_WAIT_V(8); PG8_WAIT_L(0); PG8_BAR; PG8_MMA(1, 0, At, B0); PG8_MMA(1, 1, At, B1); PG8_BAR; PG8_SCHED;
.LBB0_1571:
	s_add_u32 s16, s0, 0xfff80080
	s_addc_u32 s17, s1, -1
	s_add_i32 s46, 0, 0x10000
	s_cmp_eq_u32 s45, 28
	s_cselect_b32 s19, s9, s17
	s_cselect_b32 s18, s33, s16
	s_cselect_b32 s17, s7, s44
	s_cselect_b32 s16, s36, s37
	s_add_i32 s48, 0, 0x14000
	ds_read_b128 v[140:143], v252
	ds_read_b128 v[148:151], v252 offset:1024
	ds_read_b128 v[152:155], v252 offset:2048
	ds_read_b128 v[156:159], v252 offset:3072
	ds_read_b128 v[178:181], v253
	ds_read_b128 v[182:185], v253 offset:1024
	ds_read_b128 v[186:189], v253 offset:2048
	ds_read_b128 v[190:193], v253 offset:3072
	s_add_i32 m0, s15, 0xc000
	ds_read_b128 v[194:197], v147
	ds_read_b128 v[208:211], v147 offset:1024
	ds_read_b128 v[212:215], v147 offset:2048
	ds_read_b128 v[216:219], v147 offset:3072
	ds_read_b128 v[220:223], v147 offset:4096
	ds_read_b128 v[224:227], v147 offset:5120
	ds_read_b128 v[228:231], v147 offset:6144
	ds_read_b128 v[232:235], v147 offset:7168
	global_load_lds_dwordx4 v136, s[0:1]
	s_add_i32 m0, s15, 0xe000
	s_nop 0
	global_load_lds_dwordx4 v138, s[0:1]
	s_waitcnt vmcnt(8)
	s_waitcnt lgkmcnt(0)
	s_barrier
	s_setprio 1
	s_waitcnt lgkmcnt(0)
	v_mfma_f32_16x16x32_bf16 v[126:129], v[140:143], v[194:197], v[126:129]
	v_mfma_f32_16x16x32_bf16 v[122:125], v[152:155], v[194:197], v[122:125]
	v_mfma_f32_16x16x32_bf16 v[110:113], v[140:143], v[212:215], v[110:113]
	v_mfma_f32_16x16x32_bf16 v[106:109], v[152:155], v[212:215], v[106:109]
	v_mfma_f32_16x16x32_bf16 v[94:97], v[140:143], v[220:223], v[94:97]
	v_mfma_f32_16x16x32_bf16 v[90:93], v[152:155], v[220:223], v[90:93]
	v_mfma_f32_16x16x32_bf16 v[78:81], v[140:143], v[228:231], v[78:81]
	v_mfma_f32_16x16x32_bf16 v[74:77], v[152:155], v[228:231], v[74:77]
	s_setprio 0
	s_nop 1
	s_setprio 1
	v_mfma_f32_16x16x32_bf16 v[126:129], v[148:151], v[208:211], v[126:129]
	v_mfma_f32_16x16x32_bf16 v[122:125], v[156:159], v[208:211], v[122:125]
	v_mfma_f32_16x16x32_bf16 v[110:113], v[148:151], v[216:219], v[110:113]
	v_mfma_f32_16x16x32_bf16 v[106:109], v[156:159], v[216:219], v[106:109]
	v_mfma_f32_16x16x32_bf16 v[94:97], v[148:151], v[224:227], v[94:97]
	v_mfma_f32_16x16x32_bf16 v[90:93], v[156:159], v[224:227], v[90:93]
	v_mfma_f32_16x16x32_bf16 v[78:81], v[148:151], v[232:235], v[78:81]
	v_mfma_f32_16x16x32_bf16 v[74:77], v[156:159], v[232:235], v[74:77]
	s_setprio 0
	s_nop 1
	s_setprio 1
	v_mfma_f32_16x16x32_bf16 v[118:121], v[178:181], v[194:197], v[118:121]
	v_mfma_f32_16x16x32_bf16 v[114:117], v[186:189], v[194:197], v[114:117]
	v_mfma_f32_16x16x32_bf16 v[102:105], v[178:181], v[212:215], v[102:105]
	v_mfma_f32_16x16x32_bf16 v[98:101], v[186:189], v[212:215], v[98:101]
	v_mfma_f32_16x16x32_bf16 v[86:89], v[178:181], v[220:223], v[86:89]
	v_mfma_f32_16x16x32_bf16 v[82:85], v[186:189], v[220:223], v[82:85]
	v_mfma_f32_16x16x32_bf16 v[70:73], v[178:181], v[228:231], v[70:73]
	v_mfma_f32_16x16x32_bf16 v[66:69], v[186:189], v[228:231], v[66:69]
	s_setprio 0
	s_nop 1
	s_setprio 1
	v_mfma_f32_16x16x32_bf16 v[118:121], v[182:185], v[208:211], v[118:121]
	v_mfma_f32_16x16x32_bf16 v[114:117], v[190:193], v[208:211], v[114:117]
	v_mfma_f32_16x16x32_bf16 v[102:105], v[182:185], v[216:219], v[102:105]
	v_mfma_f32_16x16x32_bf16 v[98:101], v[190:193], v[216:219], v[98:101]
	v_mfma_f32_16x16x32_bf16 v[86:89], v[182:185], v[224:227], v[86:89]
	v_mfma_f32_16x16x32_bf16 v[82:85], v[190:193], v[224:227], v[82:85]
	v_mfma_f32_16x16x32_bf16 v[70:73], v[182:185], v[232:235], v[70:73]
	v_mfma_f32_16x16x32_bf16 v[66:69], v[190:193], v[232:235], v[66:69]
	s_setprio 0
	s_barrier
	s_add_i32 s46, s46, s28
	s_mov_b32 m0, s46
	ds_read_b128 v[194:197], v147 offset:16384
	ds_read_b128 v[208:211], v147 offset:17408
	ds_read_b128 v[212:215], v147 offset:18432
	ds_read_b128 v[216:219], v147 offset:19456
	ds_read_b128 v[220:223], v147 offset:20480
	ds_read_b128 v[224:227], v147 offset:21504
	ds_read_b128 v[228:231], v147 offset:22528
	ds_read_b128 v[232:235], v147 offset:23552
	global_load_lds_dwordx4 v64, s[16:17]
	s_add_i32 m0, s46, 0x2000
	s_add_u32 s46, s16, 0x80000
	s_addc_u32 s47, s17, 0
	s_add_i32 s48, s48, s28
	global_load_lds_dwordx4 v130, s[16:17]
	s_mov_b32 m0, s48
	s_mov_b64 s[100:101], s[18:19]
	global_load_lds_dwordx4 v64, s[46:47]
	s_add_i32 m0, s48, 0x2000
	s_nop 0
	global_load_lds_dwordx4 v130, s[46:47]
	s_mov_b32 m0, s15
	s_nop 0
	global_load_lds_dwordx4 v134, s[18:19]
	s_mov_b32 m0, s27
	s_nop 0
	global_load_lds_dwordx4 v132, s[18:19]
	s_waitcnt vmcnt(8)
	s_waitcnt lgkmcnt(0)
	s_barrier
; #define PG8_STAGE(bufoff, gbase, voff) do { _Pragma("unroll") for (int _i = 0; _i < 2; ++_i) \
;         __builtin_amdgcn_global_load_lds((const unsigned*)((const char*)(gbase) + (voff)[_i]), (PG8_LAS unsigned*)(lds + (bufoff) + ldsw + _i * 8192), 16, 0, 0); } while (0)
; #define PG8_LDA(dst, b, h) do { _Pragma("unroll") for (int m = 0; m < 4; ++m) _Pragma("unroll") for (int k = 0; k < 2; ++k) dst[m][k] = *(const PG8_LAS bf16x8*)(lds + PG8_SA(b, h) + aoff + m * 2048 + k * 1024); } while (0)
; #define PG8_LDB(dst, b, h) do { _Pragma("unroll") for (int n = 0; n < 2; ++n) _Pragma("unroll") for (int k = 0; k < 2; ++k) dst[n][k] = *(const PG8_LAS bf16x8*)(lds + PG8_SB(b, h) + boff + n * 2048 + k * 1024); } while (0)
; #define PG8_MMA(ai, bj, At, Bt) do { __builtin_amdgcn_s_setprio(1); _Pragma("unroll") for (int m = 0; m < 4; ++m) _Pragma("unroll") for (int n = 0; n < 2; ++n) _Pragma("unroll") for (int k = 0; k < 2; ++k) \
;         acc[ai][bj][m][n] = __builtin_amdgcn_mfma_f32_16x16x32_bf16(Bt[n][k], At[m][k], acc[ai][bj][m][n], 0, 0, 0); __builtin_amdgcn_s_setprio(0); } while (0)
; #define PG8_WAIT_V(n) asm volatile("s_waitcnt vmcnt(" #n ")" ::: "memory")
; #define PG8_WAIT_L(n) asm volatile("s_waitcnt lgkmcnt(" #n ")" ::: "memory")
; #define PG8_BAR __builtin_amdgcn_s_barrier()
; #define PG8_SCHED __builtin_amdgcn_sched_barrier(0)
; template <class Epi, class Sched, bool ALIGN_EPI = false, bool SP2 = false>
; __device__ __forceinline__ void gemm_phase(PG8_LAS unsigned char* lds, const Gemm g, const Sched& S, const Epi& E, const int wave0) {
;     ...
;             PG8_WAIT_V(8); PG8_WAIT_L(0); PG8_BAR; PG8_MMA(1, 0, At, B0); PG8_MMA(1, 1, At, B1); PG8_BAR; PG8_SCHED;
;             PG8_LDB(B0, 1, 0); PG8_LDB(B1, 1, 1); PG8_SCHED; PG8_LDA(At, 1, 0); PG8_STAGE(PG8_SA(0, 1), a2 + hstepA, voffA);
;             PG8_WAIT_V(8); PG8_WAIT_L(0); PG8_BAR; PG8_MMA(0, 0, At, B0); PG8_MMA(0, 1, At, B1); PG8_BAR; PG8_SCHED;
	s_setprio 1
	s_waitcnt lgkmcnt(0)
	v_mfma_f32_16x16x32_bf16 v[60:63], v[140:143], v[194:197], v[60:63]
	v_mfma_f32_16x16x32_bf16 v[56:59], v[152:155], v[194:197], v[56:59]
	v_mfma_f32_16x16x32_bf16 v[44:47], v[140:143], v[212:215], v[44:47]
	v_mfma_f32_16x16x32_bf16 v[40:43], v[152:155], v[212:215], v[40:43]
	v_mfma_f32_16x16x32_bf16 v[28:31], v[140:143], v[220:223], v[28:31]
	v_mfma_f32_16x16x32_bf16 v[24:27], v[152:155], v[220:223], v[24:27]
	v_mfma_f32_16x16x32_bf16 v[12:15], v[140:143], v[228:231], v[12:15]
	v_mfma_f32_16x16x32_bf16 v[8:11], v[152:155], v[228:231], v[8:11]
	s_setprio 0
	s_nop 1
	s_setprio 1
	v_mfma_f32_16x16x32_bf16 v[60:63], v[148:151], v[208:211], v[60:63]
	v_mfma_f32_16x16x32_bf16 v[56:59], v[156:159], v[208:211], v[56:59]
	v_mfma_f32_16x16x32_bf16 v[44:47], v[148:151], v[216:219], v[44:47]
	v_mfma_f32_16x16x32_bf16 v[40:43], v[156:159], v[216:219], v[40:43]
	v_mfma_f32_16x16x32_bf16 v[28:31], v[148:151], v[224:227], v[28:31]
	v_mfma_f32_16x16x32_bf16 v[24:27], v[156:159], v[224:227], v[24:27]
	v_mfma_f32_16x16x32_bf16 v[12:15], v[148:151], v[232:235], v[12:15]
	v_mfma_f32_16x16x32_bf16 v[8:11], v[156:159], v[232:235], v[8:11]
	s_setprio 0
	s_nop 1
	s_setprio 1
	v_mfma_f32_16x16x32_bf16 v[52:55], v[178:181], v[194:197], v[52:55]
	v_mfma_f32_16x16x32_bf16 v[48:51], v[186:189], v[194:197], v[48:51]
	v_mfma_f32_16x16x32_bf16 v[36:39], v[178:181], v[212:215], v[36:39]
	v_mfma_f32_16x16x32_bf16 v[32:35], v[186:189], v[212:215], v[32:35]
	v_mfma_f32_16x16x32_bf16 v[20:23], v[178:181], v[220:223], v[20:23]
	v_mfma_f32_16x16x32_bf16 v[16:19], v[186:189], v[220:223], v[16:19]
	v_mfma_f32_16x16x32_bf16 v[4:7], v[178:181], v[228:231], v[4:7]
	v_mfma_f32_16x16x32_bf16 v[0:3], v[186:189], v[228:231], v[0:3]
	s_setprio 0
	s_nop 1
	s_setprio 1
	v_mfma_f32_16x16x32_bf16 v[52:55], v[182:185], v[208:211], v[52:55]
	v_mfma_f32_16x16x32_bf16 v[48:51], v[190:193], v[208:211], v[48:51]
	v_mfma_f32_16x16x32_bf16 v[36:39], v[182:185], v[216:219], v[36:39]
	v_mfma_f32_16x16x32_bf16 v[32:35], v[190:193], v[216:219], v[32:35]
	v_mfma_f32_16x16x32_bf16 v[20:23], v[182:185], v[224:227], v[20:23]
	v_mfma_f32_16x16x32_bf16 v[16:19], v[190:193], v[224:227], v[16:19]
	v_mfma_f32_16x16x32_bf16 v[4:7], v[182:185], v[232:235], v[4:7]
	v_mfma_f32_16x16x32_bf16 v[0:3], v[190:193], v[232:235], v[0:3]
	s_setprio 0
	s_barrier
	s_add_i32 s46, 0, 0x18000
	s_add_i32 s47, 0, 0x1c000
	ds_read_b128 v[140:143], v254
	ds_read_b128 v[148:151], v254 offset:1024
	ds_read_b128 v[152:155], v254 offset:2048
	ds_read_b128 v[156:159], v254 offset:3072
	ds_read_b128 v[178:181], v255
	ds_read_b128 v[182:185], v255 offset:1024
	ds_read_b128 v[186:189], v255 offset:2048
	ds_read_b128 v[190:193], v255 offset:3072
	s_add_u32 s18, s18, 0x80000
	s_addc_u32 s19, s19, 0
	s_mov_b32 m0, s29
	ds_read_b128 v[194:197], v147 offset:32768
	ds_read_b128 v[208:211], v147 offset:33792
	ds_read_b128 v[212:215], v147 offset:34816
	ds_read_b128 v[216:219], v147 offset:35840
	ds_read_b128 v[220:223], v147 offset:36864
	ds_read_b128 v[224:227], v147 offset:37888
	ds_read_b128 v[228:231], v147 offset:38912
	ds_read_b128 v[232:235], v147 offset:39936
	global_load_lds_dwordx4 v134, s[18:19]
	s_mov_b32 m0, s30
	s_nop 0
	global_load_lds_dwordx4 v132, s[18:19]
	s_waitcnt vmcnt(8)
	s_waitcnt lgkmcnt(0)
	s_barrier
	s_setprio 1
	s_waitcnt lgkmcnt(0)
	v_mfma_f32_16x16x32_bf16 v[126:129], v[140:143], v[194:197], v[126:129]
	v_mfma_f32_16x16x32_bf16 v[122:125], v[152:155], v[194:197], v[122:125]
	v_mfma_f32_16x16x32_bf16 v[110:113], v[140:143], v[212:215], v[110:113]
	v_mfma_f32_16x16x32_bf16 v[106:109], v[152:155], v[212:215], v[106:109]
	v_mfma_f32_16x16x32_bf16 v[94:97], v[140:143], v[220:223], v[94:97]
	v_mfma_f32_16x16x32_bf16 v[90:93], v[152:155], v[220:223], v[90:93]
	v_mfma_f32_16x16x32_bf16 v[78:81], v[140:143], v[228:231], v[78:81]
	v_mfma_f32_16x16x32_bf16 v[74:77], v[152:155], v[228:231], v[74:77]
	s_setprio 0
	s_nop 1
	s_setprio 1
	v_mfma_f32_16x16x32_bf16 v[126:129], v[148:151], v[208:211], v[126:129]
	v_mfma_f32_16x16x32_bf16 v[122:125], v[156:159], v[208:211], v[122:125]
	v_mfma_f32_16x16x32_bf16 v[110:113], v[148:151], v[216:219], v[110:113]
	v_mfma_f32_16x16x32_bf16 v[106:109], v[156:159], v[216:219], v[106:109]
	v_mfma_f32_16x16x32_bf16 v[94:97], v[148:151], v[224:227], v[94:97]
	v_mfma_f32_16x16x32_bf16 v[90:93], v[156:159], v[224:227], v[90:93]
	v_mfma_f32_16x16x32_bf16 v[78:81], v[148:151], v[232:235], v[78:81]
	v_mfma_f32_16x16x32_bf16 v[74:77], v[156:159], v[232:235], v[74:77]
	s_setprio 0
	s_nop 1
	s_setprio 1
	v_mfma_f32_16x16x32_bf16 v[118:121], v[178:181], v[194:197], v[118:121]
	v_mfma_f32_16x16x32_bf16 v[114:117], v[186:189], v[194:197], v[114:117]
	v_mfma_f32_16x16x32_bf16 v[102:105], v[178:181], v[212:215], v[102:105]
	v_mfma_f32_16x16x32_bf16 v[98:101], v[186:189], v[212:215], v[98:101]
	v_mfma_f32_16x16x32_bf16 v[86:89], v[178:181], v[220:223], v[86:89]
	v_mfma_f32_16x16x32_bf16 v[82:85], v[186:189], v[220:223], v[82:85]
	v_mfma_f32_16x16x32_bf16 v[70:73], v[178:181], v[228:231], v[70:73]
	v_mfma_f32_16x16x32_bf16 v[66:69], v[186:189], v[228:231], v[66:69]
	s_setprio 0
	s_nop 1
	s_setprio 1
	v_mfma_f32_16x16x32_bf16 v[118:121], v[182:185], v[208:211], v[118:121]
	v_mfma_f32_16x16x32_bf16 v[114:117], v[190:193], v[208:211], v[114:117]
	v_mfma_f32_16x16x32_bf16 v[102:105], v[182:185], v[216:219], v[102:105]
	v_mfma_f32_16x16x32_bf16 v[98:101], v[190:193], v[216:219], v[98:101]
	v_mfma_f32_16x16x32_bf16 v[86:89], v[182:185], v[224:227], v[86:89]
	v_mfma_f32_16x16x32_bf16 v[82:85], v[190:193], v[224:227], v[82:85]
	v_mfma_f32_16x16x32_bf16 v[70:73], v[182:185], v[232:235], v[70:73]
	v_mfma_f32_16x16x32_bf16 v[66:69], v[190:193], v[232:235], v[66:69]
	s_setprio 0
	s_barrier
; #define PG8_STAGE(bufoff, gbase, voff) do { _Pragma("unroll") for (int _i = 0; _i < 2; ++_i) \
;         __builtin_amdgcn_global_load_lds((const unsigned*)((const char*)(gbase) + (voff)[_i]), (PG8_LAS unsigned*)(lds + (bufoff) + ldsw + _i * 8192), 16, 0, 0); } while (0)
; #define PG8_LDA(dst, b, h) do { _Pragma("unroll") for (int m = 0; m < 4; ++m) _Pragma("unroll") for (int k = 0; k < 2; ++k) dst[m][k] = *(const PG8_LAS bf16x8*)(lds + PG8_SA(b, h) + aoff + m * 2048 + k * 1024); } while (0)
; #define PG8_MMA(ai, bj, At, Bt) do { __builtin_amdgcn_s_setprio(1); _Pragma("unroll") for (int m = 0; m < 4; ++m) _Pragma("unroll") for (int n = 0; n < 2; ++n) _Pragma("unroll") for (int k = 0; k < 2; ++k) \
;         acc[ai][bj][m][n] = __builtin_amdgcn_mfma_f32_16x16x32_bf16(Bt[n][k], At[m][k], acc[ai][bj][m][n], 0, 0, 0); __builtin_amdgcn_s_setprio(0); } while (0)
; #define PG8_WAIT_V(n) asm volatile("s_waitcnt vmcnt(" #n ")" ::: "memory")
; #define PG8_WAIT_L(n) asm volatile("s_waitcnt lgkmcnt(" #n ")" ::: "memory")
; #define PG8_BAR __builtin_amdgcn_s_barrier()
; #define PG8_SCHED __builtin_amdgcn_sched_barrier(0)
; template <class Epi, class Sched, bool ALIGN_EPI = false, bool SP2 = false>
; __device__ __forceinline__ void gemm_phase(PG8_LAS unsigned char* lds, const Gemm g, const Sched& S, const Epi& E, const int wave0) {
;     ...
;         for (int t = 0; t < nt; t += 2) {
;             const bool last = (t == nt - 2);
;             const char* a1 = cA + (size_t)(t + 1) * kstep;
;             const char* a2 = last ? nA : cA + (size_t)(t + 2) * kstep; const char* b2 = last ? nB : cB + (size_t)(t + 2) * kstep;
;     ...
;             PG8_LDA(At, 1, 1); PG8_STAGE(PG8_SB(1, 0), b3, voffB); PG8_STAGE(PG8_SB(1, 1), b3 + hstepB, voffB); PG8_STAGE(PG8_SA(1, 0), a3, voffA);
;             PG8_WAIT_V(8); PG8_WAIT_L(0); PG8_BAR; PG8_MMA(1, 0, At, B0); PG8_MMA(1, 1, At, B1); PG8_BAR; PG8_SCHED;
	s_add_i32 s18, s46, s28
	s_add_u32 s50, s16, 0x80
	s_addc_u32 s51, s17, 0
	s_mov_b32 m0, s18
	ds_read_b128 v[194:197], v147 offset:49152
	ds_read_b128 v[208:211], v147 offset:50176
	ds_read_b128 v[212:215], v147 offset:51200
	ds_read_b128 v[216:219], v147 offset:52224
	ds_read_b128 v[220:223], v147 offset:53248
	ds_read_b128 v[224:227], v147 offset:54272
	ds_read_b128 v[228:231], v147 offset:55296
	ds_read_b128 v[232:235], v147 offset:56320
	global_load_lds_dwordx4 v64, s[50:51]
	s_add_i32 m0, s18, 0x2000
	s_add_u32 s16, s16, 0x80080
	s_addc_u32 s17, s17, 0
	s_add_i32 s18, s47, s28
	global_load_lds_dwordx4 v130, s[50:51]
	s_mov_b32 m0, s18
	s_nop 0
	global_load_lds_dwordx4 v64, s[16:17]
	s_add_i32 m0, s18, 0x2000
	s_nop 0
	global_load_lds_dwordx4 v130, s[16:17]
	s_add_u32 s100, s100, 0x80
	s_addc_u32 s101, s101, 0
	s_mov_b32 m0, s31
	s_nop 0
	global_load_lds_dwordx4 v134, s[100:101]
	s_mov_b32 m0, s34
	s_nop 0
	global_load_lds_dwordx4 v132, s[100:101]
	s_waitcnt vmcnt(8)
	s_waitcnt lgkmcnt(0)
	s_barrier
	s_setprio 1
	s_waitcnt lgkmcnt(0)
	v_mfma_f32_16x16x32_bf16 v[60:63], v[140:143], v[194:197], v[60:63]
	v_mfma_f32_16x16x32_bf16 v[56:59], v[152:155], v[194:197], v[56:59]
	v_mfma_f32_16x16x32_bf16 v[44:47], v[140:143], v[212:215], v[44:47]
	v_mfma_f32_16x16x32_bf16 v[40:43], v[152:155], v[212:215], v[40:43]
	v_mfma_f32_16x16x32_bf16 v[28:31], v[140:143], v[220:223], v[28:31]
	v_mfma_f32_16x16x32_bf16 v[24:27], v[152:155], v[220:223], v[24:27]
	v_mfma_f32_16x16x32_bf16 v[12:15], v[140:143], v[228:231], v[12:15]
	v_mfma_f32_16x16x32_bf16 v[8:11], v[152:155], v[228:231], v[8:11]
	s_setprio 0
	s_nop 1
	s_setprio 1
	v_mfma_f32_16x16x32_bf16 v[60:63], v[148:151], v[208:211], v[60:63]
	v_mfma_f32_16x16x32_bf16 v[56:59], v[156:159], v[208:211], v[56:59]
	v_mfma_f32_16x16x32_bf16 v[44:47], v[148:151], v[216:219], v[44:47]
	v_mfma_f32_16x16x32_bf16 v[40:43], v[156:159], v[216:219], v[40:43]
	v_mfma_f32_16x16x32_bf16 v[28:31], v[148:151], v[224:227], v[28:31]
	v_mfma_f32_16x16x32_bf16 v[24:27], v[156:159], v[224:227], v[24:27]
	v_mfma_f32_16x16x32_bf16 v[12:15], v[148:151], v[232:235], v[12:15]
	v_mfma_f32_16x16x32_bf16 v[8:11], v[156:159], v[232:235], v[8:11]
	s_setprio 0
	s_nop 1
	s_setprio 1
	v_mfma_f32_16x16x32_bf16 v[52:55], v[178:181], v[194:197], v[52:55]
	v_mfma_f32_16x16x32_bf16 v[48:51], v[186:189], v[194:197], v[48:51]
	v_mfma_f32_16x16x32_bf16 v[36:39], v[178:181], v[212:215], v[36:39]
	v_mfma_f32_16x16x32_bf16 v[32:35], v[186:189], v[212:215], v[32:35]
	v_mfma_f32_16x16x32_bf16 v[20:23], v[178:181], v[220:223], v[20:23]
	v_mfma_f32_16x16x32_bf16 v[16:19], v[186:189], v[220:223], v[16:19]
	v_mfma_f32_16x16x32_bf16 v[4:7], v[178:181], v[228:231], v[4:7]
	v_mfma_f32_16x16x32_bf16 v[0:3], v[186:189], v[228:231], v[0:3]
	s_setprio 0
	s_nop 1
	s_setprio 1
	v_mfma_f32_16x16x32_bf16 v[52:55], v[182:185], v[208:211], v[52:55]
	v_mfma_f32_16x16x32_bf16 v[48:51], v[190:193], v[208:211], v[48:51]
	v_mfma_f32_16x16x32_bf16 v[36:39], v[182:185], v[216:219], v[36:39]
	v_mfma_f32_16x16x32_bf16 v[32:35], v[190:193], v[216:219], v[32:35]
	v_mfma_f32_16x16x32_bf16 v[20:23], v[182:185], v[224:227], v[20:23]
	v_mfma_f32_16x16x32_bf16 v[16:19], v[190:193], v[224:227], v[16:19]
	v_mfma_f32_16x16x32_bf16 v[4:7], v[182:185], v[232:235], v[4:7]
	v_mfma_f32_16x16x32_bf16 v[0:3], v[190:193], v[232:235], v[0:3]
	s_setprio 0
	s_barrier
	s_add_i32 s45, s45, 2
	s_add_u32 s0, s0, 0x100
	s_addc_u32 s1, s1, 0
	s_add_u32 s37, s37, 0x100
	s_addc_u32 s44, s44, 0
	s_cmp_gt_u32 s45, 29
	s_cbranch_scc0 .LBB0_1571
	s_mov_b64 s[50:51], 0x80
	s_and_b64 vcc, exec, s[4:5]
	s_cbranch_vccz .LBB0_1574
	s_barrier

; #define PG8_STAGE(bufoff, gbase, voff) do { _Pragma("unroll") for (int _i = 0; _i < 2; ++_i) \
;         __builtin_amdgcn_global_load_lds((const unsigned*)((const char*)(gbase) + (voff)[_i]), (PG8_LAS unsigned*)(lds + (bufoff) + ldsw + _i * 8192), 16, 0, 0); } while (0)
; #define PG8_LDA(dst, b, h) do { _Pragma("unroll") for (int m = 0; m < 4; ++m) _Pragma("unroll") for (int k = 0; k < 2; ++k) dst[m][k] = *(const PG8_LAS bf16x8*)(lds + PG8_SA(b, h) + aoff + m * 2048 + k * 1024); } while (0)
; #define PG8_LDB(dst, b, h) do { _Pragma("unroll") for (int n = 0; n < 2; ++n) _Pragma("unroll") for (int k = 0; k < 2; ++k) dst[n][k] = *(const PG8_LAS bf16x8*)(lds + PG8_SB(b, h) + boff + n * 2048 + k * 1024); } while (0)
; #define PG8_MMA(ai, bj, At, Bt) do { __builtin_amdgcn_s_setprio(1); _Pragma("unroll") for (int m = 0; m < 4; ++m) _Pragma("unroll") for (int n = 0; n < 2; ++n) _Pragma("unroll") for (int k = 0; k < 2; ++k) \
;         acc[ai][bj][m][n] = __builtin_amdgcn_mfma_f32_16x16x32_bf16(Bt[n][k], At[m][k], acc[ai][bj][m][n], 0, 0, 0); __builtin_amdgcn_s_setprio(0); } while (0)
; #define PG8_WAIT_V(n) asm volatile("s_waitcnt vmcnt(" #n ")" ::: "memory")
; #define PG8_BAR __builtin_amdgcn_s_barrier()
; template <class Epi, class Sched, bool ALIGN_EPI = false, bool SP2 = false>
; __device__ __forceinline__ void gemm_phase(PG8_LAS unsigned char* lds, const Gemm g, const Sched& S, const Epi& E, const int wave0) {
;     ...
;         for (int t = 0; t < nt; t += 2) {
;             const bool last = (t == nt - 2);
;             const char* a1 = cA + (size_t)(t + 1) * kstep;
;             const char* a2 = last ? nA : cA + (size_t)(t + 2) * kstep; const char* b2 = last ? nB : cB + (size_t)(t + 2) * kstep;
;             const char* a3 = a2 + kstep; const char* b3 = b2 + kstep;
;             if (last && has_next) S.a_ready(nxt);
;             if constexpr (SP2) {
;             PG8_LDB(B0, 0, 0); PG8_LDB(B1, 0, 1); PG8_SCHED; PG8_LDA(At, 0, 0); PG8_STAGE(PG8_SA(1, 1), a1 + hstepA, voffA);
;             PG8_WAIT_V(8); PG8_WAIT_L(0); PG8_BAR; PG8_MMA(0, 0, At, B0); PG8_MMA(0, 1, At, B1); PG8_BAR; PG8_SCHED;
;             PG8_LDA(At, 0, 1); PG8_STAGE(PG8_SB(0, 0), b2, voffB); PG8_STAGE(PG8_SB(0, 1), b2 + hstepB, voffB); PG8_STAGE(PG8_SA(0, 0), a2, voffA);
;             PG8_WAIT_V(8); PG8_WAIT_L(0); PG8_BAR; PG8_MMA(1, 0, At, B0); PG8_MMA(1, 1, At, B1); PG8_BAR; PG8_SCHED;
.LBB0_1685:
	s_add_u32 s16, s0, 0xffe00080
	s_addc_u32 s17, s1, -1
	s_add_i32 s43, 0, 0x10000
	s_cmpk_eq_i32 s42, 0x7c
	s_cselect_b32 s19, s11, s17
	s_cselect_b32 s18, s34, s16
	s_cselect_b32 s17, s9, s37
	s_cselect_b32 s16, s35, s36
	s_add_i32 s46, 0, 0x14000
	ds_read_b128 v[144:147], v252
	ds_read_b128 v[148:151], v252 offset:1024
	ds_read_b128 v[152:155], v252 offset:2048
	ds_read_b128 v[156:159], v252 offset:3072
	ds_read_b128 v[178:181], v253
	ds_read_b128 v[182:185], v253 offset:1024
	ds_read_b128 v[186:189], v253 offset:2048
	ds_read_b128 v[190:193], v253 offset:3072
	s_add_i32 m0, s21, 0xc000
	ds_read_b128 v[194:197], v143
	ds_read_b128 v[208:211], v143 offset:1024
	ds_read_b128 v[212:215], v143 offset:2048
	ds_read_b128 v[216:219], v143 offset:3072
	ds_read_b128 v[220:223], v143 offset:4096
	ds_read_b128 v[224:227], v143 offset:5120
	ds_read_b128 v[228:231], v143 offset:6144
	ds_read_b128 v[232:235], v143 offset:7168
	global_load_lds_dwordx4 v136, s[0:1]
	s_add_i32 m0, s21, 0xe000
	s_nop 0
	global_load_lds_dwordx4 v138, s[0:1]
	s_waitcnt vmcnt(8)
	s_waitcnt lgkmcnt(0)
	s_barrier
	s_setprio 1
	s_waitcnt lgkmcnt(0)
	v_mfma_f32_16x16x32_bf16 v[126:129], v[144:147], v[194:197], v[126:129]
	v_mfma_f32_16x16x32_bf16 v[122:125], v[152:155], v[194:197], v[122:125]
	v_mfma_f32_16x16x32_bf16 v[118:121], v[144:147], v[212:215], v[118:121]
	v_mfma_f32_16x16x32_bf16 v[114:117], v[152:155], v[212:215], v[114:117]
	v_mfma_f32_16x16x32_bf16 v[102:105], v[144:147], v[220:223], v[102:105]
	v_mfma_f32_16x16x32_bf16 v[98:101], v[152:155], v[220:223], v[98:101]
	v_mfma_f32_16x16x32_bf16 v[86:89], v[144:147], v[228:231], v[86:89]
	v_mfma_f32_16x16x32_bf16 v[82:85], v[152:155], v[228:231], v[82:85]
	s_setprio 0
	s_nop 1
	s_setprio 1
	v_mfma_f32_16x16x32_bf16 v[126:129], v[148:151], v[208:211], v[126:129]
	v_mfma_f32_16x16x32_bf16 v[122:125], v[156:159], v[208:211], v[122:125]
	v_mfma_f32_16x16x32_bf16 v[118:121], v[148:151], v[216:219], v[118:121]
	v_mfma_f32_16x16x32_bf16 v[114:117], v[156:159], v[216:219], v[114:117]
	v_mfma_f32_16x16x32_bf16 v[102:105], v[148:151], v[224:227], v[102:105]
	v_mfma_f32_16x16x32_bf16 v[98:101], v[156:159], v[224:227], v[98:101]
	v_mfma_f32_16x16x32_bf16 v[86:89], v[148:151], v[232:235], v[86:89]
	v_mfma_f32_16x16x32_bf16 v[82:85], v[156:159], v[232:235], v[82:85]
	s_setprio 0
	s_nop 1
	s_setprio 1
	v_mfma_f32_16x16x32_bf16 v[110:113], v[178:181], v[194:197], v[110:113]
	v_mfma_f32_16x16x32_bf16 v[106:109], v[186:189], v[194:197], v[106:109]
	v_mfma_f32_16x16x32_bf16 v[94:97], v[178:181], v[212:215], v[94:97]
	v_mfma_f32_16x16x32_bf16 v[90:93], v[186:189], v[212:215], v[90:93]
	v_mfma_f32_16x16x32_bf16 v[78:81], v[178:181], v[220:223], v[78:81]
	v_mfma_f32_16x16x32_bf16 v[74:77], v[186:189], v[220:223], v[74:77]
	v_mfma_f32_16x16x32_bf16 v[70:73], v[178:181], v[228:231], v[70:73]
	v_mfma_f32_16x16x32_bf16 v[66:69], v[186:189], v[228:231], v[66:69]
	s_setprio 0
	s_nop 1
	s_setprio 1
	v_mfma_f32_16x16x32_bf16 v[110:113], v[182:185], v[208:211], v[110:113]
	v_mfma_f32_16x16x32_bf16 v[106:109], v[190:193], v[208:211], v[106:109]
	v_mfma_f32_16x16x32_bf16 v[94:97], v[182:185], v[216:219], v[94:97]
	v_mfma_f32_16x16x32_bf16 v[90:93], v[190:193], v[216:219], v[90:93]
	v_mfma_f32_16x16x32_bf16 v[78:81], v[182:185], v[224:227], v[78:81]
	v_mfma_f32_16x16x32_bf16 v[74:77], v[190:193], v[224:227], v[74:77]
	v_mfma_f32_16x16x32_bf16 v[70:73], v[182:185], v[232:235], v[70:73]
	v_mfma_f32_16x16x32_bf16 v[66:69], v[190:193], v[232:235], v[66:69]
	s_setprio 0
	s_barrier
	s_add_i32 s43, s43, s20
	s_mov_b32 m0, s43
	ds_read_b128 v[194:197], v143 offset:16384
	ds_read_b128 v[208:211], v143 offset:17408
	ds_read_b128 v[212:215], v143 offset:18432
	ds_read_b128 v[216:219], v143 offset:19456
	ds_read_b128 v[220:223], v143 offset:20480
	ds_read_b128 v[224:227], v143 offset:21504
	ds_read_b128 v[228:231], v143 offset:22528
	ds_read_b128 v[232:235], v143 offset:23552
	global_load_lds_dwordx4 v64, s[16:17]
	s_add_i32 m0, s43, 0x2000
	s_add_u32 s44, s16, 0x200000
	s_addc_u32 s45, s17, 0
	s_add_i32 s43, s46, s20
	global_load_lds_dwordx4 v130, s[16:17]
	s_mov_b32 m0, s43
	s_mov_b64 s[100:101], s[18:19]
	global_load_lds_dwordx4 v64, s[44:45]
	s_add_i32 m0, s43, 0x2000
	s_nop 0
	global_load_lds_dwordx4 v130, s[44:45]
	s_mov_b32 m0, s21
	s_nop 0
	global_load_lds_dwordx4 v134, s[18:19]
	s_mov_b32 m0, s25
	s_nop 0
	global_load_lds_dwordx4 v132, s[18:19]
	s_waitcnt vmcnt(8)
	s_waitcnt lgkmcnt(0)
	s_barrier
; #define PG8_STAGE(bufoff, gbase, voff) do { _Pragma("unroll") for (int _i = 0; _i < 2; ++_i) \
;         __builtin_amdgcn_global_load_lds((const unsigned*)((const char*)(gbase) + (voff)[_i]), (PG8_LAS unsigned*)(lds + (bufoff) + ldsw + _i * 8192), 16, 0, 0); } while (0)
; #define PG8_LDA(dst, b, h) do { _Pragma("unroll") for (int m = 0; m < 4; ++m) _Pragma("unroll") for (int k = 0; k < 2; ++k) dst[m][k] = *(const PG8_LAS bf16x8*)(lds + PG8_SA(b, h) + aoff + m * 2048 + k * 1024); } while (0)
; #define PG8_LDB(dst, b, h) do { _Pragma("unroll") for (int n = 0; n < 2; ++n) _Pragma("unroll") for (int k = 0; k < 2; ++k) dst[n][k] = *(const PG8_LAS bf16x8*)(lds + PG8_SB(b, h) + boff + n * 2048 + k * 1024); } while (0)
; #define PG8_MMA(ai, bj, At, Bt) do { __builtin_amdgcn_s_setprio(1); _Pragma("unroll") for (int m = 0; m < 4; ++m) _Pragma("unroll") for (int n = 0; n < 2; ++n) _Pragma("unroll") for (int k = 0; k < 2; ++k) \
;         acc[ai][bj][m][n] = __builtin_amdgcn_mfma_f32_16x16x32_bf16(Bt[n][k], At[m][k], acc[ai][bj][m][n], 0, 0, 0); __builtin_amdgcn_s_setprio(0); } while (0)
; #define PG8_WAIT_V(n) asm volatile("s_waitcnt vmcnt(" #n ")" ::: "memory")
; #define PG8_WAIT_L(n) asm volatile("s_waitcnt lgkmcnt(" #n ")" ::: "memory")
; #define PG8_BAR __builtin_amdgcn_s_barrier()
; #define PG8_SCHED __builtin_amdgcn_sched_barrier(0)
; template <class Epi, class Sched, bool ALIGN_EPI = false, bool SP2 = false>
; __device__ __forceinline__ void gemm_phase(PG8_LAS unsigned char* lds, const Gemm g, const Sched& S, const Epi& E, const int wave0) {
;     ...
;             PG8_WAIT_V(8); PG8_WAIT_L(0); PG8_BAR; PG8_MMA(1, 0, At, B0); PG8_MMA(1, 1, At, B1); PG8_BAR; PG8_SCHED;
;             PG8_LDB(B0, 1, 0); PG8_LDB(B1, 1, 1); PG8_SCHED; PG8_LDA(At, 1, 0); PG8_STAGE(PG8_SA(0, 1), a2 + hstepA, voffA);
;             PG8_WAIT_V(8); PG8_WAIT_L(0); PG8_BAR; PG8_MMA(0, 0, At, B0); PG8_MMA(0, 1, At, B1); PG8_BAR; PG8_SCHED;
	s_setprio 1
	s_waitcnt lgkmcnt(0)
	v_mfma_f32_16x16x32_bf16 v[60:63], v[144:147], v[194:197], v[60:63]
	v_mfma_f32_16x16x32_bf16 v[56:59], v[152:155], v[194:197], v[56:59]
	v_mfma_f32_16x16x32_bf16 v[52:55], v[144:147], v[212:215], v[52:55]
	v_mfma_f32_16x16x32_bf16 v[48:51], v[152:155], v[212:215], v[48:51]
	v_mfma_f32_16x16x32_bf16 v[36:39], v[144:147], v[220:223], v[36:39]
	v_mfma_f32_16x16x32_bf16 v[32:35], v[152:155], v[220:223], v[32:35]
	v_mfma_f32_16x16x32_bf16 v[20:23], v[144:147], v[228:231], v[20:23]
	v_mfma_f32_16x16x32_bf16 v[16:19], v[152:155], v[228:231], v[16:19]
	s_setprio 0
	s_nop 1
	s_setprio 1
	v_mfma_f32_16x16x32_bf16 v[60:63], v[148:151], v[208:211], v[60:63]
	v_mfma_f32_16x16x32_bf16 v[56:59], v[156:159], v[208:211], v[56:59]
	v_mfma_f32_16x16x32_bf16 v[52:55], v[148:151], v[216:219], v[52:55]
	v_mfma_f32_16x16x32_bf16 v[48:51], v[156:159], v[216:219], v[48:51]
	v_mfma_f32_16x16x32_bf16 v[36:39], v[148:151], v[224:227], v[36:39]
	v_mfma_f32_16x16x32_bf16 v[32:35], v[156:159], v[224:227], v[32:35]
	v_mfma_f32_16x16x32_bf16 v[20:23], v[148:151], v[232:235], v[20:23]
	v_mfma_f32_16x16x32_bf16 v[16:19], v[156:159], v[232:235], v[16:19]
	s_setprio 0
	s_nop 1
	s_setprio 1
	v_mfma_f32_16x16x32_bf16 v[44:47], v[178:181], v[194:197], v[44:47]
	v_mfma_f32_16x16x32_bf16 v[40:43], v[186:189], v[194:197], v[40:43]
	v_mfma_f32_16x16x32_bf16 v[28:31], v[178:181], v[212:215], v[28:31]
	v_mfma_f32_16x16x32_bf16 v[24:27], v[186:189], v[212:215], v[24:27]
	v_mfma_f32_16x16x32_bf16 v[12:15], v[178:181], v[220:223], v[12:15]
	v_mfma_f32_16x16x32_bf16 v[8:11], v[186:189], v[220:223], v[8:11]
	v_mfma_f32_16x16x32_bf16 v[4:7], v[178:181], v[228:231], v[4:7]
	v_mfma_f32_16x16x32_bf16 v[0:3], v[186:189], v[228:231], v[0:3]
	s_setprio 0
	s_nop 1
	s_setprio 1
	v_mfma_f32_16x16x32_bf16 v[44:47], v[182:185], v[208:211], v[44:47]
	v_mfma_f32_16x16x32_bf16 v[40:43], v[190:193], v[208:211], v[40:43]
	v_mfma_f32_16x16x32_bf16 v[28:31], v[182:185], v[216:219], v[28:31]
	v_mfma_f32_16x16x32_bf16 v[24:27], v[190:193], v[216:219], v[24:27]
	v_mfma_f32_16x16x32_bf16 v[12:15], v[182:185], v[224:227], v[12:15]
	v_mfma_f32_16x16x32_bf16 v[8:11], v[190:193], v[224:227], v[8:11]
	v_mfma_f32_16x16x32_bf16 v[4:7], v[182:185], v[232:235], v[4:7]
	v_mfma_f32_16x16x32_bf16 v[0:3], v[190:193], v[232:235], v[0:3]
	s_setprio 0
	s_barrier
	s_add_i32 s43, 0, 0x18000
	s_add_i32 s44, 0, 0x1c000
	ds_read_b128 v[144:147], v254
	ds_read_b128 v[148:151], v254 offset:1024
	ds_read_b128 v[152:155], v254 offset:2048
	ds_read_b128 v[156:159], v254 offset:3072
	ds_read_b128 v[178:181], v255
	ds_read_b128 v[182:185], v255 offset:1024
	ds_read_b128 v[186:189], v255 offset:2048
	ds_read_b128 v[190:193], v255 offset:3072
	s_add_u32 s18, s18, 0x200000
	s_addc_u32 s19, s19, 0
	s_mov_b32 m0, s26
	ds_read_b128 v[194:197], v143 offset:32768
	ds_read_b128 v[208:211], v143 offset:33792
	ds_read_b128 v[212:215], v143 offset:34816
	ds_read_b128 v[216:219], v143 offset:35840
	ds_read_b128 v[220:223], v143 offset:36864
	ds_read_b128 v[224:227], v143 offset:37888
	ds_read_b128 v[228:231], v143 offset:38912
	ds_read_b128 v[232:235], v143 offset:39936
	global_load_lds_dwordx4 v134, s[18:19]
	s_mov_b32 m0, s27
	s_nop 0
	global_load_lds_dwordx4 v132, s[18:19]
	s_waitcnt vmcnt(8)
	s_waitcnt lgkmcnt(0)
	s_barrier
	s_setprio 1
	s_waitcnt lgkmcnt(0)
	v_mfma_f32_16x16x32_bf16 v[126:129], v[144:147], v[194:197], v[126:129]
	v_mfma_f32_16x16x32_bf16 v[122:125], v[152:155], v[194:197], v[122:125]
	v_mfma_f32_16x16x32_bf16 v[118:121], v[144:147], v[212:215], v[118:121]
	v_mfma_f32_16x16x32_bf16 v[114:117], v[152:155], v[212:215], v[114:117]
	v_mfma_f32_16x16x32_bf16 v[102:105], v[144:147], v[220:223], v[102:105]
	v_mfma_f32_16x16x32_bf16 v[98:101], v[152:155], v[220:223], v[98:101]
	v_mfma_f32_16x16x32_bf16 v[86:89], v[144:147], v[228:231], v[86:89]
	v_mfma_f32_16x16x32_bf16 v[82:85], v[152:155], v[228:231], v[82:85]
	s_setprio 0
	s_nop 1
	s_setprio 1
	v_mfma_f32_16x16x32_bf16 v[126:129], v[148:151], v[208:211], v[126:129]
	v_mfma_f32_16x16x32_bf16 v[122:125], v[156:159], v[208:211], v[122:125]
	v_mfma_f32_16x16x32_bf16 v[118:121], v[148:151], v[216:219], v[118:121]
	v_mfma_f32_16x16x32_bf16 v[114:117], v[156:159], v[216:219], v[114:117]
	v_mfma_f32_16x16x32_bf16 v[102:105], v[148:151], v[224:227], v[102:105]
	v_mfma_f32_16x16x32_bf16 v[98:101], v[156:159], v[224:227], v[98:101]
	v_mfma_f32_16x16x32_bf16 v[86:89], v[148:151], v[232:235], v[86:89]
	v_mfma_f32_16x16x32_bf16 v[82:85], v[156:159], v[232:235], v[82:85]
	s_setprio 0
	s_nop 1
	s_setprio 1
	v_mfma_f32_16x16x32_bf16 v[110:113], v[178:181], v[194:197], v[110:113]
	v_mfma_f32_16x16x32_bf16 v[106:109], v[186:189], v[194:197], v[106:109]
	v_mfma_f32_16x16x32_bf16 v[94:97], v[178:181], v[212:215], v[94:97]
	v_mfma_f32_16x16x32_bf16 v[90:93], v[186:189], v[212:215], v[90:93]
	v_mfma_f32_16x16x32_bf16 v[78:81], v[178:181], v[220:223], v[78:81]
	v_mfma_f32_16x16x32_bf16 v[74:77], v[186:189], v[220:223], v[74:77]
	v_mfma_f32_16x16x32_bf16 v[70:73], v[178:181], v[228:231], v[70:73]
	v_mfma_f32_16x16x32_bf16 v[66:69], v[186:189], v[228:231], v[66:69]
	s_setprio 0
	s_nop 1
	s_setprio 1
	v_mfma_f32_16x16x32_bf16 v[110:113], v[182:185], v[208:211], v[110:113]
	v_mfma_f32_16x16x32_bf16 v[106:109], v[190:193], v[208:211], v[106:109]
	v_mfma_f32_16x16x32_bf16 v[94:97], v[182:185], v[216:219], v[94:97]
	v_mfma_f32_16x16x32_bf16 v[90:93], v[190:193], v[216:219], v[90:93]
	v_mfma_f32_16x16x32_bf16 v[78:81], v[182:185], v[224:227], v[78:81]
	v_mfma_f32_16x16x32_bf16 v[74:77], v[190:193], v[224:227], v[74:77]
	v_mfma_f32_16x16x32_bf16 v[70:73], v[182:185], v[232:235], v[70:73]
	v_mfma_f32_16x16x32_bf16 v[66:69], v[190:193], v[232:235], v[66:69]
	s_setprio 0
	s_barrier
; #define PG8_STAGE(bufoff, gbase, voff) do { _Pragma("unroll") for (int _i = 0; _i < 2; ++_i) \
;         __builtin_amdgcn_global_load_lds((const unsigned*)((const char*)(gbase) + (voff)[_i]), (PG8_LAS unsigned*)(lds + (bufoff) + ldsw + _i * 8192), 16, 0, 0); } while (0)
; #define PG8_LDA(dst, b, h) do { _Pragma("unroll") for (int m = 0; m < 4; ++m) _Pragma("unroll") for (int k = 0; k < 2; ++k) dst[m][k] = *(const PG8_LAS bf16x8*)(lds + PG8_SA(b, h) + aoff + m * 2048 + k * 1024); } while (0)
; #define PG8_MMA(ai, bj, At, Bt) do { __builtin_amdgcn_s_setprio(1); _Pragma("unroll") for (int m = 0; m < 4; ++m) _Pragma("unroll") for (int n = 0; n < 2; ++n) _Pragma("unroll") for (int k = 0; k < 2; ++k) \
;         acc[ai][bj][m][n] = __builtin_amdgcn_mfma_f32_16x16x32_bf16(Bt[n][k], At[m][k], acc[ai][bj][m][n], 0, 0, 0); __builtin_amdgcn_s_setprio(0); } while (0)
; #define PG8_WAIT_V(n) asm volatile("s_waitcnt vmcnt(" #n ")" ::: "memory")
; #define PG8_WAIT_L(n) asm volatile("s_waitcnt lgkmcnt(" #n ")" ::: "memory")
; #define PG8_BAR __builtin_amdgcn_s_barrier()
; #define PG8_SCHED __builtin_amdgcn_sched_barrier(0)
; template <class Epi, class Sched, bool ALIGN_EPI = false, bool SP2 = false>
; __device__ __forceinline__ void gemm_phase(PG8_LAS unsigned char* lds, const Gemm g, const Sched& S, const Epi& E, const int wave0) {
;     ...
;         for (int t = 0; t < nt; t += 2) {
;             const bool last = (t == nt - 2);
;             const char* a1 = cA + (size_t)(t + 1) * kstep;
;             const char* a2 = last ? nA : cA + (size_t)(t + 2) * kstep; const char* b2 = last ? nB : cB + (size_t)(t + 2) * kstep;
;     ...
;             PG8_LDA(At, 1, 1); PG8_STAGE(PG8_SB(1, 0), b3, voffB); PG8_STAGE(PG8_SB(1, 1), b3 + hstepB, voffB); PG8_STAGE(PG8_SA(1, 0), a3, voffA);
;             PG8_WAIT_V(8); PG8_WAIT_L(0); PG8_BAR; PG8_MMA(1, 0, At, B0); PG8_MMA(1, 1, At, B1); PG8_BAR; PG8_SCHED;
	s_add_i32 s18, s43, s20
	s_add_u32 s48, s16, 0x80
	s_addc_u32 s49, s17, 0
	s_mov_b32 m0, s18
	ds_read_b128 v[194:197], v143 offset:49152
	ds_read_b128 v[208:211], v143 offset:50176
	ds_read_b128 v[212:215], v143 offset:51200
	ds_read_b128 v[216:219], v143 offset:52224
	ds_read_b128 v[220:223], v143 offset:53248
	ds_read_b128 v[224:227], v143 offset:54272
	ds_read_b128 v[228:231], v143 offset:55296
	ds_read_b128 v[232:235], v143 offset:56320
	global_load_lds_dwordx4 v64, s[48:49]
	s_add_i32 m0, s18, 0x2000
	s_add_u32 s16, s16, 0x200080
	s_addc_u32 s17, s17, 0
	s_add_i32 s18, s44, s20
	global_load_lds_dwordx4 v130, s[48:49]
	s_mov_b32 m0, s18
	s_nop 0
	global_load_lds_dwordx4 v64, s[16:17]
	s_add_i32 m0, s18, 0x2000
	s_nop 0
	global_load_lds_dwordx4 v130, s[16:17]
	s_add_u32 s100, s100, 0x80
	s_addc_u32 s101, s101, 0
	s_mov_b32 m0, s28
	s_nop 0
	global_load_lds_dwordx4 v134, s[100:101]
	s_mov_b32 m0, s29
	s_nop 0
	global_load_lds_dwordx4 v132, s[100:101]
	s_waitcnt vmcnt(8)
	s_waitcnt lgkmcnt(0)
	s_barrier
	s_setprio 1
	s_waitcnt lgkmcnt(0)
	v_mfma_f32_16x16x32_bf16 v[60:63], v[144:147], v[194:197], v[60:63]
	v_mfma_f32_16x16x32_bf16 v[56:59], v[152:155], v[194:197], v[56:59]
	v_mfma_f32_16x16x32_bf16 v[52:55], v[144:147], v[212:215], v[52:55]
	v_mfma_f32_16x16x32_bf16 v[48:51], v[152:155], v[212:215], v[48:51]
	v_mfma_f32_16x16x32_bf16 v[36:39], v[144:147], v[220:223], v[36:39]
	v_mfma_f32_16x16x32_bf16 v[32:35], v[152:155], v[220:223], v[32:35]
	v_mfma_f32_16x16x32_bf16 v[20:23], v[144:147], v[228:231], v[20:23]
	v_mfma_f32_16x16x32_bf16 v[16:19], v[152:155], v[228:231], v[16:19]
	s_setprio 0
	s_nop 1
	s_setprio 1
	v_mfma_f32_16x16x32_bf16 v[60:63], v[148:151], v[208:211], v[60:63]
	v_mfma_f32_16x16x32_bf16 v[56:59], v[156:159], v[208:211], v[56:59]
	v_mfma_f32_16x16x32_bf16 v[52:55], v[148:151], v[216:219], v[52:55]
	v_mfma_f32_16x16x32_bf16 v[48:51], v[156:159], v[216:219], v[48:51]
	v_mfma_f32_16x16x32_bf16 v[36:39], v[148:151], v[224:227], v[36:39]
	v_mfma_f32_16x16x32_bf16 v[32:35], v[156:159], v[224:227], v[32:35]
	v_mfma_f32_16x16x32_bf16 v[20:23], v[148:151], v[232:235], v[20:23]
	v_mfma_f32_16x16x32_bf16 v[16:19], v[156:159], v[232:235], v[16:19]
	s_setprio 0
	s_nop 1
	s_setprio 1
	v_mfma_f32_16x16x32_bf16 v[44:47], v[178:181], v[194:197], v[44:47]
	v_mfma_f32_16x16x32_bf16 v[40:43], v[186:189], v[194:197], v[40:43]
	v_mfma_f32_16x16x32_bf16 v[28:31], v[178:181], v[212:215], v[28:31]
	v_mfma_f32_16x16x32_bf16 v[24:27], v[186:189], v[212:215], v[24:27]
	v_mfma_f32_16x16x32_bf16 v[12:15], v[178:181], v[220:223], v[12:15]
	v_mfma_f32_16x16x32_bf16 v[8:11], v[186:189], v[220:223], v[8:11]
	v_mfma_f32_16x16x32_bf16 v[4:7], v[178:181], v[228:231], v[4:7]
	v_mfma_f32_16x16x32_bf16 v[0:3], v[186:189], v[228:231], v[0:3]
	s_setprio 0
	s_nop 1
	s_setprio 1
	v_mfma_f32_16x16x32_bf16 v[44:47], v[182:185], v[208:211], v[44:47]
	v_mfma_f32_16x16x32_bf16 v[40:43], v[190:193], v[208:211], v[40:43]
	v_mfma_f32_16x16x32_bf16 v[28:31], v[182:185], v[216:219], v[28:31]
	v_mfma_f32_16x16x32_bf16 v[24:27], v[190:193], v[216:219], v[24:27]
	v_mfma_f32_16x16x32_bf16 v[12:15], v[182:185], v[224:227], v[12:15]
	v_mfma_f32_16x16x32_bf16 v[8:11], v[190:193], v[224:227], v[8:11]
	v_mfma_f32_16x16x32_bf16 v[4:7], v[182:185], v[232:235], v[4:7]
	v_mfma_f32_16x16x32_bf16 v[0:3], v[190:193], v[232:235], v[0:3]
	s_setprio 0
	s_barrier
	s_add_i32 s42, s42, 2
	s_add_u32 s0, s0, 0x100
	s_addc_u32 s1, s1, 0
	s_add_u32 s36, s36, 0x100
	s_addc_u32 s37, s37, 0
	s_cmpk_gt_u32 s42, 0x7d
	s_cbranch_scc0 .LBB0_1685
	s_mov_b64 s[48:49], 0x80
	s_and_b64 vcc, exec, s[6:7]
	s_mov_b64 s[34:35], 0x45000
	s_cbranch_vccz .LBB0_1688
	s_barrier

; #define PG8_STAGE(bufoff, gbase, voff) do { _Pragma("unroll") for (int _i = 0; _i < 2; ++_i) \
;         __builtin_amdgcn_global_load_lds((const unsigned*)((const char*)(gbase) + (voff)[_i]), (PG8_LAS unsigned*)(lds + (bufoff) + ldsw + _i * 8192), 16, 0, 0); } while (0)
; #define PG8_LDA(dst, b, h) do { _Pragma("unroll") for (int m = 0; m < 4; ++m) _Pragma("unroll") for (int k = 0; k < 2; ++k) dst[m][k] = *(const PG8_LAS bf16x8*)(lds + PG8_SA(b, h) + aoff + m * 2048 + k * 1024); } while (0)
; #define PG8_LDB(dst, b, h) do { _Pragma("unroll") for (int n = 0; n < 2; ++n) _Pragma("unroll") for (int k = 0; k < 2; ++k) dst[n][k] = *(const PG8_LAS bf16x8*)(lds + PG8_SB(b, h) + boff + n * 2048 + k * 1024); } while (0)
; #define PG8_MMA(ai, bj, At, Bt) do { __builtin_amdgcn_s_setprio(1); _Pragma("unroll") for (int m = 0; m < 4; ++m) _Pragma("unroll") for (int n = 0; n < 2; ++n) _Pragma("unroll") for (int k = 0; k < 2; ++k) \
;         acc[ai][bj][m][n] = __builtin_amdgcn_mfma_f32_16x16x32_bf16(Bt[n][k], At[m][k], acc[ai][bj][m][n], 0, 0, 0); __builtin_amdgcn_s_setprio(0); } while (0)
; #define PG8_WAIT_V(n) asm volatile("s_waitcnt vmcnt(" #n ")" ::: "memory")
; #define PG8_BAR __builtin_amdgcn_s_barrier()
; template <class Epi, class Sched, bool ALIGN_EPI = false, bool SP2 = false>
; __device__ __forceinline__ void gemm_phase(PG8_LAS unsigned char* lds, const Gemm g, const Sched& S, const Epi& E, const int wave0) {
;     ...
;         for (int t = 0; t < nt; t += 2) {
;             const bool last = (t == nt - 2);
;             const char* a1 = cA + (size_t)(t + 1) * kstep;
;             const char* a2 = last ? nA : cA + (size_t)(t + 2) * kstep; const char* b2 = last ? nB : cB + (size_t)(t + 2) * kstep;
;             const char* a3 = a2 + kstep; const char* b3 = b2 + kstep;
;             if (last && has_next) S.a_ready(nxt);
;             if constexpr (SP2) {
;             PG8_LDB(B0, 0, 0); PG8_LDB(B1, 0, 1); PG8_SCHED; PG8_LDA(At, 0, 0); PG8_STAGE(PG8_SA(1, 1), a1 + hstepA, voffA);
;             PG8_WAIT_V(8); PG8_WAIT_L(0); PG8_BAR; PG8_MMA(0, 0, At, B0); PG8_MMA(0, 1, At, B1); PG8_BAR; PG8_SCHED;
;             PG8_LDA(At, 0, 1); PG8_STAGE(PG8_SB(0, 0), b2, voffB); PG8_STAGE(PG8_SB(0, 1), b2 + hstepB, voffB); PG8_STAGE(PG8_SA(0, 0), a2, voffA);
;             PG8_WAIT_V(8); PG8_WAIT_L(0); PG8_BAR; PG8_MMA(1, 0, At, B0); PG8_MMA(1, 1, At, B1); PG8_BAR; PG8_SCHED;
.LBB0_1702:
	s_add_u32 s18, s16, 0xffe00080
	s_addc_u32 s19, s17, -1
	s_add_i32 s44, 0, 0x10000
	s_cmp_eq_u32 s43, 12
	s_cselect_b32 s21, s9, s19
	s_cselect_b32 s20, s11, s18
	s_cselect_b32 s19, s13, s42
	s_cselect_b32 s18, s38, s39
	s_add_i32 s46, 0, 0x14000
	ds_read_b128 v[144:147], v252
	ds_read_b128 v[148:151], v252 offset:1024
	ds_read_b128 v[152:155], v252 offset:2048
	ds_read_b128 v[156:159], v252 offset:3072
	ds_read_b128 v[178:181], v253
	ds_read_b128 v[182:185], v253 offset:1024
	ds_read_b128 v[186:189], v253 offset:2048
	ds_read_b128 v[190:193], v253 offset:3072
	s_add_i32 m0, s28, 0xc000
	ds_read_b128 v[194:197], v143
	ds_read_b128 v[208:211], v143 offset:1024
	ds_read_b128 v[212:215], v143 offset:2048
	ds_read_b128 v[216:219], v143 offset:3072
	ds_read_b128 v[220:223], v143 offset:4096
	ds_read_b128 v[224:227], v143 offset:5120
	ds_read_b128 v[228:231], v143 offset:6144
	ds_read_b128 v[232:235], v143 offset:7168
	global_load_lds_dwordx4 v136, s[16:17]
	s_add_i32 m0, s28, 0xe000
	s_nop 0
	global_load_lds_dwordx4 v138, s[16:17]
	s_waitcnt vmcnt(8)
	s_waitcnt lgkmcnt(0)
	s_barrier
	s_setprio 1
	s_waitcnt lgkmcnt(0)
	v_mfma_f32_16x16x32_bf16 v[126:129], v[144:147], v[194:197], v[126:129]
	v_mfma_f32_16x16x32_bf16 v[122:125], v[152:155], v[194:197], v[122:125]
	v_mfma_f32_16x16x32_bf16 v[118:121], v[144:147], v[212:215], v[118:121]
	v_mfma_f32_16x16x32_bf16 v[114:117], v[152:155], v[212:215], v[114:117]
	v_mfma_f32_16x16x32_bf16 v[102:105], v[144:147], v[220:223], v[102:105]
	v_mfma_f32_16x16x32_bf16 v[98:101], v[152:155], v[220:223], v[98:101]
	v_mfma_f32_16x16x32_bf16 v[86:89], v[144:147], v[228:231], v[86:89]
	v_mfma_f32_16x16x32_bf16 v[82:85], v[152:155], v[228:231], v[82:85]
	s_setprio 0
	s_nop 1
	s_setprio 1
	v_mfma_f32_16x16x32_bf16 v[126:129], v[148:151], v[208:211], v[126:129]
	v_mfma_f32_16x16x32_bf16 v[122:125], v[156:159], v[208:211], v[122:125]
	v_mfma_f32_16x16x32_bf16 v[118:121], v[148:151], v[216:219], v[118:121]
	v_mfma_f32_16x16x32_bf16 v[114:117], v[156:159], v[216:219], v[114:117]
	v_mfma_f32_16x16x32_bf16 v[102:105], v[148:151], v[224:227], v[102:105]
	v_mfma_f32_16x16x32_bf16 v[98:101], v[156:159], v[224:227], v[98:101]
	v_mfma_f32_16x16x32_bf16 v[86:89], v[148:151], v[232:235], v[86:89]
	v_mfma_f32_16x16x32_bf16 v[82:85], v[156:159], v[232:235], v[82:85]
	s_setprio 0
	s_nop 1
	s_setprio 1
	v_mfma_f32_16x16x32_bf16 v[110:113], v[178:181], v[194:197], v[110:113]
	v_mfma_f32_16x16x32_bf16 v[106:109], v[186:189], v[194:197], v[106:109]
	v_mfma_f32_16x16x32_bf16 v[94:97], v[178:181], v[212:215], v[94:97]
	v_mfma_f32_16x16x32_bf16 v[90:93], v[186:189], v[212:215], v[90:93]
	v_mfma_f32_16x16x32_bf16 v[78:81], v[178:181], v[220:223], v[78:81]
	v_mfma_f32_16x16x32_bf16 v[74:77], v[186:189], v[220:223], v[74:77]
	v_mfma_f32_16x16x32_bf16 v[70:73], v[178:181], v[228:231], v[70:73]
	v_mfma_f32_16x16x32_bf16 v[66:69], v[186:189], v[228:231], v[66:69]
	s_setprio 0
	s_nop 1
	s_setprio 1
	v_mfma_f32_16x16x32_bf16 v[110:113], v[182:185], v[208:211], v[110:113]
	v_mfma_f32_16x16x32_bf16 v[106:109], v[190:193], v[208:211], v[106:109]
	v_mfma_f32_16x16x32_bf16 v[94:97], v[182:185], v[216:219], v[94:97]
	v_mfma_f32_16x16x32_bf16 v[90:93], v[190:193], v[216:219], v[90:93]
	v_mfma_f32_16x16x32_bf16 v[78:81], v[182:185], v[224:227], v[78:81]
	v_mfma_f32_16x16x32_bf16 v[74:77], v[190:193], v[224:227], v[74:77]
	v_mfma_f32_16x16x32_bf16 v[70:73], v[182:185], v[232:235], v[70:73]
	v_mfma_f32_16x16x32_bf16 v[66:69], v[190:193], v[232:235], v[66:69]
	s_setprio 0
	s_barrier
	s_add_i32 s44, s44, s25
	s_mov_b32 m0, s44
	ds_read_b128 v[194:197], v143 offset:16384
	ds_read_b128 v[208:211], v143 offset:17408
	ds_read_b128 v[212:215], v143 offset:18432
	ds_read_b128 v[216:219], v143 offset:19456
	ds_read_b128 v[220:223], v143 offset:20480
	ds_read_b128 v[224:227], v143 offset:21504
	ds_read_b128 v[228:231], v143 offset:22528
	ds_read_b128 v[232:235], v143 offset:23552
	global_load_lds_dwordx4 v64, s[18:19]
	s_add_i32 m0, s44, 0x2000
	s_add_u32 s44, s18, 0x200000
	s_addc_u32 s45, s19, 0
	s_add_i32 s46, s46, s25
	global_load_lds_dwordx4 v130, s[18:19]
	s_mov_b32 m0, s46
	s_mov_b64 s[100:101], s[20:21]
	global_load_lds_dwordx4 v64, s[44:45]
	s_add_i32 m0, s46, 0x2000
	s_nop 0
	global_load_lds_dwordx4 v130, s[44:45]
	s_mov_b32 m0, s28
	s_nop 0
	global_load_lds_dwordx4 v134, s[20:21]
	s_mov_b32 m0, s29
	s_nop 0
	global_load_lds_dwordx4 v132, s[20:21]
	s_waitcnt vmcnt(8)
	s_waitcnt lgkmcnt(0)
	s_barrier
; #define PG8_STAGE(bufoff, gbase, voff) do { _Pragma("unroll") for (int _i = 0; _i < 2; ++_i) \
;         __builtin_amdgcn_global_load_lds((const unsigned*)((const char*)(gbase) + (voff)[_i]), (PG8_LAS unsigned*)(lds + (bufoff) + ldsw + _i * 8192), 16, 0, 0); } while (0)
; #define PG8_LDA(dst, b, h) do { _Pragma("unroll") for (int m = 0; m < 4; ++m) _Pragma("unroll") for (int k = 0; k < 2; ++k) dst[m][k] = *(const PG8_LAS bf16x8*)(lds + PG8_SA(b, h) + aoff + m * 2048 + k * 1024); } while (0)
; #define PG8_LDB(dst, b, h) do { _Pragma("unroll") for (int n = 0; n < 2; ++n) _Pragma("unroll") for (int k = 0; k < 2; ++k) dst[n][k] = *(const PG8_LAS bf16x8*)(lds + PG8_SB(b, h) + boff + n * 2048 + k * 1024); } while (0)
; #define PG8_MMA(ai, bj, At, Bt) do { __builtin_amdgcn_s_setprio(1); _Pragma("unroll") for (int m = 0; m < 4; ++m) _Pragma("unroll") for (int n = 0; n < 2; ++n) _Pragma("unroll") for (int k = 0; k < 2; ++k) \
;         acc[ai][bj][m][n] = __builtin_amdgcn_mfma_f32_16x16x32_bf16(Bt[n][k], At[m][k], acc[ai][bj][m][n], 0, 0, 0); __builtin_amdgcn_s_setprio(0); } while (0)
; #define PG8_WAIT_V(n) asm volatile("s_waitcnt vmcnt(" #n ")" ::: "memory")
; #define PG8_WAIT_L(n) asm volatile("s_waitcnt lgkmcnt(" #n ")" ::: "memory")
; #define PG8_BAR __builtin_amdgcn_s_barrier()
; #define PG8_SCHED __builtin_amdgcn_sched_barrier(0)
; template <class Epi, class Sched, bool ALIGN_EPI = false, bool SP2 = false>
; __device__ __forceinline__ void gemm_phase(PG8_LAS unsigned char* lds, const Gemm g, const Sched& S, const Epi& E, const int wave0) {
;     ...
;             PG8_WAIT_V(8); PG8_WAIT_L(0); PG8_BAR; PG8_MMA(1, 0, At, B0); PG8_MMA(1, 1, At, B1); PG8_BAR; PG8_SCHED;
;             PG8_LDB(B0, 1, 0); PG8_LDB(B1, 1, 1); PG8_SCHED; PG8_LDA(At, 1, 0); PG8_STAGE(PG8_SA(0, 1), a2 + hstepA, voffA);
;             PG8_WAIT_V(8); PG8_WAIT_L(0); PG8_BAR; PG8_MMA(0, 0, At, B0); PG8_MMA(0, 1, At, B1); PG8_BAR; PG8_SCHED;
	s_setprio 1
	s_waitcnt lgkmcnt(0)
	v_mfma_f32_16x16x32_bf16 v[60:63], v[144:147], v[194:197], v[60:63]
	v_mfma_f32_16x16x32_bf16 v[56:59], v[152:155], v[194:197], v[56:59]
	v_mfma_f32_16x16x32_bf16 v[52:55], v[144:147], v[212:215], v[52:55]
	v_mfma_f32_16x16x32_bf16 v[48:51], v[152:155], v[212:215], v[48:51]
	v_mfma_f32_16x16x32_bf16 v[36:39], v[144:147], v[220:223], v[36:39]
	v_mfma_f32_16x16x32_bf16 v[32:35], v[152:155], v[220:223], v[32:35]
	v_mfma_f32_16x16x32_bf16 v[20:23], v[144:147], v[228:231], v[20:23]
	v_mfma_f32_16x16x32_bf16 v[16:19], v[152:155], v[228:231], v[16:19]
	s_setprio 0
	s_nop 1
	s_setprio 1
	v_mfma_f32_16x16x32_bf16 v[60:63], v[148:151], v[208:211], v[60:63]
	v_mfma_f32_16x16x32_bf16 v[56:59], v[156:159], v[208:211], v[56:59]
	v_mfma_f32_16x16x32_bf16 v[52:55], v[148:151], v[216:219], v[52:55]
	v_mfma_f32_16x16x32_bf16 v[48:51], v[156:159], v[216:219], v[48:51]
	v_mfma_f32_16x16x32_bf16 v[36:39], v[148:151], v[224:227], v[36:39]
	v_mfma_f32_16x16x32_bf16 v[32:35], v[156:159], v[224:227], v[32:35]
	v_mfma_f32_16x16x32_bf16 v[20:23], v[148:151], v[232:235], v[20:23]
	v_mfma_f32_16x16x32_bf16 v[16:19], v[156:159], v[232:235], v[16:19]
	s_setprio 0
	s_nop 1
	s_setprio 1
	v_mfma_f32_16x16x32_bf16 v[44:47], v[178:181], v[194:197], v[44:47]
	v_mfma_f32_16x16x32_bf16 v[40:43], v[186:189], v[194:197], v[40:43]
	v_mfma_f32_16x16x32_bf16 v[28:31], v[178:181], v[212:215], v[28:31]
	v_mfma_f32_16x16x32_bf16 v[24:27], v[186:189], v[212:215], v[24:27]
	v_mfma_f32_16x16x32_bf16 v[12:15], v[178:181], v[220:223], v[12:15]
	v_mfma_f32_16x16x32_bf16 v[8:11], v[186:189], v[220:223], v[8:11]
	v_mfma_f32_16x16x32_bf16 v[4:7], v[178:181], v[228:231], v[4:7]
	v_mfma_f32_16x16x32_bf16 v[0:3], v[186:189], v[228:231], v[0:3]
	s_setprio 0
	s_nop 1
	s_setprio 1
	v_mfma_f32_16x16x32_bf16 v[44:47], v[182:185], v[208:211], v[44:47]
	v_mfma_f32_16x16x32_bf16 v[40:43], v[190:193], v[208:211], v[40:43]
	v_mfma_f32_16x16x32_bf16 v[28:31], v[182:185], v[216:219], v[28:31]
	v_mfma_f32_16x16x32_bf16 v[24:27], v[190:193], v[216:219], v[24:27]
	v_mfma_f32_16x16x32_bf16 v[12:15], v[182:185], v[224:227], v[12:15]
	v_mfma_f32_16x16x32_bf16 v[8:11], v[190:193], v[224:227], v[8:11]
	v_mfma_f32_16x16x32_bf16 v[4:7], v[182:185], v[232:235], v[4:7]
	v_mfma_f32_16x16x32_bf16 v[0:3], v[190:193], v[232:235], v[0:3]
	s_setprio 0
	s_barrier
	s_add_i32 s44, 0, 0x18000
	s_add_i32 s45, 0, 0x1c000
	ds_read_b128 v[144:147], v254
	ds_read_b128 v[148:151], v254 offset:1024
	ds_read_b128 v[152:155], v254 offset:2048
	ds_read_b128 v[156:159], v254 offset:3072
	ds_read_b128 v[178:181], v255
	ds_read_b128 v[182:185], v255 offset:1024
	ds_read_b128 v[186:189], v255 offset:2048
	ds_read_b128 v[190:193], v255 offset:3072
	s_add_u32 s20, s20, 0x200000
	s_addc_u32 s21, s21, 0
	s_mov_b32 m0, s30
	ds_read_b128 v[194:197], v143 offset:32768
	ds_read_b128 v[208:211], v143 offset:33792
	ds_read_b128 v[212:215], v143 offset:34816
	ds_read_b128 v[216:219], v143 offset:35840
	ds_read_b128 v[220:223], v143 offset:36864
	ds_read_b128 v[224:227], v143 offset:37888
	ds_read_b128 v[228:231], v143 offset:38912
	ds_read_b128 v[232:235], v143 offset:39936
	global_load_lds_dwordx4 v134, s[20:21]
	s_mov_b32 m0, s31
	s_nop 0
	global_load_lds_dwordx4 v132, s[20:21]
	s_waitcnt vmcnt(8)
	s_waitcnt lgkmcnt(0)
	s_barrier
	s_setprio 1
	s_waitcnt lgkmcnt(0)
	v_mfma_f32_16x16x32_bf16 v[126:129], v[144:147], v[194:197], v[126:129]
	v_mfma_f32_16x16x32_bf16 v[122:125], v[152:155], v[194:197], v[122:125]
	v_mfma_f32_16x16x32_bf16 v[118:121], v[144:147], v[212:215], v[118:121]
	v_mfma_f32_16x16x32_bf16 v[114:117], v[152:155], v[212:215], v[114:117]
	v_mfma_f32_16x16x32_bf16 v[102:105], v[144:147], v[220:223], v[102:105]
	v_mfma_f32_16x16x32_bf16 v[98:101], v[152:155], v[220:223], v[98:101]
	v_mfma_f32_16x16x32_bf16 v[86:89], v[144:147], v[228:231], v[86:89]
	v_mfma_f32_16x16x32_bf16 v[82:85], v[152:155], v[228:231], v[82:85]
	s_setprio 0
	s_nop 1
	s_setprio 1
	v_mfma_f32_16x16x32_bf16 v[126:129], v[148:151], v[208:211], v[126:129]
	v_mfma_f32_16x16x32_bf16 v[122:125], v[156:159], v[208:211], v[122:125]
	v_mfma_f32_16x16x32_bf16 v[118:121], v[148:151], v[216:219], v[118:121]
	v_mfma_f32_16x16x32_bf16 v[114:117], v[156:159], v[216:219], v[114:117]
	v_mfma_f32_16x16x32_bf16 v[102:105], v[148:151], v[224:227], v[102:105]
	v_mfma_f32_16x16x32_bf16 v[98:101], v[156:159], v[224:227], v[98:101]
	v_mfma_f32_16x16x32_bf16 v[86:89], v[148:151], v[232:235], v[86:89]
	v_mfma_f32_16x16x32_bf16 v[82:85], v[156:159], v[232:235], v[82:85]
	s_setprio 0
	s_nop 1
	s_setprio 1
	v_mfma_f32_16x16x32_bf16 v[110:113], v[178:181], v[194:197], v[110:113]
	v_mfma_f32_16x16x32_bf16 v[106:109], v[186:189], v[194:197], v[106:109]
	v_mfma_f32_16x16x32_bf16 v[94:97], v[178:181], v[212:215], v[94:97]
	v_mfma_f32_16x16x32_bf16 v[90:93], v[186:189], v[212:215], v[90:93]
	v_mfma_f32_16x16x32_bf16 v[78:81], v[178:181], v[220:223], v[78:81]
	v_mfma_f32_16x16x32_bf16 v[74:77], v[186:189], v[220:223], v[74:77]
	v_mfma_f32_16x16x32_bf16 v[70:73], v[178:181], v[228:231], v[70:73]
	v_mfma_f32_16x16x32_bf16 v[66:69], v[186:189], v[228:231], v[66:69]
	s_setprio 0
	s_nop 1
	s_setprio 1
	v_mfma_f32_16x16x32_bf16 v[110:113], v[182:185], v[208:211], v[110:113]
	v_mfma_f32_16x16x32_bf16 v[106:109], v[190:193], v[208:211], v[106:109]
	v_mfma_f32_16x16x32_bf16 v[94:97], v[182:185], v[216:219], v[94:97]
	v_mfma_f32_16x16x32_bf16 v[90:93], v[190:193], v[216:219], v[90:93]
	v_mfma_f32_16x16x32_bf16 v[78:81], v[182:185], v[224:227], v[78:81]
	v_mfma_f32_16x16x32_bf16 v[74:77], v[190:193], v[224:227], v[74:77]
	v_mfma_f32_16x16x32_bf16 v[70:73], v[182:185], v[232:235], v[70:73]
	v_mfma_f32_16x16x32_bf16 v[66:69], v[190:193], v[232:235], v[66:69]
	s_setprio 0
	s_barrier
; #define PG8_STAGE(bufoff, gbase, voff) do { _Pragma("unroll") for (int _i = 0; _i < 2; ++_i) \
;         __builtin_amdgcn_global_load_lds((const unsigned*)((const char*)(gbase) + (voff)[_i]), (PG8_LAS unsigned*)(lds + (bufoff) + ldsw + _i * 8192), 16, 0, 0); } while (0)
; #define PG8_LDA(dst, b, h) do { _Pragma("unroll") for (int m = 0; m < 4; ++m) _Pragma("unroll") for (int k = 0; k < 2; ++k) dst[m][k] = *(const PG8_LAS bf16x8*)(lds + PG8_SA(b, h) + aoff + m * 2048 + k * 1024); } while (0)
; #define PG8_MMA(ai, bj, At, Bt) do { __builtin_amdgcn_s_setprio(1); _Pragma("unroll") for (int m = 0; m < 4; ++m) _Pragma("unroll") for (int n = 0; n < 2; ++n) _Pragma("unroll") for (int k = 0; k < 2; ++k) \
;         acc[ai][bj][m][n] = __builtin_amdgcn_mfma_f32_16x16x32_bf16(Bt[n][k], At[m][k], acc[ai][bj][m][n], 0, 0, 0); __builtin_amdgcn_s_setprio(0); } while (0)
; #define PG8_WAIT_V(n) asm volatile("s_waitcnt vmcnt(" #n ")" ::: "memory")
; #define PG8_WAIT_L(n) asm volatile("s_waitcnt lgkmcnt(" #n ")" ::: "memory")
; #define PG8_BAR __builtin_amdgcn_s_barrier()
; #define PG8_SCHED __builtin_amdgcn_sched_barrier(0)
; template <class Epi, class Sched, bool ALIGN_EPI = false, bool SP2 = false>
; __device__ __forceinline__ void gemm_phase(PG8_LAS unsigned char* lds, const Gemm g, const Sched& S, const Epi& E, const int wave0) {
;     ...
;         for (int t = 0; t < nt; t += 2) {
;             const bool last = (t == nt - 2);
;             const char* a1 = cA + (size_t)(t + 1) * kstep;
;             const char* a2 = last ? nA : cA + (size_t)(t + 2) * kstep; const char* b2 = last ? nB : cB + (size_t)(t + 2) * kstep;
;     ...
;             PG8_LDA(At, 1, 1); PG8_STAGE(PG8_SB(1, 0), b3, voffB); PG8_STAGE(PG8_SB(1, 1), b3 + hstepB, voffB); PG8_STAGE(PG8_SA(1, 0), a3, voffA);
;             PG8_WAIT_V(8); PG8_WAIT_L(0); PG8_BAR; PG8_MMA(1, 0, At, B0); PG8_MMA(1, 1, At, B1); PG8_BAR; PG8_SCHED;
	s_add_i32 s20, s44, s25
	s_add_u32 s48, s18, 0x80
	s_addc_u32 s49, s19, 0
	s_mov_b32 m0, s20
	ds_read_b128 v[194:197], v143 offset:49152
	ds_read_b128 v[208:211], v143 offset:50176
	ds_read_b128 v[212:215], v143 offset:51200
	ds_read_b128 v[216:219], v143 offset:52224
	ds_read_b128 v[220:223], v143 offset:53248
	ds_read_b128 v[224:227], v143 offset:54272
	ds_read_b128 v[228:231], v143 offset:55296
	ds_read_b128 v[232:235], v143 offset:56320
	global_load_lds_dwordx4 v64, s[48:49]
	s_add_i32 m0, s20, 0x2000
	s_add_u32 s18, s18, 0x200080
	s_addc_u32 s19, s19, 0
	s_add_i32 s20, s45, s25
	global_load_lds_dwordx4 v130, s[48:49]
	s_mov_b32 m0, s20
	s_nop 0
	global_load_lds_dwordx4 v64, s[18:19]
	s_add_i32 m0, s20, 0x2000
	s_nop 0
	global_load_lds_dwordx4 v130, s[18:19]
	s_add_u32 s100, s100, 0x80
	s_addc_u32 s101, s101, 0
	s_mov_b32 m0, s33
	s_nop 0
	global_load_lds_dwordx4 v134, s[100:101]
	s_mov_b32 m0, s34
	s_nop 0
	global_load_lds_dwordx4 v132, s[100:101]
	s_waitcnt vmcnt(8)
	s_waitcnt lgkmcnt(0)
	s_barrier
	s_setprio 1
	s_waitcnt lgkmcnt(0)
	v_mfma_f32_16x16x32_bf16 v[60:63], v[144:147], v[194:197], v[60:63]
	v_mfma_f32_16x16x32_bf16 v[56:59], v[152:155], v[194:197], v[56:59]
	v_mfma_f32_16x16x32_bf16 v[52:55], v[144:147], v[212:215], v[52:55]
	v_mfma_f32_16x16x32_bf16 v[48:51], v[152:155], v[212:215], v[48:51]
	v_mfma_f32_16x16x32_bf16 v[36:39], v[144:147], v[220:223], v[36:39]
	v_mfma_f32_16x16x32_bf16 v[32:35], v[152:155], v[220:223], v[32:35]
	v_mfma_f32_16x16x32_bf16 v[20:23], v[144:147], v[228:231], v[20:23]
	v_mfma_f32_16x16x32_bf16 v[16:19], v[152:155], v[228:231], v[16:19]
	s_setprio 0
	s_nop 1
	s_setprio 1
	v_mfma_f32_16x16x32_bf16 v[60:63], v[148:151], v[208:211], v[60:63]
	v_mfma_f32_16x16x32_bf16 v[56:59], v[156:159], v[208:211], v[56:59]
	v_mfma_f32_16x16x32_bf16 v[52:55], v[148:151], v[216:219], v[52:55]
	v_mfma_f32_16x16x32_bf16 v[48:51], v[156:159], v[216:219], v[48:51]
	v_mfma_f32_16x16x32_bf16 v[36:39], v[148:151], v[224:227], v[36:39]
	v_mfma_f32_16x16x32_bf16 v[32:35], v[156:159], v[224:227], v[32:35]
	v_mfma_f32_16x16x32_bf16 v[20:23], v[148:151], v[232:235], v[20:23]
	v_mfma_f32_16x16x32_bf16 v[16:19], v[156:159], v[232:235], v[16:19]
	s_setprio 0
	s_nop 1
	s_setprio 1
	v_mfma_f32_16x16x32_bf16 v[44:47], v[178:181], v[194:197], v[44:47]
	v_mfma_f32_16x16x32_bf16 v[40:43], v[186:189], v[194:197], v[40:43]
	v_mfma_f32_16x16x32_bf16 v[28:31], v[178:181], v[212:215], v[28:31]
	v_mfma_f32_16x16x32_bf16 v[24:27], v[186:189], v[212:215], v[24:27]
	v_mfma_f32_16x16x32_bf16 v[12:15], v[178:181], v[220:223], v[12:15]
	v_mfma_f32_16x16x32_bf16 v[8:11], v[186:189], v[220:223], v[8:11]
	v_mfma_f32_16x16x32_bf16 v[4:7], v[178:181], v[228:231], v[4:7]
	v_mfma_f32_16x16x32_bf16 v[0:3], v[186:189], v[228:231], v[0:3]
	s_setprio 0
	s_nop 1
	s_setprio 1
	v_mfma_f32_16x16x32_bf16 v[44:47], v[182:185], v[208:211], v[44:47]
	v_mfma_f32_16x16x32_bf16 v[40:43], v[190:193], v[208:211], v[40:43]
	v_mfma_f32_16x16x32_bf16 v[28:31], v[182:185], v[216:219], v[28:31]
	v_mfma_f32_16x16x32_bf16 v[24:27], v[190:193], v[216:219], v[24:27]
	v_mfma_f32_16x16x32_bf16 v[12:15], v[182:185], v[224:227], v[12:15]
	v_mfma_f32_16x16x32_bf16 v[8:11], v[190:193], v[224:227], v[8:11]
	v_mfma_f32_16x16x32_bf16 v[4:7], v[182:185], v[232:235], v[4:7]
	v_mfma_f32_16x16x32_bf16 v[0:3], v[190:193], v[232:235], v[0:3]
	s_setprio 0
	s_barrier
	s_add_i32 s43, s43, 2
	s_add_u32 s16, s16, 0x100
	s_addc_u32 s17, s17, 0
	s_add_u32 s39, s39, 0x100
	s_addc_u32 s42, s42, 0
	s_cmp_gt_u32 s43, 13
	s_cbranch_scc0 .LBB0_1702
	s_mov_b64 s[48:49], 0x80
	s_and_b64 vcc, exec, s[6:7]
	s_cbranch_vccz .LBB0_1705
	s_barrier
